# P3 scan: per-batch MG/BL preload (no per-step vmcnt(0)); PEER V: lns via readlane, coalesced residual loads/stores via lane permute, nt hints on streaming accesses
# speedup vs baseline: 1.0267x; 1.0267x over previous
.LBB0_314:
	v_readlane_b32 s0, v255, 4
	s_cmp_lt_i32 s0, 4
	s_cselect_b64 s[4:5], -1, 0
	s_and_b64 s[2:3], s[4:5], s[2:3]
	s_andn2_b64 vcc, exec, s[2:3]
	v_readlane_b32 s1, v255, 5
	s_cbranch_vccnz .LBB0_513
	v_writelane_b32 v255, s4, 8
	s_mov_b32 s0, 0x20000
	v_cmp_gt_i32_e32 vcc, s0, v99
	v_writelane_b32 v255, s5, 9
	s_mov_b64 s[0:1], exec
	v_writelane_b32 v255, s0, 10
	s_and_b64 s[2:3], s[0:1], vcc
	s_nop 0
	v_writelane_b32 v255, s1, 11
	s_mov_b64 exec, s[2:3]
	s_cbranch_execz .LBB0_512
	v_mbcnt_lo_u32_b32 v154, -1, 0
	v_mbcnt_hi_u32_b32 v154, -1, v154
	v_and_b32_e32 v154, 31, v154
	v_lshlrev_b32_e32 v154, 2, v154
	s_add_u32 s6, s80, 0x3f100000
	s_addc_u32 s7, s81, 0
	s_add_u32 s8, s80, 0x3f110000
	s_waitcnt vmcnt(0)
	v_and_b32_e32 v0, 0x7f, v128
	s_addc_u32 s9, s81, 0
	v_lshlrev_b32_e32 v0, 2, v0
	v_mov_b32_e32 v1, 0
	s_add_u32 s10, s80, 0x3f120000
	v_lshl_add_u64 v[2:3], s[80:81], 0, v[0:1]
	s_mov_b64 s[2:3], 0x3ef00000
	s_addc_u32 s11, s81, 0
	s_lshl_b32 s86, s84, 9
	v_lshl_add_u64 v[2:3], v[2:3], 0, s[2:3]
	s_mov_b64 s[12:13], 0
	s_mov_b32 s15, 0
	s_branch .LBB0_318

.LBB0_320:
	v_add_u32_e32 v159, s14, v82
	v_lshl_add_u32 v159, v159, 2, v154
	v_add_u32_e32 v160, s14, v83
	v_lshl_add_u32 v160, v160, 2, v154
	global_load_dword v155, v159, s[6:7]
	global_load_dword v156, v159, s[8:9]
	global_load_dword v157, v160, s[6:7]
	global_load_dword v158, v160, s[8:9]
	s_lshl_b64 s[4:5], s[14:15], 15
	v_lshl_add_u64 v[78:79], v[4:5], 0, s[4:5]
	global_load_dword v0, v[78:79], off
	v_mov_b32_e32 v148, 0
	v_mov_b32_e32 v9, 0
	s_and_saveexec_b64 s[4:5], vcc
	s_cbranch_execz .LBB0_322
	s_lshl_b64 s[16:17], s[14:15], 9
	v_lshl_add_u64 v[10:11], v[6:7], 0, s[16:17]
	global_load_dword v9, v[10:11], off

.LBB0_384:
	s_or_b64 exec, exec, s[82:83]
	v_add_u32_e32 v12, s14, v82
	v_ashrrev_i32_e32 v13, 31, v12
	v_lshlrev_b64 v[80:81], 2, v[12:13]
	v_lshl_add_u64 v[150:151], s[6:7], 0, v[80:81]
	v_lshl_add_u64 v[80:81], s[8:9], 0, v[80:81]
	s_waitcnt vmcnt(0)
	v_readlane_b32 s98, v156, 0
	s_nop 0
	v_readlane_b32 s99, v155, 0
	s_nop 1
	v_mov_b32_e32 v75, s98
	v_mov_b32_e32 v80, s99
	v_lshlrev_b32_e32 v153, 16, v0
	v_add_f32_e32 v75, v77, v75
	v_max_f32_e32 v77, v80, v80
	v_max_f32_e32 v150, v75, v77
	v_sub_f32_e32 v75, v75, v150
	v_sub_f32_e32 v77, v80, v150
	v_mul_f32_e32 v80, 0x3fb8aa3b, v75
	v_mul_f32_e32 v75, 0x3fb8aa3b, v77
	v_exp_f32_e32 v75, v75
	v_exp_f32_e32 v152, v80
	v_mul_f32_e32 v80, v75, v153
	v_pk_fma_f32 v[80:81], v[74:75], v[152:153], v[80:81] op_sel_hi:[1,1,0]
	v_and_b32_e32 v153, 0xffff0000, v0
	v_mov_b32_e32 v77, v75
	v_mul_f32_e32 v0, v75, v153
	v_pk_fma_f32 v[76:77], v[76:77], v[152:153], v[0:1] op_sel_hi:[1,1,0]
	s_nop 0
	v_cvt_pk_bf16_f32 v0, v80, v76
	global_store_dword v[78:79], v0, off
	s_and_saveexec_b64 s[82:83], s[2:3]
	s_cbranch_execz .LBB0_386
	v_lshl_add_u64 v[74:75], v[12:13], 2, s[10:11]
	global_store_dword v[74:75], v150, off
.LBB0_386:
	s_or_b64 exec, exec, s[82:83]
	v_add_u32_e32 v0, s14, v83
	s_and_saveexec_b64 s[82:83], vcc
	s_cbranch_execz .LBB0_388
	v_lshlrev_b64 v[74:75], 2, v[0:1]
	v_lshl_add_u64 v[78:79], s[6:7], 0, v[74:75]
	v_lshl_add_u64 v[74:75], s[8:9], 0, v[74:75]
	v_readlane_b32 s98, v157, 0
	s_lshl_b64 s[0:1], s[14:15], 9
	v_readlane_b32 s99, v158, 0
	s_nop 1
	v_mov_b32_e32 v13, s98
	v_mov_b32_e32 v74, s99
	v_max_f32_e32 v75, v13, v13
	v_add_f32_e32 v74, v84, v74
	v_max_f32_e32 v84, v74, v75
	v_sub_f32_e32 v74, v74, v84
	v_sub_f32_e32 v13, v13, v84
	v_mul_f32_e32 v74, 0x3fb8aa3b, v74
	v_mul_f32_e32 v13, 0x3fb8aa3b, v13
	v_exp_f32_e32 v74, v74
	v_exp_f32_e32 v75, v13
	s_nop 0
	v_pk_mul_f32 v[8:9], v[8:9], v[74:75]
	s_nop 0
	v_add_f32_e32 v8, v8, v9
	v_lshl_add_u64 v[74:75], v[6:7], 0, s[0:1]
	global_store_dword v[74:75], v8, off
.LBB0_388:
	s_or_b64 exec, exec, s[82:83]
	v_or_b32_e32 v78, 1, v12
	v_ashrrev_i32_e32 v79, 31, v78
	v_lshlrev_b64 v[74:75], 2, v[78:79]
	v_lshl_add_u64 v[152:153], s[6:7], 0, v[74:75]
	v_lshl_add_u64 v[74:75], s[8:9], 0, v[74:75]
	v_readlane_b32 s98, v156, 1
	s_nop 0
	v_readlane_b32 s99, v155, 1
	v_lshlrev_b32_e32 v151, 16, v149
	s_nop 1
	v_mov_b32_e32 v9, s98
	v_mov_b32_e32 v74, s99
	v_add_f32_e32 v9, v150, v9
	v_max_f32_e32 v13, v74, v74
	v_max_f32_e32 v13, v9, v13
	v_sub_f32_e32 v74, v74, v13
	v_sub_f32_e32 v9, v9, v13
	v_mul_f32_e32 v74, 0x3fb8aa3b, v74
	v_mul_f32_e32 v9, 0x3fb8aa3b, v9
	v_exp_f32_e32 v81, v74
	v_exp_f32_e32 v150, v9
	v_mul_f32_e32 v74, v81, v151
	v_pk_fma_f32 v[74:75], v[80:81], v[150:151], v[74:75] op_sel_hi:[1,1,0]
	v_and_b32_e32 v151, 0xffff0000, v149
	v_mov_b32_e32 v77, v81
	v_mul_f32_e32 v80, v81, v151
	v_pk_fma_f32 v[76:77], v[76:77], v[150:151], v[80:81] op_sel_hi:[1,1,0]
	s_nop 0
	v_cvt_pk_bf16_f32 v9, v74, v76
	global_store_dword v[72:73], v9, off
	s_and_saveexec_b64 s[82:83], s[2:3]
	s_cbranch_execz .LBB0_390
	v_lshl_add_u64 v[72:73], v[78:79], 2, s[10:11]
	global_store_dword v[72:73], v13, off
.LBB0_390:
	s_or_b64 exec, exec, s[82:83]
	s_and_saveexec_b64 s[82:83], vcc
	s_cbranch_execz .LBB0_392
	v_or_b32_e32 v72, 1, v0
	v_mov_b32_e32 v73, v1
	v_lshlrev_b64 v[72:73], 2, v[72:73]
	v_lshl_add_u64 v[78:79], s[6:7], 0, v[72:73]
	v_lshl_add_u64 v[72:73], s[8:9], 0, v[72:73]
	v_readlane_b32 s98, v157, 1
	s_lshl_b64 s[0:1], s[4:5], 9
	v_readlane_b32 s99, v158, 1
	s_nop 1
	v_mov_b32_e32 v9, s98
	v_mov_b32_e32 v72, s99
	v_max_f32_e32 v73, v9, v9
	v_add_f32_e32 v72, v84, v72
	v_max_f32_e32 v84, v72, v73
	v_sub_f32_e32 v72, v72, v84
	v_sub_f32_e32 v9, v9, v84
	v_mul_f32_e32 v72, 0x3fb8aa3b, v72
	v_mul_f32_e32 v9, 0x3fb8aa3b, v9
	v_exp_f32_e32 v72, v72
	v_exp_f32_e32 v73, v9
	v_mov_b32_e32 v9, v148
	v_pk_mul_f32 v[8:9], v[8:9], v[72:73]
	s_nop 0
	v_add_f32_e32 v8, v8, v9
	v_lshl_add_u64 v[72:73], v[6:7], 0, s[0:1]
	global_store_dword v[72:73], v8, off
.LBB0_392:
	s_or_b64 exec, exec, s[82:83]
	v_or_b32_e32 v78, 2, v12
	v_ashrrev_i32_e32 v79, 31, v78
	v_lshlrev_b64 v[72:73], 2, v[78:79]
	v_lshl_add_u64 v[80:81], s[6:7], 0, v[72:73]
	v_lshl_add_u64 v[72:73], s[8:9], 0, v[72:73]
	v_readlane_b32 s98, v156, 2
	s_nop 0
	v_readlane_b32 s99, v155, 2
	v_lshlrev_b32_e32 v81, 16, v147
	s_nop 1
	v_mov_b32_e32 v9, s98
	v_mov_b32_e32 v72, s99
	v_add_f32_e32 v9, v13, v9
	v_max_f32_e32 v13, v72, v72
	v_max_f32_e32 v13, v9, v13
	v_sub_f32_e32 v72, v72, v13
	v_sub_f32_e32 v9, v9, v13
	v_mul_f32_e32 v72, 0x3fb8aa3b, v72
	v_mul_f32_e32 v9, 0x3fb8aa3b, v9
	v_exp_f32_e32 v75, v72
	v_exp_f32_e32 v80, v9
	v_mul_f32_e32 v72, v75, v81
	v_pk_fma_f32 v[72:73], v[74:75], v[80:81], v[72:73] op_sel_hi:[1,1,0]
	v_and_b32_e32 v81, 0xffff0000, v147
	v_mov_b32_e32 v77, v75
	v_mul_f32_e32 v74, v75, v81
	v_pk_fma_f32 v[74:75], v[76:77], v[80:81], v[74:75] op_sel_hi:[1,1,0]
	s_nop 0
	v_cvt_pk_bf16_f32 v9, v72, v74
	global_store_dword v[70:71], v9, off
	s_and_saveexec_b64 s[4:5], s[2:3]
	s_cbranch_execz .LBB0_394
	v_lshl_add_u64 v[70:71], v[78:79], 2, s[10:11]
	global_store_dword v[70:71], v13, off
.LBB0_394:
	s_or_b64 exec, exec, s[4:5]
	s_and_saveexec_b64 s[4:5], vcc
	s_cbranch_execz .LBB0_396
	v_or_b32_e32 v70, 2, v0
	v_mov_b32_e32 v71, v1
	v_lshlrev_b64 v[70:71], 2, v[70:71]
	v_lshl_add_u64 v[76:77], s[6:7], 0, v[70:71]
	v_lshl_add_u64 v[70:71], s[8:9], 0, v[70:71]
	v_readlane_b32 s98, v157, 2
	s_lshl_b64 s[0:1], s[42:43], 9
	v_readlane_b32 s99, v158, 2
	s_nop 1
	v_mov_b32_e32 v9, s98
	v_mov_b32_e32 v70, s99
	v_max_f32_e32 v71, v9, v9
	v_add_f32_e32 v70, v84, v70
	v_max_f32_e32 v84, v70, v71
	v_sub_f32_e32 v70, v70, v84
	v_sub_f32_e32 v9, v9, v84
	v_mul_f32_e32 v70, 0x3fb8aa3b, v70
	v_mul_f32_e32 v9, 0x3fb8aa3b, v9
	v_exp_f32_e32 v70, v70
	v_exp_f32_e32 v71, v9
	v_mov_b32_e32 v9, v146
	v_pk_mul_f32 v[8:9], v[8:9], v[70:71]
	s_nop 0
	v_add_f32_e32 v8, v8, v9
	v_lshl_add_u64 v[70:71], v[6:7], 0, s[0:1]
	global_store_dword v[70:71], v8, off
.LBB0_396:
	s_or_b64 exec, exec, s[4:5]
	v_or_b32_e32 v76, 3, v12
	v_ashrrev_i32_e32 v77, 31, v76
	v_lshlrev_b64 v[70:71], 2, v[76:77]
	v_lshl_add_u64 v[78:79], s[6:7], 0, v[70:71]
	v_lshl_add_u64 v[70:71], s[8:9], 0, v[70:71]
	v_readlane_b32 s98, v156, 3
	s_nop 0
	v_readlane_b32 s99, v155, 3
	v_lshlrev_b32_e32 v79, 16, v145
	s_nop 1
	v_mov_b32_e32 v9, s98
	v_mov_b32_e32 v70, s99
	v_add_f32_e32 v9, v13, v9
	v_max_f32_e32 v13, v70, v70
	v_max_f32_e32 v13, v9, v13
	v_sub_f32_e32 v70, v70, v13
	v_sub_f32_e32 v9, v9, v13
	v_mul_f32_e32 v70, 0x3fb8aa3b, v70
	v_mul_f32_e32 v9, 0x3fb8aa3b, v9
	v_exp_f32_e32 v73, v70
	v_exp_f32_e32 v78, v9
	v_mul_f32_e32 v70, v73, v79
	v_pk_fma_f32 v[70:71], v[72:73], v[78:79], v[70:71] op_sel_hi:[1,1,0]
	v_and_b32_e32 v79, 0xffff0000, v145
	v_mov_b32_e32 v75, v73
	v_mul_f32_e32 v72, v73, v79
	v_pk_fma_f32 v[72:73], v[74:75], v[78:79], v[72:73] op_sel_hi:[1,1,0]
	s_nop 0
	v_cvt_pk_bf16_f32 v9, v70, v72
	global_store_dword v[68:69], v9, off
	s_and_saveexec_b64 s[4:5], s[2:3]
	s_cbranch_execz .LBB0_398
	v_lshl_add_u64 v[68:69], v[76:77], 2, s[10:11]
	global_store_dword v[68:69], v13, off
.LBB0_398:
	s_or_b64 exec, exec, s[4:5]
	s_and_saveexec_b64 s[4:5], vcc
	s_cbranch_execz .LBB0_400
	v_or_b32_e32 v68, 3, v0
	v_mov_b32_e32 v69, v1
	v_lshlrev_b64 v[68:69], 2, v[68:69]
	v_lshl_add_u64 v[74:75], s[6:7], 0, v[68:69]
	v_lshl_add_u64 v[68:69], s[8:9], 0, v[68:69]
	v_readlane_b32 s98, v157, 3
	s_lshl_b64 s[0:1], s[96:97], 9
	v_readlane_b32 s99, v158, 3
	s_nop 1
	v_mov_b32_e32 v9, s98
	v_mov_b32_e32 v68, s99
	v_max_f32_e32 v69, v9, v9
	v_add_f32_e32 v68, v84, v68
	v_max_f32_e32 v84, v68, v69
	v_sub_f32_e32 v68, v68, v84
	v_sub_f32_e32 v9, v9, v84
	v_mul_f32_e32 v68, 0x3fb8aa3b, v68
	v_mul_f32_e32 v9, 0x3fb8aa3b, v9
	v_exp_f32_e32 v68, v68
	v_exp_f32_e32 v69, v9
	v_mov_b32_e32 v9, v144
	v_pk_mul_f32 v[8:9], v[8:9], v[68:69]
	s_nop 0
	v_add_f32_e32 v8, v8, v9
	v_lshl_add_u64 v[68:69], v[6:7], 0, s[0:1]
	global_store_dword v[68:69], v8, off
.LBB0_400:
	s_or_b64 exec, exec, s[4:5]
	v_or_b32_e32 v74, 4, v12
	v_ashrrev_i32_e32 v75, 31, v74
	v_lshlrev_b64 v[68:69], 2, v[74:75]
	v_lshl_add_u64 v[76:77], s[6:7], 0, v[68:69]
	v_lshl_add_u64 v[68:69], s[8:9], 0, v[68:69]
	v_readlane_b32 s98, v156, 4
	s_nop 0
	v_readlane_b32 s99, v155, 4
	v_lshlrev_b32_e32 v77, 16, v143
	s_nop 1
	v_mov_b32_e32 v9, s98
	v_mov_b32_e32 v68, s99
	v_add_f32_e32 v9, v13, v9
	v_max_f32_e32 v13, v68, v68
	v_max_f32_e32 v13, v9, v13
	v_sub_f32_e32 v68, v68, v13
	v_sub_f32_e32 v9, v9, v13
	v_mul_f32_e32 v68, 0x3fb8aa3b, v68
	v_mul_f32_e32 v9, 0x3fb8aa3b, v9
	v_exp_f32_e32 v71, v68
	v_exp_f32_e32 v76, v9
	v_mul_f32_e32 v68, v71, v77
	v_pk_fma_f32 v[68:69], v[70:71], v[76:77], v[68:69] op_sel_hi:[1,1,0]
	v_and_b32_e32 v77, 0xffff0000, v143
	v_mov_b32_e32 v73, v71
	v_mul_f32_e32 v70, v71, v77
	v_pk_fma_f32 v[70:71], v[72:73], v[76:77], v[70:71] op_sel_hi:[1,1,0]
	s_nop 0
	v_cvt_pk_bf16_f32 v9, v68, v70
	global_store_dword v[66:67], v9, off
	s_and_saveexec_b64 s[4:5], s[2:3]
	s_cbranch_execz .LBB0_402
	v_lshl_add_u64 v[66:67], v[74:75], 2, s[10:11]
	global_store_dword v[66:67], v13, off
.LBB0_402:
	s_or_b64 exec, exec, s[4:5]
	s_and_saveexec_b64 s[4:5], vcc
	s_cbranch_execz .LBB0_404
	v_or_b32_e32 v66, 4, v0
	v_mov_b32_e32 v67, v1
	v_lshlrev_b64 v[66:67], 2, v[66:67]
	v_lshl_add_u64 v[72:73], s[6:7], 0, v[66:67]
	v_lshl_add_u64 v[66:67], s[8:9], 0, v[66:67]
	v_readlane_b32 s98, v157, 4
	s_lshl_b64 s[0:1], s[94:95], 9
	v_readlane_b32 s99, v158, 4
	s_nop 1
	v_mov_b32_e32 v9, s98
	v_mov_b32_e32 v66, s99
	v_max_f32_e32 v67, v9, v9
	v_add_f32_e32 v66, v84, v66
	v_max_f32_e32 v84, v66, v67
	v_sub_f32_e32 v66, v66, v84
	v_sub_f32_e32 v9, v9, v84
	v_mul_f32_e32 v66, 0x3fb8aa3b, v66
	v_mul_f32_e32 v9, 0x3fb8aa3b, v9
	v_exp_f32_e32 v66, v66
	v_exp_f32_e32 v67, v9
	v_mov_b32_e32 v9, v142
	v_pk_mul_f32 v[8:9], v[8:9], v[66:67]
	s_nop 0
	v_add_f32_e32 v8, v8, v9
	v_lshl_add_u64 v[66:67], v[6:7], 0, s[0:1]
	global_store_dword v[66:67], v8, off
.LBB0_404:
	s_or_b64 exec, exec, s[4:5]
	v_or_b32_e32 v72, 5, v12
	v_ashrrev_i32_e32 v73, 31, v72
	v_lshlrev_b64 v[66:67], 2, v[72:73]
	v_lshl_add_u64 v[74:75], s[6:7], 0, v[66:67]
	v_lshl_add_u64 v[66:67], s[8:9], 0, v[66:67]
	v_readlane_b32 s98, v156, 5
	s_nop 0
	v_readlane_b32 s99, v155, 5
	v_lshlrev_b32_e32 v75, 16, v141
	s_nop 1
	v_mov_b32_e32 v9, s98
	v_mov_b32_e32 v66, s99
	v_add_f32_e32 v9, v13, v9
	v_max_f32_e32 v13, v66, v66
	v_max_f32_e32 v13, v9, v13
	v_sub_f32_e32 v66, v66, v13
	v_sub_f32_e32 v9, v9, v13
	v_mul_f32_e32 v66, 0x3fb8aa3b, v66
	v_mul_f32_e32 v9, 0x3fb8aa3b, v9
	v_exp_f32_e32 v69, v66
	v_exp_f32_e32 v74, v9
	v_mul_f32_e32 v66, v69, v75
	v_pk_fma_f32 v[66:67], v[68:69], v[74:75], v[66:67] op_sel_hi:[1,1,0]
	v_and_b32_e32 v75, 0xffff0000, v141
	v_mov_b32_e32 v71, v69
	v_mul_f32_e32 v68, v69, v75
	v_pk_fma_f32 v[68:69], v[70:71], v[74:75], v[68:69] op_sel_hi:[1,1,0]
	s_nop 0
	v_cvt_pk_bf16_f32 v9, v66, v68
	global_store_dword v[64:65], v9, off
	s_and_saveexec_b64 s[4:5], s[2:3]
	s_cbranch_execz .LBB0_406
	v_lshl_add_u64 v[64:65], v[72:73], 2, s[10:11]
	global_store_dword v[64:65], v13, off
.LBB0_406:
	s_or_b64 exec, exec, s[4:5]
	s_and_saveexec_b64 s[4:5], vcc
	s_cbranch_execz .LBB0_408
	v_or_b32_e32 v64, 5, v0
	v_mov_b32_e32 v65, v1
	v_lshlrev_b64 v[64:65], 2, v[64:65]
	v_lshl_add_u64 v[70:71], s[6:7], 0, v[64:65]
	v_lshl_add_u64 v[64:65], s[8:9], 0, v[64:65]
	v_readlane_b32 s98, v157, 5
	s_lshl_b64 s[0:1], s[92:93], 9
	v_readlane_b32 s99, v158, 5
	s_nop 1
	v_mov_b32_e32 v9, s98
	v_mov_b32_e32 v64, s99
	v_max_f32_e32 v65, v9, v9
	v_add_f32_e32 v64, v84, v64
	v_max_f32_e32 v84, v64, v65
	v_sub_f32_e32 v64, v64, v84
	v_sub_f32_e32 v9, v9, v84
	v_mul_f32_e32 v64, 0x3fb8aa3b, v64
	v_mul_f32_e32 v9, 0x3fb8aa3b, v9
	v_exp_f32_e32 v64, v64
	v_exp_f32_e32 v65, v9
	v_mov_b32_e32 v9, v140
	v_pk_mul_f32 v[8:9], v[8:9], v[64:65]
	s_nop 0
	v_add_f32_e32 v8, v8, v9
	v_lshl_add_u64 v[64:65], v[6:7], 0, s[0:1]
	global_store_dword v[64:65], v8, off
.LBB0_408:
	s_or_b64 exec, exec, s[4:5]
	v_or_b32_e32 v70, 6, v12
	v_ashrrev_i32_e32 v71, 31, v70
	v_lshlrev_b64 v[64:65], 2, v[70:71]
	v_lshl_add_u64 v[72:73], s[6:7], 0, v[64:65]
	v_lshl_add_u64 v[64:65], s[8:9], 0, v[64:65]
	v_readlane_b32 s98, v156, 6
	s_nop 0
	v_readlane_b32 s99, v155, 6
	v_lshlrev_b32_e32 v73, 16, v139
	s_nop 1
	v_mov_b32_e32 v9, s98
	v_mov_b32_e32 v64, s99
	v_add_f32_e32 v9, v13, v9
	v_max_f32_e32 v13, v64, v64
	v_max_f32_e32 v13, v9, v13
	v_sub_f32_e32 v64, v64, v13
	v_sub_f32_e32 v9, v9, v13
	v_mul_f32_e32 v64, 0x3fb8aa3b, v64
	v_mul_f32_e32 v9, 0x3fb8aa3b, v9
	v_exp_f32_e32 v67, v64
	v_exp_f32_e32 v72, v9
	v_mul_f32_e32 v64, v67, v73
	v_pk_fma_f32 v[64:65], v[66:67], v[72:73], v[64:65] op_sel_hi:[1,1,0]
	v_and_b32_e32 v73, 0xffff0000, v139
	v_mov_b32_e32 v69, v67
	v_mul_f32_e32 v66, v67, v73
	v_pk_fma_f32 v[66:67], v[68:69], v[72:73], v[66:67] op_sel_hi:[1,1,0]
	s_nop 0
	v_cvt_pk_bf16_f32 v9, v64, v66
	global_store_dword v[62:63], v9, off
	s_and_saveexec_b64 s[4:5], s[2:3]
	s_cbranch_execz .LBB0_410
	v_lshl_add_u64 v[62:63], v[70:71], 2, s[10:11]
	global_store_dword v[62:63], v13, off
.LBB0_410:
	s_or_b64 exec, exec, s[4:5]
	s_and_saveexec_b64 s[4:5], vcc
	s_cbranch_execz .LBB0_412
	v_or_b32_e32 v62, 6, v0
	v_mov_b32_e32 v63, v1
	v_lshlrev_b64 v[62:63], 2, v[62:63]
	v_lshl_add_u64 v[68:69], s[6:7], 0, v[62:63]
	v_lshl_add_u64 v[62:63], s[8:9], 0, v[62:63]
	v_readlane_b32 s98, v158, 6
	s_nop 0
	v_readlane_b32 s99, v157, 6
	s_lshl_b64 s[0:1], s[90:91], 9
	s_nop 1
	v_mov_b32_e32 v9, s98
	v_mov_b32_e32 v62, s99
	v_add_f32_e32 v9, v84, v9
	v_max_f32_e32 v63, v62, v62
	v_max_f32_e32 v84, v9, v63
	v_sub_f32_e32 v9, v9, v84
	v_sub_f32_e32 v62, v62, v84
	v_mul_f32_e32 v9, 0x3fb8aa3b, v9
	v_mul_f32_e32 v63, 0x3fb8aa3b, v62
	v_exp_f32_e32 v62, v9
	v_exp_f32_e32 v63, v63
	v_mov_b32_e32 v9, v138
	v_pk_mul_f32 v[8:9], v[8:9], v[62:63]
	s_nop 0
	v_add_f32_e32 v8, v8, v9
	v_lshl_add_u64 v[62:63], v[6:7], 0, s[0:1]
	global_store_dword v[62:63], v8, off
.LBB0_412:
	s_or_b64 exec, exec, s[4:5]
	v_or_b32_e32 v68, 7, v12
	v_ashrrev_i32_e32 v69, 31, v68
	v_lshlrev_b64 v[62:63], 2, v[68:69]
	v_lshl_add_u64 v[70:71], s[6:7], 0, v[62:63]
	v_lshl_add_u64 v[62:63], s[8:9], 0, v[62:63]
	v_readlane_b32 s98, v156, 7
	s_nop 0
	v_readlane_b32 s99, v155, 7
	v_lshlrev_b32_e32 v71, 16, v137
	s_nop 1
	v_mov_b32_e32 v9, s98
	v_mov_b32_e32 v62, s99
	v_add_f32_e32 v9, v13, v9
	v_max_f32_e32 v13, v62, v62
	v_max_f32_e32 v13, v9, v13
	v_sub_f32_e32 v62, v62, v13
	v_sub_f32_e32 v9, v9, v13
	v_mul_f32_e32 v62, 0x3fb8aa3b, v62
	v_mul_f32_e32 v9, 0x3fb8aa3b, v9
	v_exp_f32_e32 v65, v62
	v_exp_f32_e32 v70, v9
	v_mul_f32_e32 v62, v65, v71
	v_pk_fma_f32 v[62:63], v[64:65], v[70:71], v[62:63] op_sel_hi:[1,1,0]
	v_and_b32_e32 v71, 0xffff0000, v137
	v_mov_b32_e32 v67, v65
	v_mul_f32_e32 v64, v65, v71
	v_pk_fma_f32 v[64:65], v[66:67], v[70:71], v[64:65] op_sel_hi:[1,1,0]
	s_nop 0
	v_cvt_pk_bf16_f32 v9, v62, v64
	global_store_dword v[60:61], v9, off
	s_and_saveexec_b64 s[4:5], s[2:3]
	s_cbranch_execz .LBB0_414
	v_lshl_add_u64 v[60:61], v[68:69], 2, s[10:11]
	global_store_dword v[60:61], v13, off
.LBB0_414:
	s_or_b64 exec, exec, s[4:5]
	s_and_saveexec_b64 s[4:5], vcc
	s_cbranch_execz .LBB0_416
	v_or_b32_e32 v60, 7, v0
	v_mov_b32_e32 v61, v1
	v_lshlrev_b64 v[60:61], 2, v[60:61]
	v_lshl_add_u64 v[66:67], s[6:7], 0, v[60:61]
	v_lshl_add_u64 v[60:61], s[8:9], 0, v[60:61]
	v_readlane_b32 s98, v158, 7
	s_nop 0
	v_readlane_b32 s99, v157, 7
	s_lshl_b64 s[0:1], s[88:89], 9
	s_nop 1
	v_mov_b32_e32 v9, s98
	v_mov_b32_e32 v60, s99
	v_add_f32_e32 v9, v84, v9
	v_max_f32_e32 v61, v60, v60
	v_max_f32_e32 v84, v9, v61
	v_sub_f32_e32 v9, v9, v84
	v_sub_f32_e32 v60, v60, v84
	v_mul_f32_e32 v9, 0x3fb8aa3b, v9
	v_mul_f32_e32 v61, 0x3fb8aa3b, v60
	v_exp_f32_e32 v60, v9
	v_exp_f32_e32 v61, v61
	v_mov_b32_e32 v9, v136
	v_pk_mul_f32 v[8:9], v[8:9], v[60:61]
	s_nop 0
	v_add_f32_e32 v8, v8, v9
	v_lshl_add_u64 v[60:61], v[6:7], 0, s[0:1]
	global_store_dword v[60:61], v8, off
.LBB0_416:
	s_or_b64 exec, exec, s[4:5]
	v_or_b32_e32 v66, 8, v12
	v_ashrrev_i32_e32 v67, 31, v66
	v_lshlrev_b64 v[60:61], 2, v[66:67]
	v_lshl_add_u64 v[68:69], s[6:7], 0, v[60:61]
	v_lshl_add_u64 v[60:61], s[8:9], 0, v[60:61]
	v_readlane_b32 s98, v156, 8
	s_nop 0
	v_readlane_b32 s99, v155, 8
	v_lshlrev_b32_e32 v69, 16, v135
	s_nop 1
	v_mov_b32_e32 v9, s98
	v_mov_b32_e32 v60, s99
	v_add_f32_e32 v9, v13, v9
	v_max_f32_e32 v13, v60, v60
	v_max_f32_e32 v13, v9, v13
	v_sub_f32_e32 v60, v60, v13
	v_sub_f32_e32 v9, v9, v13
	v_mul_f32_e32 v60, 0x3fb8aa3b, v60
	v_mul_f32_e32 v9, 0x3fb8aa3b, v9
	v_exp_f32_e32 v63, v60
	v_exp_f32_e32 v68, v9
	v_mul_f32_e32 v60, v63, v69
	v_pk_fma_f32 v[60:61], v[62:63], v[68:69], v[60:61] op_sel_hi:[1,1,0]
	v_and_b32_e32 v69, 0xffff0000, v135
	v_mov_b32_e32 v65, v63
	v_mul_f32_e32 v62, v63, v69
	v_pk_fma_f32 v[62:63], v[64:65], v[68:69], v[62:63] op_sel_hi:[1,1,0]
	s_nop 0
	v_cvt_pk_bf16_f32 v9, v60, v62
	global_store_dword v[58:59], v9, off
	s_and_saveexec_b64 s[4:5], s[2:3]
	s_cbranch_execz .LBB0_418
	v_lshl_add_u64 v[58:59], v[66:67], 2, s[10:11]
	global_store_dword v[58:59], v13, off
.LBB0_418:
	s_or_b64 exec, exec, s[4:5]
	s_and_saveexec_b64 s[4:5], vcc
	s_cbranch_execz .LBB0_420
	v_or_b32_e32 v58, 8, v0
	v_mov_b32_e32 v59, v1
	v_lshlrev_b64 v[58:59], 2, v[58:59]
	v_lshl_add_u64 v[64:65], s[6:7], 0, v[58:59]
	v_lshl_add_u64 v[58:59], s[8:9], 0, v[58:59]
	v_readlane_b32 s98, v158, 8
	s_nop 0
	v_readlane_b32 s99, v157, 8
	s_lshl_b64 s[0:1], s[72:73], 9
	s_nop 1
	v_mov_b32_e32 v9, s98
	v_mov_b32_e32 v58, s99
	v_add_f32_e32 v9, v84, v9
	v_max_f32_e32 v59, v58, v58
	v_max_f32_e32 v84, v9, v59
	v_sub_f32_e32 v9, v9, v84
	v_sub_f32_e32 v58, v58, v84
	v_mul_f32_e32 v9, 0x3fb8aa3b, v9
	v_mul_f32_e32 v59, 0x3fb8aa3b, v58
	v_exp_f32_e32 v58, v9
	v_exp_f32_e32 v59, v59
	v_mov_b32_e32 v9, v134
	v_pk_mul_f32 v[8:9], v[8:9], v[58:59]
	s_nop 0
	v_add_f32_e32 v8, v8, v9
	v_lshl_add_u64 v[58:59], v[6:7], 0, s[0:1]
	global_store_dword v[58:59], v8, off
.LBB0_420:
	s_or_b64 exec, exec, s[4:5]
	v_or_b32_e32 v64, 9, v12
	v_ashrrev_i32_e32 v65, 31, v64
	v_lshlrev_b64 v[58:59], 2, v[64:65]
	v_lshl_add_u64 v[66:67], s[6:7], 0, v[58:59]
	v_lshl_add_u64 v[58:59], s[8:9], 0, v[58:59]
	v_readlane_b32 s98, v156, 9
	s_nop 0
	v_readlane_b32 s99, v155, 9
	v_lshlrev_b32_e32 v67, 16, v133
	s_nop 1
	v_mov_b32_e32 v9, s98
	v_mov_b32_e32 v58, s99
	v_add_f32_e32 v9, v13, v9
	v_max_f32_e32 v13, v58, v58
	v_max_f32_e32 v13, v9, v13
	v_sub_f32_e32 v58, v58, v13
	v_sub_f32_e32 v9, v9, v13
	v_mul_f32_e32 v58, 0x3fb8aa3b, v58
	v_mul_f32_e32 v9, 0x3fb8aa3b, v9
	v_exp_f32_e32 v61, v58
	v_exp_f32_e32 v66, v9
	v_mul_f32_e32 v58, v61, v67
	v_pk_fma_f32 v[58:59], v[60:61], v[66:67], v[58:59] op_sel_hi:[1,1,0]
	v_and_b32_e32 v67, 0xffff0000, v133
	v_mov_b32_e32 v63, v61
	v_mul_f32_e32 v60, v61, v67
	v_pk_fma_f32 v[60:61], v[62:63], v[66:67], v[60:61] op_sel_hi:[1,1,0]
	s_nop 0
	v_cvt_pk_bf16_f32 v9, v58, v60
	global_store_dword v[56:57], v9, off
	s_and_saveexec_b64 s[4:5], s[2:3]
	s_cbranch_execz .LBB0_422
	v_lshl_add_u64 v[56:57], v[64:65], 2, s[10:11]
	global_store_dword v[56:57], v13, off
.LBB0_422:
	s_or_b64 exec, exec, s[4:5]
	s_and_saveexec_b64 s[4:5], vcc
	s_cbranch_execz .LBB0_424
	v_or_b32_e32 v56, 9, v0
	v_mov_b32_e32 v57, v1
	v_lshlrev_b64 v[56:57], 2, v[56:57]
	v_lshl_add_u64 v[62:63], s[6:7], 0, v[56:57]
	v_lshl_add_u64 v[56:57], s[8:9], 0, v[56:57]
	v_readlane_b32 s98, v158, 9
	s_nop 0
	v_readlane_b32 s99, v157, 9
	s_lshl_b64 s[0:1], s[70:71], 9
	s_nop 1
	v_mov_b32_e32 v9, s98
	v_mov_b32_e32 v56, s99
	v_add_f32_e32 v9, v84, v9
	v_max_f32_e32 v57, v56, v56
	v_max_f32_e32 v84, v9, v57
	v_sub_f32_e32 v9, v9, v84
	v_sub_f32_e32 v56, v56, v84
	v_mul_f32_e32 v9, 0x3fb8aa3b, v9
	v_mul_f32_e32 v57, 0x3fb8aa3b, v56
	v_exp_f32_e32 v56, v9
	v_exp_f32_e32 v57, v57
	v_mov_b32_e32 v9, v132
	v_pk_mul_f32 v[8:9], v[8:9], v[56:57]
	s_nop 0
	v_add_f32_e32 v8, v8, v9
	v_lshl_add_u64 v[56:57], v[6:7], 0, s[0:1]
	global_store_dword v[56:57], v8, off
.LBB0_424:
	s_or_b64 exec, exec, s[4:5]
	v_or_b32_e32 v62, 10, v12
	v_ashrrev_i32_e32 v63, 31, v62
	v_lshlrev_b64 v[56:57], 2, v[62:63]
	v_lshl_add_u64 v[64:65], s[6:7], 0, v[56:57]
	v_lshl_add_u64 v[56:57], s[8:9], 0, v[56:57]
	v_readlane_b32 s98, v156, 10
	s_nop 0
	v_readlane_b32 s99, v155, 10
	v_lshlrev_b32_e32 v65, 16, v131
	s_nop 1
	v_mov_b32_e32 v9, s98
	v_mov_b32_e32 v56, s99
	v_add_f32_e32 v9, v13, v9
	v_max_f32_e32 v13, v56, v56
	v_max_f32_e32 v13, v9, v13
	v_sub_f32_e32 v56, v56, v13
	v_sub_f32_e32 v9, v9, v13
	v_mul_f32_e32 v56, 0x3fb8aa3b, v56
	v_mul_f32_e32 v9, 0x3fb8aa3b, v9
	v_exp_f32_e32 v59, v56
	v_exp_f32_e32 v64, v9
	v_mul_f32_e32 v56, v59, v65
	v_pk_fma_f32 v[56:57], v[58:59], v[64:65], v[56:57] op_sel_hi:[1,1,0]
	v_and_b32_e32 v65, 0xffff0000, v131
	v_mov_b32_e32 v61, v59
	v_mul_f32_e32 v58, v59, v65
	v_pk_fma_f32 v[58:59], v[60:61], v[64:65], v[58:59] op_sel_hi:[1,1,0]
	s_nop 0
	v_cvt_pk_bf16_f32 v9, v56, v58
	global_store_dword v[54:55], v9, off
	s_and_saveexec_b64 s[4:5], s[2:3]
	s_cbranch_execz .LBB0_426
	v_lshl_add_u64 v[54:55], v[62:63], 2, s[10:11]
	global_store_dword v[54:55], v13, off
.LBB0_426:
	s_or_b64 exec, exec, s[4:5]
	s_and_saveexec_b64 s[4:5], vcc
	s_cbranch_execz .LBB0_428
	v_or_b32_e32 v54, 10, v0
	v_mov_b32_e32 v55, v1
	v_lshlrev_b64 v[54:55], 2, v[54:55]
	v_lshl_add_u64 v[60:61], s[6:7], 0, v[54:55]
	v_lshl_add_u64 v[54:55], s[8:9], 0, v[54:55]
	v_readlane_b32 s98, v158, 10
	s_nop 0
	v_readlane_b32 s99, v157, 10
	s_lshl_b64 s[0:1], s[68:69], 9
	s_nop 1
	v_mov_b32_e32 v9, s98
	v_mov_b32_e32 v54, s99
	v_add_f32_e32 v9, v84, v9
	v_max_f32_e32 v55, v54, v54
	v_max_f32_e32 v84, v9, v55
	v_sub_f32_e32 v9, v9, v84
	v_sub_f32_e32 v54, v54, v84
	v_mul_f32_e32 v9, 0x3fb8aa3b, v9
	v_mul_f32_e32 v55, 0x3fb8aa3b, v54
	v_exp_f32_e32 v54, v9
	v_exp_f32_e32 v55, v55
	v_mov_b32_e32 v9, v130
	v_pk_mul_f32 v[8:9], v[8:9], v[54:55]
	s_nop 0
	v_add_f32_e32 v8, v8, v9
	v_lshl_add_u64 v[54:55], v[6:7], 0, s[0:1]
	global_store_dword v[54:55], v8, off
.LBB0_428:
	s_or_b64 exec, exec, s[4:5]
	v_or_b32_e32 v60, 11, v12
	v_ashrrev_i32_e32 v61, 31, v60
	v_lshlrev_b64 v[54:55], 2, v[60:61]
	v_lshl_add_u64 v[62:63], s[6:7], 0, v[54:55]
	v_lshl_add_u64 v[54:55], s[8:9], 0, v[54:55]
	v_readlane_b32 s98, v156, 11
	s_nop 0
	v_readlane_b32 s99, v155, 11
	v_lshlrev_b32_e32 v63, 16, v129
	s_nop 1
	v_mov_b32_e32 v9, s98
	v_mov_b32_e32 v54, s99
	v_add_f32_e32 v9, v13, v9
	v_max_f32_e32 v13, v54, v54
	v_max_f32_e32 v13, v9, v13
	v_sub_f32_e32 v54, v54, v13
	v_sub_f32_e32 v9, v9, v13
	v_mul_f32_e32 v54, 0x3fb8aa3b, v54
	v_mul_f32_e32 v9, 0x3fb8aa3b, v9
	v_exp_f32_e32 v57, v54
	v_exp_f32_e32 v62, v9
	v_mul_f32_e32 v54, v57, v63
	v_pk_fma_f32 v[54:55], v[56:57], v[62:63], v[54:55] op_sel_hi:[1,1,0]
	v_and_b32_e32 v63, 0xffff0000, v129
	v_mov_b32_e32 v59, v57
	v_mul_f32_e32 v56, v57, v63
	v_pk_fma_f32 v[56:57], v[58:59], v[62:63], v[56:57] op_sel_hi:[1,1,0]
	s_nop 0
	v_cvt_pk_bf16_f32 v9, v54, v56
	global_store_dword v[52:53], v9, off
	s_and_saveexec_b64 s[4:5], s[2:3]
	s_cbranch_execz .LBB0_430
	v_lshl_add_u64 v[52:53], v[60:61], 2, s[10:11]
	global_store_dword v[52:53], v13, off
.LBB0_430:
	s_or_b64 exec, exec, s[4:5]
	s_and_saveexec_b64 s[4:5], vcc
	s_cbranch_execz .LBB0_432
	v_or_b32_e32 v52, 11, v0
	v_mov_b32_e32 v53, v1
	v_lshlrev_b64 v[52:53], 2, v[52:53]
	v_lshl_add_u64 v[58:59], s[6:7], 0, v[52:53]
	v_lshl_add_u64 v[52:53], s[8:9], 0, v[52:53]
	v_readlane_b32 s98, v158, 11
	s_nop 0
	v_readlane_b32 s99, v157, 11
	s_lshl_b64 s[0:1], s[66:67], 9
	s_nop 1
	v_mov_b32_e32 v9, s98
	v_mov_b32_e32 v52, s99
	v_add_f32_e32 v9, v84, v9
	v_max_f32_e32 v53, v52, v52
	v_max_f32_e32 v84, v9, v53
	v_sub_f32_e32 v9, v9, v84
	v_sub_f32_e32 v52, v52, v84
	v_mul_f32_e32 v9, 0x3fb8aa3b, v9
	v_mul_f32_e32 v53, 0x3fb8aa3b, v52
	v_exp_f32_e32 v52, v9
	v_exp_f32_e32 v53, v53
	v_mov_b32_e32 v9, v127
	v_pk_mul_f32 v[8:9], v[8:9], v[52:53]
	s_nop 0
	v_add_f32_e32 v8, v8, v9
	v_lshl_add_u64 v[52:53], v[6:7], 0, s[0:1]
	global_store_dword v[52:53], v8, off
.LBB0_432:
	s_or_b64 exec, exec, s[4:5]
	v_or_b32_e32 v58, 12, v12
	v_ashrrev_i32_e32 v59, 31, v58
	v_lshlrev_b64 v[52:53], 2, v[58:59]
	v_lshl_add_u64 v[60:61], s[6:7], 0, v[52:53]
	v_lshl_add_u64 v[52:53], s[8:9], 0, v[52:53]
	v_readlane_b32 s98, v156, 12
	s_nop 0
	v_readlane_b32 s99, v155, 12
	v_lshlrev_b32_e32 v61, 16, v126
	s_nop 1
	v_mov_b32_e32 v9, s98
	v_mov_b32_e32 v52, s99
	v_add_f32_e32 v9, v13, v9
	v_max_f32_e32 v13, v52, v52
	v_max_f32_e32 v13, v9, v13
	v_sub_f32_e32 v52, v52, v13
	v_sub_f32_e32 v9, v9, v13
	v_mul_f32_e32 v52, 0x3fb8aa3b, v52
	v_mul_f32_e32 v9, 0x3fb8aa3b, v9
	v_exp_f32_e32 v55, v52
	v_exp_f32_e32 v60, v9
	v_mul_f32_e32 v52, v55, v61
	v_pk_fma_f32 v[52:53], v[54:55], v[60:61], v[52:53] op_sel_hi:[1,1,0]
	v_and_b32_e32 v61, 0xffff0000, v126
	v_mov_b32_e32 v57, v55
	v_mul_f32_e32 v54, v55, v61
	v_pk_fma_f32 v[54:55], v[56:57], v[60:61], v[54:55] op_sel_hi:[1,1,0]
	s_nop 0
	v_cvt_pk_bf16_f32 v9, v52, v54
	global_store_dword v[50:51], v9, off
	s_and_saveexec_b64 s[4:5], s[2:3]
	s_cbranch_execz .LBB0_434
	v_lshl_add_u64 v[50:51], v[58:59], 2, s[10:11]
	global_store_dword v[50:51], v13, off
.LBB0_434:
	s_or_b64 exec, exec, s[4:5]
	s_and_saveexec_b64 s[4:5], vcc
	s_cbranch_execz .LBB0_436
	v_or_b32_e32 v50, 12, v0
	v_mov_b32_e32 v51, v1
	v_lshlrev_b64 v[50:51], 2, v[50:51]
	v_lshl_add_u64 v[56:57], s[6:7], 0, v[50:51]
	v_lshl_add_u64 v[50:51], s[8:9], 0, v[50:51]
	v_readlane_b32 s98, v158, 12
	s_nop 0
	v_readlane_b32 s99, v157, 12
	s_lshl_b64 s[0:1], s[64:65], 9
	s_nop 1
	v_mov_b32_e32 v9, s98
	v_mov_b32_e32 v50, s99
	v_add_f32_e32 v9, v84, v9
	v_max_f32_e32 v51, v50, v50
	v_max_f32_e32 v84, v9, v51
	v_sub_f32_e32 v9, v9, v84
	v_sub_f32_e32 v50, v50, v84
	v_mul_f32_e32 v9, 0x3fb8aa3b, v9
	v_mul_f32_e32 v51, 0x3fb8aa3b, v50
	v_exp_f32_e32 v50, v9
	v_exp_f32_e32 v51, v51
	v_mov_b32_e32 v9, v125
	v_pk_mul_f32 v[8:9], v[8:9], v[50:51]
	s_nop 0
	v_add_f32_e32 v8, v8, v9
	v_lshl_add_u64 v[50:51], v[6:7], 0, s[0:1]
	global_store_dword v[50:51], v8, off
.LBB0_436:
	s_or_b64 exec, exec, s[4:5]
	v_or_b32_e32 v56, 13, v12
	v_ashrrev_i32_e32 v57, 31, v56
	v_lshlrev_b64 v[50:51], 2, v[56:57]
	v_lshl_add_u64 v[58:59], s[6:7], 0, v[50:51]
	v_lshl_add_u64 v[50:51], s[8:9], 0, v[50:51]
	v_readlane_b32 s98, v156, 13
	s_nop 0
	v_readlane_b32 s99, v155, 13
	v_lshlrev_b32_e32 v59, 16, v124
	s_nop 1
	v_mov_b32_e32 v9, s98
	v_mov_b32_e32 v50, s99
	v_add_f32_e32 v9, v13, v9
	v_max_f32_e32 v13, v50, v50
	v_max_f32_e32 v13, v9, v13
	v_sub_f32_e32 v50, v50, v13
	v_sub_f32_e32 v9, v9, v13
	v_mul_f32_e32 v50, 0x3fb8aa3b, v50
	v_mul_f32_e32 v9, 0x3fb8aa3b, v9
	v_exp_f32_e32 v53, v50
	v_exp_f32_e32 v58, v9
	v_mul_f32_e32 v50, v53, v59
	v_pk_fma_f32 v[50:51], v[52:53], v[58:59], v[50:51] op_sel_hi:[1,1,0]
	v_and_b32_e32 v59, 0xffff0000, v124
	v_mov_b32_e32 v55, v53
	v_mul_f32_e32 v52, v53, v59
	v_pk_fma_f32 v[52:53], v[54:55], v[58:59], v[52:53] op_sel_hi:[1,1,0]
	s_nop 0
	v_cvt_pk_bf16_f32 v9, v50, v52
	global_store_dword v[48:49], v9, off
	s_and_saveexec_b64 s[4:5], s[2:3]
	s_cbranch_execz .LBB0_438
	v_lshl_add_u64 v[48:49], v[56:57], 2, s[10:11]
	global_store_dword v[48:49], v13, off
.LBB0_438:
	s_or_b64 exec, exec, s[4:5]
	s_and_saveexec_b64 s[4:5], vcc
	s_cbranch_execz .LBB0_440
	v_or_b32_e32 v48, 13, v0
	v_mov_b32_e32 v49, v1
	v_lshlrev_b64 v[48:49], 2, v[48:49]
	v_lshl_add_u64 v[54:55], s[6:7], 0, v[48:49]
	v_lshl_add_u64 v[48:49], s[8:9], 0, v[48:49]
	v_readlane_b32 s98, v158, 13
	s_nop 0
	v_readlane_b32 s99, v157, 13
	s_lshl_b64 s[0:1], s[62:63], 9
	s_nop 1
	v_mov_b32_e32 v9, s98
	v_mov_b32_e32 v48, s99
	v_add_f32_e32 v9, v84, v9
	v_max_f32_e32 v49, v48, v48
	v_max_f32_e32 v84, v9, v49
	v_sub_f32_e32 v9, v9, v84
	v_sub_f32_e32 v48, v48, v84
	v_mul_f32_e32 v9, 0x3fb8aa3b, v9
	v_mul_f32_e32 v49, 0x3fb8aa3b, v48
	v_exp_f32_e32 v48, v9
	v_exp_f32_e32 v49, v49
	v_mov_b32_e32 v9, v123
	v_pk_mul_f32 v[8:9], v[8:9], v[48:49]
	s_nop 0
	v_add_f32_e32 v8, v8, v9
	v_lshl_add_u64 v[48:49], v[6:7], 0, s[0:1]
	global_store_dword v[48:49], v8, off
.LBB0_440:
	s_or_b64 exec, exec, s[4:5]
	v_or_b32_e32 v54, 14, v12
	v_ashrrev_i32_e32 v55, 31, v54
	v_lshlrev_b64 v[48:49], 2, v[54:55]
	v_lshl_add_u64 v[56:57], s[6:7], 0, v[48:49]
	v_lshl_add_u64 v[48:49], s[8:9], 0, v[48:49]
	v_readlane_b32 s98, v156, 14
	s_nop 0
	v_readlane_b32 s99, v155, 14
	v_lshlrev_b32_e32 v57, 16, v122
	s_nop 1
	v_mov_b32_e32 v9, s98
	v_mov_b32_e32 v48, s99
	v_add_f32_e32 v9, v13, v9
	v_max_f32_e32 v13, v48, v48
	v_max_f32_e32 v13, v9, v13
	v_sub_f32_e32 v48, v48, v13
	v_sub_f32_e32 v9, v9, v13
	v_mul_f32_e32 v48, 0x3fb8aa3b, v48
	v_mul_f32_e32 v9, 0x3fb8aa3b, v9
	v_exp_f32_e32 v51, v48
	v_exp_f32_e32 v56, v9
	v_mul_f32_e32 v48, v51, v57
	v_pk_fma_f32 v[48:49], v[50:51], v[56:57], v[48:49] op_sel_hi:[1,1,0]
	v_and_b32_e32 v57, 0xffff0000, v122
	v_mov_b32_e32 v53, v51
	v_mul_f32_e32 v50, v51, v57
	v_pk_fma_f32 v[50:51], v[52:53], v[56:57], v[50:51] op_sel_hi:[1,1,0]
	s_nop 0
	v_cvt_pk_bf16_f32 v9, v48, v50
	global_store_dword v[46:47], v9, off
	s_and_saveexec_b64 s[4:5], s[2:3]
	s_cbranch_execz .LBB0_442
	v_lshl_add_u64 v[46:47], v[54:55], 2, s[10:11]
	global_store_dword v[46:47], v13, off
.LBB0_442:
	s_or_b64 exec, exec, s[4:5]
	s_and_saveexec_b64 s[4:5], vcc
	s_cbranch_execz .LBB0_444
	v_or_b32_e32 v46, 14, v0
	v_mov_b32_e32 v47, v1
	v_lshlrev_b64 v[46:47], 2, v[46:47]
	v_lshl_add_u64 v[52:53], s[6:7], 0, v[46:47]
	v_lshl_add_u64 v[46:47], s[8:9], 0, v[46:47]
	v_readlane_b32 s98, v158, 14
	s_nop 0
	v_readlane_b32 s99, v157, 14
	s_lshl_b64 s[0:1], s[60:61], 9
	s_nop 1
	v_mov_b32_e32 v9, s98
	v_mov_b32_e32 v46, s99
	v_add_f32_e32 v9, v84, v9
	v_max_f32_e32 v47, v46, v46
	v_max_f32_e32 v84, v9, v47
	v_sub_f32_e32 v9, v9, v84
	v_sub_f32_e32 v46, v46, v84
	v_mul_f32_e32 v9, 0x3fb8aa3b, v9
	v_mul_f32_e32 v47, 0x3fb8aa3b, v46
	v_exp_f32_e32 v46, v9
	v_exp_f32_e32 v47, v47
	v_mov_b32_e32 v9, v121
	v_pk_mul_f32 v[8:9], v[8:9], v[46:47]
	s_nop 0
	v_add_f32_e32 v8, v8, v9
	v_lshl_add_u64 v[46:47], v[6:7], 0, s[0:1]
	global_store_dword v[46:47], v8, off
.LBB0_444:
	s_or_b64 exec, exec, s[4:5]
	v_or_b32_e32 v52, 15, v12
	v_ashrrev_i32_e32 v53, 31, v52
	v_lshlrev_b64 v[46:47], 2, v[52:53]
	v_lshl_add_u64 v[54:55], s[6:7], 0, v[46:47]
	v_lshl_add_u64 v[46:47], s[8:9], 0, v[46:47]
	v_readlane_b32 s98, v156, 15
	s_nop 0
	v_readlane_b32 s99, v155, 15
	v_lshlrev_b32_e32 v55, 16, v120
	s_nop 1
	v_mov_b32_e32 v9, s98
	v_mov_b32_e32 v46, s99
	v_add_f32_e32 v9, v13, v9
	v_max_f32_e32 v13, v46, v46
	v_max_f32_e32 v13, v9, v13
	v_sub_f32_e32 v46, v46, v13
	v_sub_f32_e32 v9, v9, v13
	v_mul_f32_e32 v46, 0x3fb8aa3b, v46
	v_mul_f32_e32 v9, 0x3fb8aa3b, v9
	v_exp_f32_e32 v49, v46
	v_exp_f32_e32 v54, v9
	v_mul_f32_e32 v46, v49, v55
	v_pk_fma_f32 v[46:47], v[48:49], v[54:55], v[46:47] op_sel_hi:[1,1,0]
	v_and_b32_e32 v55, 0xffff0000, v120
	v_mov_b32_e32 v51, v49
	v_mul_f32_e32 v48, v49, v55
	v_pk_fma_f32 v[48:49], v[50:51], v[54:55], v[48:49] op_sel_hi:[1,1,0]
	s_nop 0
	v_cvt_pk_bf16_f32 v9, v46, v48
	global_store_dword v[44:45], v9, off
	s_and_saveexec_b64 s[4:5], s[2:3]
	s_cbranch_execz .LBB0_446
	v_lshl_add_u64 v[44:45], v[52:53], 2, s[10:11]
	global_store_dword v[44:45], v13, off
.LBB0_446:
	s_or_b64 exec, exec, s[4:5]
	s_and_saveexec_b64 s[4:5], vcc
	s_cbranch_execz .LBB0_448
	v_or_b32_e32 v44, 15, v0
	v_mov_b32_e32 v45, v1
	v_lshlrev_b64 v[44:45], 2, v[44:45]
	v_lshl_add_u64 v[50:51], s[6:7], 0, v[44:45]
	v_lshl_add_u64 v[44:45], s[8:9], 0, v[44:45]
	v_readlane_b32 s98, v158, 15
	s_nop 0
	v_readlane_b32 s99, v157, 15
	s_lshl_b64 s[0:1], s[56:57], 9
	s_nop 1
	v_mov_b32_e32 v9, s98
	v_mov_b32_e32 v44, s99
	v_add_f32_e32 v9, v84, v9
	v_max_f32_e32 v45, v44, v44
	v_max_f32_e32 v84, v9, v45
	v_sub_f32_e32 v9, v9, v84
	v_sub_f32_e32 v44, v44, v84
	v_mul_f32_e32 v9, 0x3fb8aa3b, v9
	v_mul_f32_e32 v45, 0x3fb8aa3b, v44
	v_exp_f32_e32 v44, v9
	v_exp_f32_e32 v45, v45
	v_mov_b32_e32 v9, v119
	v_pk_mul_f32 v[8:9], v[8:9], v[44:45]
	s_nop 0
	v_add_f32_e32 v8, v8, v9
	v_lshl_add_u64 v[44:45], v[6:7], 0, s[0:1]
	global_store_dword v[44:45], v8, off
.LBB0_448:
	s_or_b64 exec, exec, s[4:5]
	v_or_b32_e32 v50, 16, v12
	v_ashrrev_i32_e32 v51, 31, v50
	v_lshlrev_b64 v[44:45], 2, v[50:51]
	v_lshl_add_u64 v[52:53], s[6:7], 0, v[44:45]
	v_lshl_add_u64 v[44:45], s[8:9], 0, v[44:45]
	v_readlane_b32 s98, v156, 16
	s_nop 0
	v_readlane_b32 s99, v155, 16
	v_lshlrev_b32_e32 v53, 16, v118
	s_nop 1
	v_mov_b32_e32 v9, s98
	v_mov_b32_e32 v44, s99
	v_add_f32_e32 v9, v13, v9
	v_max_f32_e32 v13, v44, v44
	v_max_f32_e32 v13, v9, v13
	v_sub_f32_e32 v44, v44, v13
	v_sub_f32_e32 v9, v9, v13
	v_mul_f32_e32 v44, 0x3fb8aa3b, v44
	v_mul_f32_e32 v9, 0x3fb8aa3b, v9
	v_exp_f32_e32 v47, v44
	v_exp_f32_e32 v52, v9
	v_mul_f32_e32 v44, v47, v53
	v_pk_fma_f32 v[44:45], v[46:47], v[52:53], v[44:45] op_sel_hi:[1,1,0]
	v_and_b32_e32 v53, 0xffff0000, v118
	v_mov_b32_e32 v49, v47
	v_mul_f32_e32 v46, v47, v53
	v_pk_fma_f32 v[46:47], v[48:49], v[52:53], v[46:47] op_sel_hi:[1,1,0]
	s_nop 0
	v_cvt_pk_bf16_f32 v9, v44, v46
	global_store_dword v[42:43], v9, off
	s_and_saveexec_b64 s[4:5], s[2:3]
	s_cbranch_execz .LBB0_450
	v_lshl_add_u64 v[42:43], v[50:51], 2, s[10:11]
	global_store_dword v[42:43], v13, off
.LBB0_450:
	s_or_b64 exec, exec, s[4:5]
	s_and_saveexec_b64 s[4:5], vcc
	s_cbranch_execz .LBB0_452
	v_or_b32_e32 v42, 16, v0
	v_mov_b32_e32 v43, v1
	v_lshlrev_b64 v[42:43], 2, v[42:43]
	v_lshl_add_u64 v[48:49], s[6:7], 0, v[42:43]
	v_lshl_add_u64 v[42:43], s[8:9], 0, v[42:43]
	v_readlane_b32 s98, v158, 16
	s_nop 0
	v_readlane_b32 s99, v157, 16
	s_lshl_b64 s[0:1], s[54:55], 9
	s_nop 1
	v_mov_b32_e32 v9, s98
	v_mov_b32_e32 v42, s99
	v_add_f32_e32 v9, v84, v9
	v_max_f32_e32 v43, v42, v42
	v_max_f32_e32 v84, v9, v43
	v_sub_f32_e32 v9, v9, v84
	v_sub_f32_e32 v42, v42, v84
	v_mul_f32_e32 v9, 0x3fb8aa3b, v9
	v_mul_f32_e32 v43, 0x3fb8aa3b, v42
	v_exp_f32_e32 v42, v9
	v_exp_f32_e32 v43, v43
	v_mov_b32_e32 v9, v117
	v_pk_mul_f32 v[8:9], v[8:9], v[42:43]
	s_nop 0
	v_add_f32_e32 v8, v8, v9
	v_lshl_add_u64 v[42:43], v[6:7], 0, s[0:1]
	global_store_dword v[42:43], v8, off
.LBB0_452:
	s_or_b64 exec, exec, s[4:5]
	v_or_b32_e32 v48, 17, v12
	v_ashrrev_i32_e32 v49, 31, v48
	v_lshlrev_b64 v[42:43], 2, v[48:49]
	v_lshl_add_u64 v[50:51], s[6:7], 0, v[42:43]
	v_lshl_add_u64 v[42:43], s[8:9], 0, v[42:43]
	v_readlane_b32 s98, v156, 17
	s_nop 0
	v_readlane_b32 s99, v155, 17
	v_lshlrev_b32_e32 v51, 16, v116
	s_nop 1
	v_mov_b32_e32 v9, s98
	v_mov_b32_e32 v42, s99
	v_add_f32_e32 v9, v13, v9
	v_max_f32_e32 v13, v42, v42
	v_max_f32_e32 v13, v9, v13
	v_sub_f32_e32 v42, v42, v13
	v_sub_f32_e32 v9, v9, v13
	v_mul_f32_e32 v42, 0x3fb8aa3b, v42
	v_mul_f32_e32 v9, 0x3fb8aa3b, v9
	v_exp_f32_e32 v45, v42
	v_exp_f32_e32 v50, v9
	v_mul_f32_e32 v42, v45, v51
	v_pk_fma_f32 v[42:43], v[44:45], v[50:51], v[42:43] op_sel_hi:[1,1,0]
	v_and_b32_e32 v51, 0xffff0000, v116
	v_mov_b32_e32 v47, v45
	v_mul_f32_e32 v44, v45, v51
	v_pk_fma_f32 v[44:45], v[46:47], v[50:51], v[44:45] op_sel_hi:[1,1,0]
	s_nop 0
	v_cvt_pk_bf16_f32 v9, v42, v44
	global_store_dword v[40:41], v9, off
	s_and_saveexec_b64 s[4:5], s[2:3]
	s_cbranch_execz .LBB0_454
	v_lshl_add_u64 v[40:41], v[48:49], 2, s[10:11]
	global_store_dword v[40:41], v13, off
.LBB0_454:
	s_or_b64 exec, exec, s[4:5]
	s_and_saveexec_b64 s[4:5], vcc
	s_cbranch_execz .LBB0_456
	v_or_b32_e32 v40, 17, v0
	v_mov_b32_e32 v41, v1
	v_lshlrev_b64 v[40:41], 2, v[40:41]
	v_lshl_add_u64 v[46:47], s[6:7], 0, v[40:41]
	v_lshl_add_u64 v[40:41], s[8:9], 0, v[40:41]
	v_readlane_b32 s98, v158, 17
	s_nop 0
	v_readlane_b32 s99, v157, 17
	s_lshl_b64 s[0:1], s[52:53], 9
	s_nop 1
	v_mov_b32_e32 v9, s98
	v_mov_b32_e32 v40, s99
	v_add_f32_e32 v9, v84, v9
	v_max_f32_e32 v41, v40, v40
	v_max_f32_e32 v84, v9, v41
	v_sub_f32_e32 v9, v9, v84
	v_sub_f32_e32 v40, v40, v84
	v_mul_f32_e32 v9, 0x3fb8aa3b, v9
	v_mul_f32_e32 v41, 0x3fb8aa3b, v40
	v_exp_f32_e32 v40, v9
	v_exp_f32_e32 v41, v41
	v_mov_b32_e32 v9, v115
	v_pk_mul_f32 v[8:9], v[8:9], v[40:41]
	s_nop 0
	v_add_f32_e32 v8, v8, v9
	v_lshl_add_u64 v[40:41], v[6:7], 0, s[0:1]
	global_store_dword v[40:41], v8, off
.LBB0_456:
	s_or_b64 exec, exec, s[4:5]
	v_or_b32_e32 v46, 18, v12
	v_ashrrev_i32_e32 v47, 31, v46
	v_lshlrev_b64 v[40:41], 2, v[46:47]
	v_lshl_add_u64 v[48:49], s[6:7], 0, v[40:41]
	v_lshl_add_u64 v[40:41], s[8:9], 0, v[40:41]
	v_readlane_b32 s98, v156, 18
	s_nop 0
	v_readlane_b32 s99, v155, 18
	v_lshlrev_b32_e32 v49, 16, v114
	s_nop 1
	v_mov_b32_e32 v9, s98
	v_mov_b32_e32 v40, s99
	v_add_f32_e32 v9, v13, v9
	v_max_f32_e32 v13, v40, v40
	v_max_f32_e32 v13, v9, v13
	v_sub_f32_e32 v40, v40, v13
	v_sub_f32_e32 v9, v9, v13
	v_mul_f32_e32 v40, 0x3fb8aa3b, v40
	v_mul_f32_e32 v9, 0x3fb8aa3b, v9
	v_exp_f32_e32 v43, v40
	v_exp_f32_e32 v48, v9
	v_mul_f32_e32 v40, v43, v49
	v_pk_fma_f32 v[40:41], v[42:43], v[48:49], v[40:41] op_sel_hi:[1,1,0]
	v_and_b32_e32 v49, 0xffff0000, v114
	v_mov_b32_e32 v45, v43
	v_mul_f32_e32 v42, v43, v49
	v_pk_fma_f32 v[42:43], v[44:45], v[48:49], v[42:43] op_sel_hi:[1,1,0]
	s_nop 0
	v_cvt_pk_bf16_f32 v9, v40, v42
	global_store_dword v[38:39], v9, off
	s_and_saveexec_b64 s[4:5], s[2:3]
	s_cbranch_execz .LBB0_458
	v_lshl_add_u64 v[38:39], v[46:47], 2, s[10:11]
	global_store_dword v[38:39], v13, off
.LBB0_458:
	s_or_b64 exec, exec, s[4:5]
	s_and_saveexec_b64 s[4:5], vcc
	s_cbranch_execz .LBB0_460
	v_or_b32_e32 v38, 18, v0
	v_mov_b32_e32 v39, v1
	v_lshlrev_b64 v[38:39], 2, v[38:39]
	v_lshl_add_u64 v[44:45], s[6:7], 0, v[38:39]
	v_lshl_add_u64 v[38:39], s[8:9], 0, v[38:39]
	v_readlane_b32 s98, v158, 18
	s_nop 0
	v_readlane_b32 s99, v157, 18
	s_lshl_b64 s[0:1], s[50:51], 9
	s_nop 1
	v_mov_b32_e32 v9, s98
	v_mov_b32_e32 v38, s99
	v_add_f32_e32 v9, v84, v9
	v_max_f32_e32 v39, v38, v38
	v_max_f32_e32 v84, v9, v39
	v_sub_f32_e32 v9, v9, v84
	v_sub_f32_e32 v38, v38, v84
	v_mul_f32_e32 v9, 0x3fb8aa3b, v9
	v_mul_f32_e32 v39, 0x3fb8aa3b, v38
	v_exp_f32_e32 v38, v9
	v_exp_f32_e32 v39, v39
	v_mov_b32_e32 v9, v113
	v_pk_mul_f32 v[8:9], v[8:9], v[38:39]
	s_nop 0
	v_add_f32_e32 v8, v8, v9
	v_lshl_add_u64 v[38:39], v[6:7], 0, s[0:1]
	global_store_dword v[38:39], v8, off
.LBB0_460:
	s_or_b64 exec, exec, s[4:5]
	v_or_b32_e32 v44, 19, v12
	v_ashrrev_i32_e32 v45, 31, v44
	v_lshlrev_b64 v[38:39], 2, v[44:45]
	v_lshl_add_u64 v[46:47], s[6:7], 0, v[38:39]
	v_lshl_add_u64 v[38:39], s[8:9], 0, v[38:39]
	v_readlane_b32 s98, v156, 19
	s_nop 0
	v_readlane_b32 s99, v155, 19
	v_lshlrev_b32_e32 v47, 16, v112
	s_nop 1
	v_mov_b32_e32 v9, s98
	v_mov_b32_e32 v38, s99
	v_add_f32_e32 v9, v13, v9
	v_max_f32_e32 v13, v38, v38
	v_max_f32_e32 v13, v9, v13
	v_sub_f32_e32 v38, v38, v13
	v_sub_f32_e32 v9, v9, v13
	v_mul_f32_e32 v38, 0x3fb8aa3b, v38
	v_mul_f32_e32 v9, 0x3fb8aa3b, v9
	v_exp_f32_e32 v41, v38
	v_exp_f32_e32 v46, v9
	v_mul_f32_e32 v38, v41, v47
	v_pk_fma_f32 v[38:39], v[40:41], v[46:47], v[38:39] op_sel_hi:[1,1,0]
	v_and_b32_e32 v47, 0xffff0000, v112
	v_mov_b32_e32 v43, v41
	v_mul_f32_e32 v40, v41, v47
	v_pk_fma_f32 v[40:41], v[42:43], v[46:47], v[40:41] op_sel_hi:[1,1,0]
	s_nop 0
	v_cvt_pk_bf16_f32 v9, v38, v40
	global_store_dword v[36:37], v9, off
	s_and_saveexec_b64 s[4:5], s[2:3]
	s_cbranch_execz .LBB0_462
	v_lshl_add_u64 v[36:37], v[44:45], 2, s[10:11]
	global_store_dword v[36:37], v13, off
.LBB0_462:
	s_or_b64 exec, exec, s[4:5]
	s_and_saveexec_b64 s[4:5], vcc
	s_cbranch_execz .LBB0_464
	v_or_b32_e32 v36, 19, v0
	v_mov_b32_e32 v37, v1
	v_lshlrev_b64 v[36:37], 2, v[36:37]
	v_lshl_add_u64 v[42:43], s[6:7], 0, v[36:37]
	v_lshl_add_u64 v[36:37], s[8:9], 0, v[36:37]
	v_readlane_b32 s98, v158, 19
	s_nop 0
	v_readlane_b32 s99, v157, 19
	s_lshl_b64 s[0:1], s[44:45], 9
	s_nop 1
	v_mov_b32_e32 v9, s98
	v_mov_b32_e32 v36, s99
	v_add_f32_e32 v9, v84, v9
	v_max_f32_e32 v37, v36, v36
	v_max_f32_e32 v84, v9, v37
	v_sub_f32_e32 v9, v9, v84
	v_sub_f32_e32 v36, v36, v84
	v_mul_f32_e32 v9, 0x3fb8aa3b, v9
	v_mul_f32_e32 v37, 0x3fb8aa3b, v36
	v_exp_f32_e32 v36, v9
	v_exp_f32_e32 v37, v37
	v_mov_b32_e32 v9, v111
	v_pk_mul_f32 v[8:9], v[8:9], v[36:37]
	s_nop 0
	v_add_f32_e32 v8, v8, v9
	v_lshl_add_u64 v[36:37], v[6:7], 0, s[0:1]
	global_store_dword v[36:37], v8, off
.LBB0_464:
	s_or_b64 exec, exec, s[4:5]
	v_or_b32_e32 v42, 20, v12
	v_ashrrev_i32_e32 v43, 31, v42
	v_lshlrev_b64 v[36:37], 2, v[42:43]
	v_lshl_add_u64 v[44:45], s[6:7], 0, v[36:37]
	v_lshl_add_u64 v[36:37], s[8:9], 0, v[36:37]
	v_readlane_b32 s98, v156, 20
	s_nop 0
	v_readlane_b32 s99, v155, 20
	v_lshlrev_b32_e32 v45, 16, v110
	s_nop 1
	v_mov_b32_e32 v9, s98
	v_mov_b32_e32 v36, s99
	v_add_f32_e32 v9, v13, v9
	v_max_f32_e32 v13, v36, v36
	v_max_f32_e32 v13, v9, v13
	v_sub_f32_e32 v36, v36, v13
	v_sub_f32_e32 v9, v9, v13
	v_mul_f32_e32 v36, 0x3fb8aa3b, v36
	v_mul_f32_e32 v9, 0x3fb8aa3b, v9
	v_exp_f32_e32 v39, v36
	v_exp_f32_e32 v44, v9
	v_mul_f32_e32 v36, v39, v45
	v_pk_fma_f32 v[36:37], v[38:39], v[44:45], v[36:37] op_sel_hi:[1,1,0]
	v_and_b32_e32 v45, 0xffff0000, v110
	v_mov_b32_e32 v41, v39
	v_mul_f32_e32 v38, v39, v45
	v_pk_fma_f32 v[38:39], v[40:41], v[44:45], v[38:39] op_sel_hi:[1,1,0]
	s_nop 0
	v_cvt_pk_bf16_f32 v9, v36, v38
	global_store_dword v[34:35], v9, off
	s_and_saveexec_b64 s[4:5], s[2:3]
	s_cbranch_execz .LBB0_466
	v_lshl_add_u64 v[34:35], v[42:43], 2, s[10:11]
	global_store_dword v[34:35], v13, off
.LBB0_466:
	s_or_b64 exec, exec, s[4:5]
	s_and_saveexec_b64 s[4:5], vcc
	s_cbranch_execz .LBB0_468
	v_or_b32_e32 v34, 20, v0
	v_mov_b32_e32 v35, v1
	v_lshlrev_b64 v[34:35], 2, v[34:35]
	v_lshl_add_u64 v[40:41], s[6:7], 0, v[34:35]
	v_lshl_add_u64 v[34:35], s[8:9], 0, v[34:35]
	v_readlane_b32 s98, v158, 20
	s_nop 0
	v_readlane_b32 s99, v157, 20
	s_lshl_b64 s[0:1], s[40:41], 9
	s_nop 1
	v_mov_b32_e32 v9, s98
	v_mov_b32_e32 v34, s99
	v_add_f32_e32 v9, v84, v9
	v_max_f32_e32 v35, v34, v34
	v_max_f32_e32 v84, v9, v35
	v_sub_f32_e32 v9, v9, v84
	v_sub_f32_e32 v34, v34, v84
	v_mul_f32_e32 v9, 0x3fb8aa3b, v9
	v_mul_f32_e32 v35, 0x3fb8aa3b, v34
	v_exp_f32_e32 v34, v9
	v_exp_f32_e32 v35, v35
	v_mov_b32_e32 v9, v109
	v_pk_mul_f32 v[8:9], v[8:9], v[34:35]
	s_nop 0
	v_add_f32_e32 v8, v8, v9
	v_lshl_add_u64 v[34:35], v[6:7], 0, s[0:1]
	global_store_dword v[34:35], v8, off
.LBB0_468:
	s_or_b64 exec, exec, s[4:5]
	v_or_b32_e32 v40, 21, v12
	v_ashrrev_i32_e32 v41, 31, v40
	v_lshlrev_b64 v[34:35], 2, v[40:41]
	v_lshl_add_u64 v[42:43], s[6:7], 0, v[34:35]
	v_lshl_add_u64 v[34:35], s[8:9], 0, v[34:35]
	v_readlane_b32 s98, v156, 21
	s_nop 0
	v_readlane_b32 s99, v155, 21
	v_lshlrev_b32_e32 v43, 16, v108
	s_nop 1
	v_mov_b32_e32 v9, s98
	v_mov_b32_e32 v34, s99
	v_add_f32_e32 v9, v13, v9
	v_max_f32_e32 v13, v34, v34
	v_max_f32_e32 v13, v9, v13
	v_sub_f32_e32 v34, v34, v13
	v_sub_f32_e32 v9, v9, v13
	v_mul_f32_e32 v34, 0x3fb8aa3b, v34
	v_mul_f32_e32 v9, 0x3fb8aa3b, v9
	v_exp_f32_e32 v37, v34
	v_exp_f32_e32 v42, v9
	v_mul_f32_e32 v34, v37, v43
	v_pk_fma_f32 v[34:35], v[36:37], v[42:43], v[34:35] op_sel_hi:[1,1,0]
	v_and_b32_e32 v43, 0xffff0000, v108
	v_mov_b32_e32 v39, v37
	v_mul_f32_e32 v36, v37, v43
	v_pk_fma_f32 v[36:37], v[38:39], v[42:43], v[36:37] op_sel_hi:[1,1,0]
	s_nop 0
	v_cvt_pk_bf16_f32 v9, v34, v36
	global_store_dword v[32:33], v9, off
	s_and_saveexec_b64 s[4:5], s[2:3]
	s_cbranch_execz .LBB0_470
	v_lshl_add_u64 v[32:33], v[40:41], 2, s[10:11]
	global_store_dword v[32:33], v13, off
.LBB0_470:
	s_or_b64 exec, exec, s[4:5]
	s_and_saveexec_b64 s[4:5], vcc
	s_cbranch_execz .LBB0_472
	v_or_b32_e32 v32, 21, v0
	v_mov_b32_e32 v33, v1
	v_lshlrev_b64 v[32:33], 2, v[32:33]
	v_lshl_add_u64 v[38:39], s[6:7], 0, v[32:33]
	v_lshl_add_u64 v[32:33], s[8:9], 0, v[32:33]
	v_readlane_b32 s98, v158, 21
	s_nop 0
	v_readlane_b32 s99, v157, 21
	s_lshl_b64 s[0:1], s[38:39], 9
	s_nop 1
	v_mov_b32_e32 v9, s98
	v_mov_b32_e32 v32, s99
	v_add_f32_e32 v9, v84, v9
	v_max_f32_e32 v33, v32, v32
	v_max_f32_e32 v84, v9, v33
	v_sub_f32_e32 v9, v9, v84
	v_sub_f32_e32 v32, v32, v84
	v_mul_f32_e32 v9, 0x3fb8aa3b, v9
	v_mul_f32_e32 v33, 0x3fb8aa3b, v32
	v_exp_f32_e32 v32, v9
	v_exp_f32_e32 v33, v33
	v_mov_b32_e32 v9, v107
	v_pk_mul_f32 v[8:9], v[8:9], v[32:33]
	s_nop 0
	v_add_f32_e32 v8, v8, v9
	v_lshl_add_u64 v[32:33], v[6:7], 0, s[0:1]
	global_store_dword v[32:33], v8, off
.LBB0_472:
	s_or_b64 exec, exec, s[4:5]
	v_or_b32_e32 v38, 22, v12
	v_ashrrev_i32_e32 v39, 31, v38
	v_lshlrev_b64 v[32:33], 2, v[38:39]
	v_lshl_add_u64 v[40:41], s[6:7], 0, v[32:33]
	v_lshl_add_u64 v[32:33], s[8:9], 0, v[32:33]
	v_readlane_b32 s98, v156, 22
	s_nop 0
	v_readlane_b32 s99, v155, 22
	v_lshlrev_b32_e32 v41, 16, v106
	s_nop 1
	v_mov_b32_e32 v9, s98
	v_mov_b32_e32 v32, s99
	v_add_f32_e32 v9, v13, v9
	v_max_f32_e32 v13, v32, v32
	v_max_f32_e32 v13, v9, v13
	v_sub_f32_e32 v32, v32, v13
	v_sub_f32_e32 v9, v9, v13
	v_mul_f32_e32 v32, 0x3fb8aa3b, v32
	v_mul_f32_e32 v9, 0x3fb8aa3b, v9
	v_exp_f32_e32 v35, v32
	v_exp_f32_e32 v40, v9
	v_mul_f32_e32 v32, v35, v41
	v_pk_fma_f32 v[32:33], v[34:35], v[40:41], v[32:33] op_sel_hi:[1,1,0]
	v_and_b32_e32 v41, 0xffff0000, v106
	v_mov_b32_e32 v37, v35
	v_mul_f32_e32 v34, v35, v41
	v_pk_fma_f32 v[34:35], v[36:37], v[40:41], v[34:35] op_sel_hi:[1,1,0]
	s_nop 0
	v_cvt_pk_bf16_f32 v9, v32, v34
	global_store_dword v[30:31], v9, off
	s_and_saveexec_b64 s[4:5], s[2:3]
	s_cbranch_execz .LBB0_474
	v_lshl_add_u64 v[30:31], v[38:39], 2, s[10:11]
	global_store_dword v[30:31], v13, off
.LBB0_474:
	s_or_b64 exec, exec, s[4:5]
	s_and_saveexec_b64 s[4:5], vcc
	s_cbranch_execz .LBB0_476
	v_or_b32_e32 v30, 22, v0
	v_mov_b32_e32 v31, v1
	v_lshlrev_b64 v[30:31], 2, v[30:31]
	v_lshl_add_u64 v[36:37], s[6:7], 0, v[30:31]
	v_lshl_add_u64 v[30:31], s[8:9], 0, v[30:31]
	v_readlane_b32 s98, v158, 22
	s_nop 0
	v_readlane_b32 s99, v157, 22
	s_lshl_b64 s[0:1], s[36:37], 9
	s_nop 1
	v_mov_b32_e32 v9, s98
	v_mov_b32_e32 v30, s99
	v_add_f32_e32 v9, v84, v9
	v_max_f32_e32 v31, v30, v30
	v_max_f32_e32 v84, v9, v31
	v_sub_f32_e32 v9, v9, v84
	v_sub_f32_e32 v30, v30, v84
	v_mul_f32_e32 v9, 0x3fb8aa3b, v9
	v_mul_f32_e32 v31, 0x3fb8aa3b, v30
	v_exp_f32_e32 v30, v9
	v_exp_f32_e32 v31, v31
	v_mov_b32_e32 v9, v105
	v_pk_mul_f32 v[8:9], v[8:9], v[30:31]
	s_nop 0
	v_add_f32_e32 v8, v8, v9
	v_lshl_add_u64 v[30:31], v[6:7], 0, s[0:1]
	global_store_dword v[30:31], v8, off
.LBB0_476:
	s_or_b64 exec, exec, s[4:5]
	v_or_b32_e32 v36, 23, v12
	v_ashrrev_i32_e32 v37, 31, v36
	v_lshlrev_b64 v[30:31], 2, v[36:37]
	v_lshl_add_u64 v[38:39], s[6:7], 0, v[30:31]
	v_lshl_add_u64 v[30:31], s[8:9], 0, v[30:31]
	v_readlane_b32 s98, v156, 23
	s_nop 0
	v_readlane_b32 s99, v155, 23
	v_lshlrev_b32_e32 v39, 16, v104
	s_nop 1
	v_mov_b32_e32 v9, s98
	v_mov_b32_e32 v30, s99
	v_add_f32_e32 v9, v13, v9
	v_max_f32_e32 v13, v30, v30
	v_max_f32_e32 v13, v9, v13
	v_sub_f32_e32 v30, v30, v13
	v_sub_f32_e32 v9, v9, v13
	v_mul_f32_e32 v30, 0x3fb8aa3b, v30
	v_mul_f32_e32 v9, 0x3fb8aa3b, v9
	v_exp_f32_e32 v33, v30
	v_exp_f32_e32 v38, v9
	v_mul_f32_e32 v30, v33, v39
	v_pk_fma_f32 v[30:31], v[32:33], v[38:39], v[30:31] op_sel_hi:[1,1,0]
	v_and_b32_e32 v39, 0xffff0000, v104
	v_mov_b32_e32 v35, v33
	v_mul_f32_e32 v32, v33, v39
	v_pk_fma_f32 v[32:33], v[34:35], v[38:39], v[32:33] op_sel_hi:[1,1,0]
	s_nop 0
	v_cvt_pk_bf16_f32 v9, v30, v32
	global_store_dword v[28:29], v9, off
	s_and_saveexec_b64 s[4:5], s[2:3]
	s_cbranch_execz .LBB0_478
	v_lshl_add_u64 v[28:29], v[36:37], 2, s[10:11]
	global_store_dword v[28:29], v13, off
.LBB0_478:
	s_or_b64 exec, exec, s[4:5]
	s_and_saveexec_b64 s[4:5], vcc
	s_cbranch_execz .LBB0_480
	v_or_b32_e32 v28, 23, v0
	v_mov_b32_e32 v29, v1
	v_lshlrev_b64 v[28:29], 2, v[28:29]
	v_lshl_add_u64 v[34:35], s[6:7], 0, v[28:29]
	v_lshl_add_u64 v[28:29], s[8:9], 0, v[28:29]
	v_readlane_b32 s98, v158, 23
	s_nop 0
	v_readlane_b32 s99, v157, 23
	s_lshl_b64 s[0:1], s[34:35], 9
	s_nop 1
	v_mov_b32_e32 v9, s98
	v_mov_b32_e32 v28, s99
	v_add_f32_e32 v9, v84, v9
	v_max_f32_e32 v29, v28, v28
	v_max_f32_e32 v84, v9, v29
	v_sub_f32_e32 v9, v9, v84
	v_sub_f32_e32 v28, v28, v84
	v_mul_f32_e32 v9, 0x3fb8aa3b, v9
	v_mul_f32_e32 v29, 0x3fb8aa3b, v28
	v_exp_f32_e32 v28, v9
	v_exp_f32_e32 v29, v29
	v_mov_b32_e32 v9, v103
	v_pk_mul_f32 v[8:9], v[8:9], v[28:29]
	s_nop 0
	v_add_f32_e32 v8, v8, v9
	v_lshl_add_u64 v[28:29], v[6:7], 0, s[0:1]
	global_store_dword v[28:29], v8, off
.LBB0_480:
	s_or_b64 exec, exec, s[4:5]
	v_or_b32_e32 v34, 24, v12
	v_ashrrev_i32_e32 v35, 31, v34
	v_lshlrev_b64 v[28:29], 2, v[34:35]
	v_lshl_add_u64 v[36:37], s[6:7], 0, v[28:29]
	v_lshl_add_u64 v[28:29], s[8:9], 0, v[28:29]
	v_readlane_b32 s98, v156, 24
	s_nop 0
	v_readlane_b32 s99, v155, 24
	v_lshlrev_b32_e32 v37, 16, v102
	s_nop 1
	v_mov_b32_e32 v9, s98
	v_mov_b32_e32 v28, s99
	v_add_f32_e32 v9, v13, v9
	v_max_f32_e32 v13, v28, v28
	v_max_f32_e32 v13, v9, v13
	v_sub_f32_e32 v28, v28, v13
	v_sub_f32_e32 v9, v9, v13
	v_mul_f32_e32 v28, 0x3fb8aa3b, v28
	v_mul_f32_e32 v9, 0x3fb8aa3b, v9
	v_exp_f32_e32 v31, v28
	v_exp_f32_e32 v36, v9
	v_mul_f32_e32 v28, v31, v37
	v_pk_fma_f32 v[28:29], v[30:31], v[36:37], v[28:29] op_sel_hi:[1,1,0]
	v_and_b32_e32 v37, 0xffff0000, v102
	v_mov_b32_e32 v33, v31
	v_mul_f32_e32 v30, v31, v37
	v_pk_fma_f32 v[30:31], v[32:33], v[36:37], v[30:31] op_sel_hi:[1,1,0]
	s_nop 0
	v_cvt_pk_bf16_f32 v9, v28, v30
	global_store_dword v[26:27], v9, off
	s_and_saveexec_b64 s[4:5], s[2:3]
	s_cbranch_execz .LBB0_482
	v_lshl_add_u64 v[26:27], v[34:35], 2, s[10:11]
	global_store_dword v[26:27], v13, off
.LBB0_482:
	s_or_b64 exec, exec, s[4:5]
	s_and_saveexec_b64 s[4:5], vcc
	s_cbranch_execz .LBB0_484
	v_or_b32_e32 v26, 24, v0
	v_mov_b32_e32 v27, v1
	v_lshlrev_b64 v[26:27], 2, v[26:27]
	v_lshl_add_u64 v[32:33], s[6:7], 0, v[26:27]
	v_lshl_add_u64 v[26:27], s[8:9], 0, v[26:27]
	v_readlane_b32 s98, v158, 24
	s_nop 0
	v_readlane_b32 s99, v157, 24
	s_lshl_b64 s[0:1], s[30:31], 9
	s_nop 1
	v_mov_b32_e32 v9, s98
	v_mov_b32_e32 v26, s99
	v_add_f32_e32 v9, v84, v9
	v_max_f32_e32 v27, v26, v26
	v_max_f32_e32 v84, v9, v27
	v_sub_f32_e32 v9, v9, v84
	v_sub_f32_e32 v26, v26, v84
	v_mul_f32_e32 v9, 0x3fb8aa3b, v9
	v_mul_f32_e32 v27, 0x3fb8aa3b, v26
	v_exp_f32_e32 v26, v9
	v_exp_f32_e32 v27, v27
	v_mov_b32_e32 v9, v101
	v_pk_mul_f32 v[8:9], v[8:9], v[26:27]
	s_nop 0
	v_add_f32_e32 v8, v8, v9
	v_lshl_add_u64 v[26:27], v[6:7], 0, s[0:1]
	global_store_dword v[26:27], v8, off
.LBB0_484:
	s_or_b64 exec, exec, s[4:5]
	v_or_b32_e32 v32, 25, v12
	v_ashrrev_i32_e32 v33, 31, v32
	v_lshlrev_b64 v[26:27], 2, v[32:33]
	v_lshl_add_u64 v[34:35], s[6:7], 0, v[26:27]
	v_lshl_add_u64 v[26:27], s[8:9], 0, v[26:27]
	v_readlane_b32 s98, v156, 25
	s_nop 0
	v_readlane_b32 s99, v155, 25
	v_lshlrev_b32_e32 v35, 16, v100
	s_nop 1
	v_mov_b32_e32 v9, s98
	v_mov_b32_e32 v26, s99
	v_add_f32_e32 v9, v13, v9
	v_max_f32_e32 v13, v26, v26
	v_max_f32_e32 v13, v9, v13
	v_sub_f32_e32 v26, v26, v13
	v_sub_f32_e32 v9, v9, v13
	v_mul_f32_e32 v26, 0x3fb8aa3b, v26
	v_mul_f32_e32 v9, 0x3fb8aa3b, v9
	v_exp_f32_e32 v29, v26
	v_exp_f32_e32 v34, v9
	v_mul_f32_e32 v26, v29, v35
	v_pk_fma_f32 v[26:27], v[28:29], v[34:35], v[26:27] op_sel_hi:[1,1,0]
	v_and_b32_e32 v35, 0xffff0000, v100
	v_mov_b32_e32 v31, v29
	v_mul_f32_e32 v28, v29, v35
	v_pk_fma_f32 v[28:29], v[30:31], v[34:35], v[28:29] op_sel_hi:[1,1,0]
	s_nop 0
	v_cvt_pk_bf16_f32 v9, v26, v28
	global_store_dword v[24:25], v9, off
	s_and_saveexec_b64 s[4:5], s[2:3]
	s_cbranch_execz .LBB0_486
	v_lshl_add_u64 v[24:25], v[32:33], 2, s[10:11]
	global_store_dword v[24:25], v13, off
.LBB0_486:
	s_or_b64 exec, exec, s[4:5]
	s_and_saveexec_b64 s[4:5], vcc
	s_cbranch_execz .LBB0_488
	v_or_b32_e32 v24, 25, v0
	v_mov_b32_e32 v25, v1
	v_lshlrev_b64 v[24:25], 2, v[24:25]
	v_lshl_add_u64 v[30:31], s[6:7], 0, v[24:25]
	v_lshl_add_u64 v[24:25], s[8:9], 0, v[24:25]
	v_readlane_b32 s98, v158, 25
	s_nop 0
	v_readlane_b32 s99, v157, 25
	s_lshl_b64 s[0:1], s[28:29], 9
	s_nop 1
	v_mov_b32_e32 v9, s98
	v_mov_b32_e32 v24, s99
	v_add_f32_e32 v9, v84, v9
	v_max_f32_e32 v25, v24, v24
	v_max_f32_e32 v84, v9, v25
	v_sub_f32_e32 v9, v9, v84
	v_sub_f32_e32 v24, v24, v84
	v_mul_f32_e32 v9, 0x3fb8aa3b, v9
	v_mul_f32_e32 v25, 0x3fb8aa3b, v24
	v_exp_f32_e32 v24, v9
	v_exp_f32_e32 v25, v25
	v_mov_b32_e32 v9, v97
	v_pk_mul_f32 v[8:9], v[8:9], v[24:25]
	s_nop 0
	v_add_f32_e32 v8, v8, v9
	v_lshl_add_u64 v[24:25], v[6:7], 0, s[0:1]
	global_store_dword v[24:25], v8, off
.LBB0_488:
	s_or_b64 exec, exec, s[4:5]
	v_or_b32_e32 v30, 26, v12
	v_ashrrev_i32_e32 v31, 31, v30
	v_lshlrev_b64 v[24:25], 2, v[30:31]
	v_lshl_add_u64 v[32:33], s[6:7], 0, v[24:25]
	v_lshl_add_u64 v[24:25], s[8:9], 0, v[24:25]
	v_readlane_b32 s98, v156, 26
	s_nop 0
	v_readlane_b32 s99, v155, 26
	v_lshlrev_b32_e32 v33, 16, v96
	s_nop 1
	v_mov_b32_e32 v9, s98
	v_mov_b32_e32 v24, s99
	v_add_f32_e32 v9, v13, v9
	v_max_f32_e32 v13, v24, v24
	v_max_f32_e32 v13, v9, v13
	v_sub_f32_e32 v24, v24, v13
	v_sub_f32_e32 v9, v9, v13
	v_mul_f32_e32 v24, 0x3fb8aa3b, v24
	v_mul_f32_e32 v9, 0x3fb8aa3b, v9
	v_exp_f32_e32 v27, v24
	v_exp_f32_e32 v32, v9
	v_mul_f32_e32 v24, v27, v33
	v_pk_fma_f32 v[24:25], v[26:27], v[32:33], v[24:25] op_sel_hi:[1,1,0]
	v_and_b32_e32 v33, 0xffff0000, v96
	v_mov_b32_e32 v29, v27
	v_mul_f32_e32 v26, v27, v33
	v_pk_fma_f32 v[26:27], v[28:29], v[32:33], v[26:27] op_sel_hi:[1,1,0]
	s_nop 0
	v_cvt_pk_bf16_f32 v9, v24, v26
	global_store_dword v[22:23], v9, off
	s_and_saveexec_b64 s[4:5], s[2:3]
	s_cbranch_execz .LBB0_490
	v_lshl_add_u64 v[22:23], v[30:31], 2, s[10:11]
	global_store_dword v[22:23], v13, off
.LBB0_490:
	s_or_b64 exec, exec, s[4:5]
	s_and_saveexec_b64 s[4:5], vcc
	s_cbranch_execz .LBB0_492
	v_or_b32_e32 v22, 26, v0
	v_mov_b32_e32 v23, v1
	v_lshlrev_b64 v[22:23], 2, v[22:23]
	v_lshl_add_u64 v[28:29], s[6:7], 0, v[22:23]
	v_lshl_add_u64 v[22:23], s[8:9], 0, v[22:23]
	v_readlane_b32 s98, v158, 26
	s_nop 0
	v_readlane_b32 s99, v157, 26
	s_lshl_b64 s[0:1], s[26:27], 9
	s_nop 1
	v_mov_b32_e32 v9, s98
	v_mov_b32_e32 v22, s99
	v_add_f32_e32 v9, v84, v9
	v_max_f32_e32 v23, v22, v22
	v_max_f32_e32 v84, v9, v23
	v_sub_f32_e32 v9, v9, v84
	v_sub_f32_e32 v22, v22, v84
	v_mul_f32_e32 v9, 0x3fb8aa3b, v9
	v_mul_f32_e32 v23, 0x3fb8aa3b, v22
	v_exp_f32_e32 v22, v9
	v_exp_f32_e32 v23, v23
	v_mov_b32_e32 v9, v95
	v_pk_mul_f32 v[8:9], v[8:9], v[22:23]
	s_nop 0
	v_add_f32_e32 v8, v8, v9
	v_lshl_add_u64 v[22:23], v[6:7], 0, s[0:1]
	global_store_dword v[22:23], v8, off
.LBB0_492:
	s_or_b64 exec, exec, s[4:5]
	v_or_b32_e32 v28, 27, v12
	v_ashrrev_i32_e32 v29, 31, v28
	v_lshlrev_b64 v[22:23], 2, v[28:29]
	v_lshl_add_u64 v[30:31], s[6:7], 0, v[22:23]
	v_lshl_add_u64 v[22:23], s[8:9], 0, v[22:23]
	v_readlane_b32 s98, v156, 27
	s_nop 0
	v_readlane_b32 s99, v155, 27
	v_lshlrev_b32_e32 v31, 16, v94
	s_nop 1
	v_mov_b32_e32 v9, s98
	v_mov_b32_e32 v22, s99
	v_add_f32_e32 v9, v13, v9
	v_max_f32_e32 v13, v22, v22
	v_max_f32_e32 v13, v9, v13
	v_sub_f32_e32 v22, v22, v13
	v_sub_f32_e32 v9, v9, v13
	v_mul_f32_e32 v22, 0x3fb8aa3b, v22
	v_mul_f32_e32 v9, 0x3fb8aa3b, v9
	v_exp_f32_e32 v25, v22
	v_exp_f32_e32 v30, v9
	v_mul_f32_e32 v22, v25, v31
	v_pk_fma_f32 v[22:23], v[24:25], v[30:31], v[22:23] op_sel_hi:[1,1,0]
	v_and_b32_e32 v31, 0xffff0000, v94
	v_mov_b32_e32 v27, v25
	v_mul_f32_e32 v24, v25, v31
	v_pk_fma_f32 v[24:25], v[26:27], v[30:31], v[24:25] op_sel_hi:[1,1,0]
	s_nop 0
	v_cvt_pk_bf16_f32 v9, v22, v24
	global_store_dword v[20:21], v9, off
	s_and_saveexec_b64 s[4:5], s[2:3]
	s_cbranch_execz .LBB0_494
	v_lshl_add_u64 v[20:21], v[28:29], 2, s[10:11]
	global_store_dword v[20:21], v13, off
.LBB0_494:
	s_or_b64 exec, exec, s[4:5]
	s_and_saveexec_b64 s[4:5], vcc
	s_cbranch_execz .LBB0_496
	v_or_b32_e32 v20, 27, v0
	v_mov_b32_e32 v21, v1
	v_lshlrev_b64 v[20:21], 2, v[20:21]
	v_lshl_add_u64 v[26:27], s[6:7], 0, v[20:21]
	v_lshl_add_u64 v[20:21], s[8:9], 0, v[20:21]
	v_readlane_b32 s98, v158, 27
	s_nop 0
	v_readlane_b32 s99, v157, 27
	s_lshl_b64 s[0:1], s[24:25], 9
	s_nop 1
	v_mov_b32_e32 v9, s98
	v_mov_b32_e32 v20, s99
	v_add_f32_e32 v9, v84, v9
	v_max_f32_e32 v21, v20, v20
	v_max_f32_e32 v84, v9, v21
	v_sub_f32_e32 v9, v9, v84
	v_sub_f32_e32 v20, v20, v84
	v_mul_f32_e32 v9, 0x3fb8aa3b, v9
	v_mul_f32_e32 v21, 0x3fb8aa3b, v20
	v_exp_f32_e32 v20, v9
	v_exp_f32_e32 v21, v21
	v_mov_b32_e32 v9, v93
	v_pk_mul_f32 v[8:9], v[8:9], v[20:21]
	s_nop 0
	v_add_f32_e32 v8, v8, v9
	v_lshl_add_u64 v[20:21], v[6:7], 0, s[0:1]
	global_store_dword v[20:21], v8, off
.LBB0_496:
	s_or_b64 exec, exec, s[4:5]
	v_or_b32_e32 v26, 28, v12
	v_ashrrev_i32_e32 v27, 31, v26
	v_lshlrev_b64 v[20:21], 2, v[26:27]
	v_lshl_add_u64 v[28:29], s[6:7], 0, v[20:21]
	v_lshl_add_u64 v[20:21], s[8:9], 0, v[20:21]
	v_readlane_b32 s98, v156, 28
	s_nop 0
	v_readlane_b32 s99, v155, 28
	v_lshlrev_b32_e32 v29, 16, v92
	s_nop 1
	v_mov_b32_e32 v9, s98
	v_mov_b32_e32 v20, s99
	v_add_f32_e32 v9, v13, v9
	v_max_f32_e32 v13, v20, v20
	v_max_f32_e32 v13, v9, v13
	v_sub_f32_e32 v20, v20, v13
	v_sub_f32_e32 v9, v9, v13
	v_mul_f32_e32 v20, 0x3fb8aa3b, v20
	v_mul_f32_e32 v9, 0x3fb8aa3b, v9
	v_exp_f32_e32 v23, v20
	v_exp_f32_e32 v28, v9
	v_mul_f32_e32 v20, v23, v29
	v_pk_fma_f32 v[20:21], v[22:23], v[28:29], v[20:21] op_sel_hi:[1,1,0]
	v_and_b32_e32 v29, 0xffff0000, v92
	v_mov_b32_e32 v25, v23
	v_mul_f32_e32 v22, v23, v29
	v_pk_fma_f32 v[22:23], v[24:25], v[28:29], v[22:23] op_sel_hi:[1,1,0]
	s_nop 0
	v_cvt_pk_bf16_f32 v9, v20, v22
	global_store_dword v[18:19], v9, off
	s_and_saveexec_b64 s[4:5], s[2:3]
	s_cbranch_execz .LBB0_498
	v_lshl_add_u64 v[18:19], v[26:27], 2, s[10:11]
	global_store_dword v[18:19], v13, off
.LBB0_498:
	s_or_b64 exec, exec, s[4:5]
	s_and_saveexec_b64 s[4:5], vcc
	s_cbranch_execz .LBB0_500
	v_or_b32_e32 v18, 28, v0
	v_mov_b32_e32 v19, v1
	v_lshlrev_b64 v[18:19], 2, v[18:19]
	v_lshl_add_u64 v[24:25], s[6:7], 0, v[18:19]
	v_lshl_add_u64 v[18:19], s[8:9], 0, v[18:19]
	v_readlane_b32 s98, v158, 28
	s_nop 0
	v_readlane_b32 s99, v157, 28
	s_lshl_b64 s[0:1], s[22:23], 9
	s_nop 1
	v_mov_b32_e32 v9, s98
	v_mov_b32_e32 v18, s99
	v_add_f32_e32 v9, v84, v9
	v_max_f32_e32 v19, v18, v18
	v_max_f32_e32 v84, v9, v19
	v_sub_f32_e32 v9, v9, v84
	v_sub_f32_e32 v18, v18, v84
	v_mul_f32_e32 v9, 0x3fb8aa3b, v9
	v_mul_f32_e32 v19, 0x3fb8aa3b, v18
	v_exp_f32_e32 v18, v9
	v_exp_f32_e32 v19, v19
	v_mov_b32_e32 v9, v91
	v_pk_mul_f32 v[8:9], v[8:9], v[18:19]
	s_nop 0
	v_add_f32_e32 v8, v8, v9
	v_lshl_add_u64 v[18:19], v[6:7], 0, s[0:1]
	global_store_dword v[18:19], v8, off
.LBB0_500:
	s_or_b64 exec, exec, s[4:5]
	v_or_b32_e32 v24, 29, v12
	v_ashrrev_i32_e32 v25, 31, v24
	v_lshlrev_b64 v[18:19], 2, v[24:25]
	v_lshl_add_u64 v[26:27], s[6:7], 0, v[18:19]
	v_lshl_add_u64 v[18:19], s[8:9], 0, v[18:19]
	v_readlane_b32 s98, v156, 29
	s_nop 0
	v_readlane_b32 s99, v155, 29
	v_lshlrev_b32_e32 v27, 16, v90
	s_nop 1
	v_mov_b32_e32 v9, s98
	v_mov_b32_e32 v18, s99
	v_add_f32_e32 v9, v13, v9
	v_max_f32_e32 v13, v18, v18
	v_max_f32_e32 v13, v9, v13
	v_sub_f32_e32 v18, v18, v13
	v_sub_f32_e32 v9, v9, v13
	v_mul_f32_e32 v18, 0x3fb8aa3b, v18
	v_mul_f32_e32 v9, 0x3fb8aa3b, v9
	v_exp_f32_e32 v21, v18
	v_exp_f32_e32 v26, v9
	v_mul_f32_e32 v18, v21, v27
	v_pk_fma_f32 v[18:19], v[20:21], v[26:27], v[18:19] op_sel_hi:[1,1,0]
	v_and_b32_e32 v27, 0xffff0000, v90
	v_mov_b32_e32 v23, v21
	v_mul_f32_e32 v20, v21, v27
	v_pk_fma_f32 v[20:21], v[22:23], v[26:27], v[20:21] op_sel_hi:[1,1,0]
	s_nop 0
	v_cvt_pk_bf16_f32 v9, v18, v20
	global_store_dword v[16:17], v9, off
	s_and_saveexec_b64 s[4:5], s[2:3]
	s_cbranch_execz .LBB0_502
	v_lshl_add_u64 v[16:17], v[24:25], 2, s[10:11]
	global_store_dword v[16:17], v13, off
.LBB0_502:
	s_or_b64 exec, exec, s[4:5]
	s_and_saveexec_b64 s[4:5], vcc
	s_cbranch_execz .LBB0_504
	v_or_b32_e32 v16, 29, v0
	v_mov_b32_e32 v17, v1
	v_lshlrev_b64 v[16:17], 2, v[16:17]
	v_lshl_add_u64 v[22:23], s[6:7], 0, v[16:17]
	v_lshl_add_u64 v[16:17], s[8:9], 0, v[16:17]
	v_readlane_b32 s98, v158, 29
	s_nop 0
	v_readlane_b32 s99, v157, 29
	s_lshl_b64 s[0:1], s[20:21], 9
	s_nop 1
	v_mov_b32_e32 v9, s98
	v_mov_b32_e32 v16, s99
	v_add_f32_e32 v9, v84, v9
	v_max_f32_e32 v17, v16, v16
	v_max_f32_e32 v84, v9, v17
	v_sub_f32_e32 v9, v9, v84
	v_sub_f32_e32 v16, v16, v84
	v_mul_f32_e32 v9, 0x3fb8aa3b, v9
	v_mul_f32_e32 v17, 0x3fb8aa3b, v16
	v_exp_f32_e32 v16, v9
	v_exp_f32_e32 v17, v17
	v_mov_b32_e32 v9, v89
	v_pk_mul_f32 v[8:9], v[8:9], v[16:17]
	s_nop 0
	v_add_f32_e32 v8, v8, v9
	v_lshl_add_u64 v[16:17], v[6:7], 0, s[0:1]
	global_store_dword v[16:17], v8, off
.LBB0_504:
	s_or_b64 exec, exec, s[4:5]
	v_or_b32_e32 v22, 30, v12
	v_ashrrev_i32_e32 v23, 31, v22
	v_lshlrev_b64 v[16:17], 2, v[22:23]
	v_lshl_add_u64 v[24:25], s[6:7], 0, v[16:17]
	v_lshl_add_u64 v[16:17], s[8:9], 0, v[16:17]
	v_readlane_b32 s98, v156, 30
	v_readlane_b32 s99, v155, 30
	v_lshlrev_b32_e32 v27, 16, v88
	s_nop 1
	v_mov_b32_e32 v9, s98
	v_mov_b32_e32 v19, s99
	v_add_f32_e32 v9, v13, v9
	v_max_f32_e32 v13, v19, v19
	v_max_f32_e32 v24, v9, v13
	v_sub_f32_e32 v13, v19, v24
	v_sub_f32_e32 v9, v9, v24
	v_mul_f32_e32 v13, 0x3fb8aa3b, v13
	v_mul_f32_e32 v9, 0x3fb8aa3b, v9
	v_exp_f32_e32 v19, v13
	v_exp_f32_e32 v26, v9
	v_mul_f32_e32 v16, v19, v27
	v_pk_fma_f32 v[16:17], v[18:19], v[26:27], v[16:17] op_sel_hi:[1,1,0]
	v_and_b32_e32 v27, 0xffff0000, v88
	v_mov_b32_e32 v21, v19
	v_mul_f32_e32 v18, v19, v27
	v_pk_fma_f32 v[18:19], v[20:21], v[26:27], v[18:19] op_sel_hi:[1,1,0]
	s_nop 0
	v_cvt_pk_bf16_f32 v9, v16, v18
	global_store_dword v[14:15], v9, off
	s_and_saveexec_b64 s[4:5], s[2:3]
	s_cbranch_execz .LBB0_506
	v_lshl_add_u64 v[14:15], v[22:23], 2, s[10:11]
	global_store_dword v[14:15], v24, off
.LBB0_506:
	s_or_b64 exec, exec, s[4:5]
	s_and_saveexec_b64 s[4:5], vcc
	s_cbranch_execz .LBB0_508
	v_or_b32_e32 v14, 30, v0
	v_mov_b32_e32 v15, v1
	v_lshlrev_b64 v[14:15], 2, v[14:15]
	v_lshl_add_u64 v[20:21], s[6:7], 0, v[14:15]
	v_lshl_add_u64 v[14:15], s[8:9], 0, v[14:15]
	v_readlane_b32 s98, v158, 30
	v_readlane_b32 s99, v157, 30
	s_lshl_b64 s[0:1], s[18:19], 9
	s_nop 1
	v_mov_b32_e32 v9, s98
	v_mov_b32_e32 v13, s99
	v_add_f32_e32 v9, v84, v9
	v_max_f32_e32 v14, v13, v13
	v_max_f32_e32 v84, v9, v14
	v_sub_f32_e32 v9, v9, v84
	v_sub_f32_e32 v13, v13, v84
	v_mul_f32_e32 v9, 0x3fb8aa3b, v9
	v_mul_f32_e32 v13, 0x3fb8aa3b, v13
	v_exp_f32_e32 v14, v9
	v_exp_f32_e32 v15, v13
	v_mov_b32_e32 v9, v87
	v_pk_mul_f32 v[8:9], v[8:9], v[14:15]
	s_nop 0
	v_add_f32_e32 v8, v8, v9
	v_lshl_add_u64 v[14:15], v[6:7], 0, s[0:1]
	global_store_dword v[14:15], v8, off
.LBB0_508:
	s_or_b64 exec, exec, s[4:5]
	v_or_b32_e32 v12, 31, v12
	v_ashrrev_i32_e32 v13, 31, v12
	v_lshlrev_b64 v[14:15], 2, v[12:13]
	v_lshl_add_u64 v[20:21], s[6:7], 0, v[14:15]
	v_lshl_add_u64 v[14:15], s[8:9], 0, v[14:15]
	v_readlane_b32 s98, v156, 31
	v_readlane_b32 s99, v155, 31
	s_nop 1
	v_mov_b32_e32 v9, s98
	v_mov_b32_e32 v17, s99
	v_add_f32_e32 v9, v24, v9
	v_max_f32_e32 v14, v17, v17
	v_max_f32_e32 v77, v9, v14
	v_sub_f32_e32 v9, v9, v77
	v_sub_f32_e32 v14, v17, v77
	v_mul_f32_e32 v9, 0x3fb8aa3b, v9
	v_mul_f32_e32 v15, 0x3fb8aa3b, v14
	v_exp_f32_e32 v14, v9
	v_exp_f32_e32 v17, v15
	v_lshlrev_b32_e32 v15, 16, v86
	v_pk_mul_f32 v[20:21], v[16:17], v[14:15]
	v_and_b32_e32 v15, 0xffff0000, v86
	v_mov_b32_e32 v19, v17
	v_pk_mul_f32 v[14:15], v[18:19], v[14:15]
	v_mov_b32_e32 v16, v20
	v_mov_b32_e32 v17, v14
	v_mov_b32_e32 v14, v21
	v_pk_add_f32 v[74:75], v[16:17], v[14:15]
	s_nop 0
	v_cvt_pk_bf16_f32 v9, v74, v75
	global_store_dword v[10:11], v9, off
	s_and_saveexec_b64 s[4:5], s[2:3]
	s_cbranch_execz .LBB0_510
	v_lshl_add_u64 v[10:11], v[12:13], 2, s[10:11]
	global_store_dword v[10:11], v77, off
.LBB0_510:
	s_or_b64 exec, exec, s[4:5]
	s_and_saveexec_b64 s[4:5], vcc
	s_cbranch_execz .LBB0_319
	v_or_b32_e32 v0, 31, v0
	v_lshlrev_b64 v[10:11], 2, v[0:1]
	v_lshl_add_u64 v[12:13], s[6:7], 0, v[10:11]
	v_lshl_add_u64 v[10:11], s[8:9], 0, v[10:11]
	v_readlane_b32 s98, v158, 31
	v_readlane_b32 s99, v157, 31
	s_lshl_b64 s[0:1], s[16:17], 9
	s_nop 1
	v_mov_b32_e32 v0, s98
	v_mov_b32_e32 v9, s99
	v_add_f32_e32 v0, v84, v0
	v_max_f32_e32 v10, v9, v9
	v_max_f32_e32 v84, v0, v10
	v_sub_f32_e32 v0, v0, v84
	v_sub_f32_e32 v9, v9, v84
	v_mul_f32_e32 v0, 0x3fb8aa3b, v0
	v_mul_f32_e32 v9, 0x3fb8aa3b, v9
	v_exp_f32_e32 v10, v0
	v_exp_f32_e32 v11, v9
	v_mov_b32_e32 v9, v85
	v_pk_mul_f32 v[8:9], v[8:9], v[10:11]
	s_nop 0
	v_add_f32_e32 v8, v8, v9
	v_lshl_add_u64 v[10:11], v[6:7], 0, s[0:1]
	global_store_dword v[10:11], v8, off
	s_branch .LBB0_319

.LBB0_918:
	s_cmp_lt_i32 s70, 10
	s_cselect_b64 s[18:19], -1, 0
	s_and_b64 s[0:1], s[18:19], s[2:3]
	s_andn2_b64 vcc, exec, s[0:1]
	s_cbranch_vccnz .LBB0_943
	s_cmpk_gt_i32 s33, 0xff
	s_cbranch_scc1 .LBB0_943
	s_add_u32 s20, s80, 0x3f130000
	s_addc_u32 s21, s81, 0
	s_add_u32 s22, s80, 0x3f140000
	s_addc_u32 s23, s81, 0
	s_add_u32 s24, s80, 0x3f190000
	s_addc_u32 s25, s81, 0
	s_add_u32 s26, s80, 0x3f150000
	s_addc_u32 s27, s81, 0
	s_add_u32 s28, s80, 0x12000000
	s_addc_u32 s29, s81, 0
	s_add_u32 s30, s80, 0x1a000000
	s_waitcnt vmcnt(0)
	v_and_b32_e32 v2, 63, v128
	v_lshrrev_b32_e32 v0, 6, v128
	s_addc_u32 s31, s81, 0
	s_add_i32 s0, 16, 0x10000
	v_lshlrev_b32_e32 v1, 13, v0
	v_mov_b32_e32 v139, 0
	v_lshlrev_b32_e32 v138, 4, v2
	v_add_u32_e32 v4, s0, v1
	v_add_u32_e32 v5, 16, v1
	v_lshlrev_b32_e32 v175, 4, v0
	v_lshl_add_u64 v[0:1], s[80:81], 0, v[138:139]
	s_mov_b64 s[0:1], 0x10000000
	v_lshl_add_u64 v[140:141], v[0:1], 0, s[0:1]
	v_lshlrev_b32_e32 v0, 4, v128
	v_and_b32_e32 v142, 0x70, v0
	v_and_b32_e32 v0, 4, v128
	v_cmp_eq_u32_e64 s[2:3], 0, v0
	v_and_b32_e32 v0, 2, v128
	v_and_b32_e32 v1, 1, v128
	v_bfe_u32 v3, v128, 3, 3
	v_add_u32_e32 v188, v5, v138
	v_cmp_eq_u32_e64 s[4:5], 0, v0
	v_cmp_eq_u32_e64 s[6:7], 0, v1
	v_lshlrev_b32_e32 v0, 3, v2
	v_mov_b32_e32 v1, v139
	v_add_u32_e32 v190, v4, v0
	v_sub_u32_e32 v191, v188, v0
	v_lshl_add_u64 v[0:1], s[80:81], 0, v[0:1]
	s_mov_b64 s[0:1], 0x11000000
	v_lshlrev_b32_e32 v192, 1, v2
	v_and_b32_e32 v250, 7, v2
	v_lshrrev_b32_e32 v251, 3, v2
	v_lshl_or_b32 v250, v250, 3, v251
	v_lshlrev_b32_e32 v250, 2, v250
	v_lshl_add_u64 v[146:147], v[0:1], 0, s[0:1]
	v_lshlrev_b32_e32 v0, 1, v192
	v_mov_b32_e32 v1, v139
	v_lshl_add_u64 v[148:149], s[80:81], 0, v[0:1]
	v_lshl_add_u64 v[150:151], s[28:29], 0, v[0:1]
	v_and_b32_e32 v0, 32, v128
	v_cmp_eq_u32_e64 s[8:9], 0, v0
	v_and_b32_e32 v0, 16, v128
	v_cmp_eq_u32_e64 s[10:11], 0, v0
	v_mbcnt_lo_u32_b32 v0, -1, 0
	v_mbcnt_hi_u32_b32 v0, -1, v0
	v_lshlrev_b32_e32 v136, 2, v2
	v_and_b32_e32 v1, 8, v128
	v_and_b32_e32 v2, 64, v0
	v_cmp_eq_u32_e64 s[12:13], 0, v1
	v_xor_b32_e32 v1, 4, v0
	v_add_u32_e32 v2, 64, v2
	v_cmp_lt_i32_e32 vcc, v1, v2
	v_lshl_add_u64 v[152:153], s[58:59], 0, v[138:139]
	v_lshl_add_u64 v[154:155], s[76:77], 0, v[138:139]
	v_cndmask_b32_e32 v1, v0, v1, vcc
	v_lshlrev_b32_e32 v201, 2, v1
	v_xor_b32_e32 v1, 2, v0
	v_cmp_lt_i32_e32 vcc, v1, v2
	s_mov_b64 s[0:1], 0x1000
	s_add_u32 s36, s80, 0x36d00000
	v_cndmask_b32_e32 v1, v0, v1, vcc
	v_lshlrev_b32_e32 v202, 2, v1
	v_xor_b32_e32 v1, 1, v0
	v_cmp_lt_i32_e32 vcc, v1, v2
	v_lshl_add_u64 v[156:157], v[152:153], 0, s[0:1]
	v_lshl_add_u64 v[158:159], v[154:155], 0, s[0:1]
	v_cndmask_b32_e32 v1, v0, v1, vcc
	v_lshlrev_b32_e32 v203, 2, v1
	v_xor_b32_e32 v1, 32, v0
	v_cmp_lt_i32_e32 vcc, v1, v2
	s_mov_b64 s[0:1], 0x1400
	s_addc_u32 s37, s81, 0
	v_cndmask_b32_e32 v1, v0, v1, vcc
	v_lshlrev_b32_e32 v204, 2, v1
	v_xor_b32_e32 v1, 16, v0
	v_cmp_lt_i32_e32 vcc, v1, v2
	v_lshl_add_u64 v[160:161], v[152:153], 0, s[0:1]
	v_lshl_add_u64 v[162:163], v[154:155], 0, s[0:1]
	v_cndmask_b32_e32 v1, v0, v1, vcc
	v_lshlrev_b32_e32 v205, 2, v1
	v_xor_b32_e32 v1, 8, v0
	s_mov_b64 s[0:1], 0x1800
	v_cmp_lt_i32_e32 vcc, v1, v2
	v_lshlrev_b32_e32 v6, 6, v3
	v_mov_b32_e32 v143, v139
	s_add_u32 s38, s80, 0x3ad00000
	v_lshl_add_u64 v[164:165], v[152:153], 0, s[0:1]
	v_lshl_add_u64 v[166:167], v[154:155], 0, s[0:1]
	s_mov_b64 s[0:1], 0x1c00
	v_cndmask_b32_e32 v0, v0, v1, vcc
	v_add_u32_e32 v189, v5, v6
	v_lshl_add_u64 v[144:145], s[30:31], 0, v[142:143]
	s_mov_b32 s35, 0
	v_add_u32_e32 v193, v4, v6
	v_add_u32_e32 v194, 0x400, v188
	v_add_u32_e32 v195, 0x800, v188
	v_add_u32_e32 v196, 0xc00, v188
	s_movk_i32 s41, 0x1000
	v_add_u32_e32 v197, 0x1000, v188
	v_add_u32_e32 v198, 0x1400, v188
	v_add_u32_e32 v199, 0x1800, v188
	v_add_u32_e32 v200, 0x1c00, v188
	s_addc_u32 s39, s81, 0
	v_lshl_add_u64 v[168:169], v[152:153], 0, s[0:1]
	v_lshl_add_u64 v[170:171], v[154:155], 0, s[0:1]
	v_lshl_add_u64 v[172:173], s[78:79], 0, v[138:139]
	v_lshlrev_b32_e32 v206, 2, v0
	v_mov_b32_e32 v174, v142
	v_mov_b32_e32 v137, v142
	v_lshl_add_u32 v207, s33, 7, v175
	s_lshl_b32 s42, s84, 7
	s_mov_b32 s40, 0x3f3504f3
	s_brev_b32 s43, -2
	s_mov_b32 s44, 0xb9c68948
	s_mov_b32 s50, 0x378e98ab
	s_mov_b32 s52, 0x3b7cd369
	s_mov_b32 s54, 0xbcc618b2
	s_mov_b32 s56, 0x3dda74e4
	s_mov_b32 s58, 0x3f228afd
	s_mov_b32 s60, 0x3e03c728
	s_mov_b32 s45, 0xbfb8aa3b
	s_mov_b32 s51, 0x42ce8ed0
	s_mov_b32 s53, 0xc2b17218
	s_mov_b32 s62, 0x3ba10414
	s_mov_b32 s64, 0xba1345e1
	s_mov_b32 s66, 0xbcdac9b8
	s_mov_b32 s68, 0x3de703be
	s_mov_b32 s70, 0xbec09330
	s_mov_b32 s72, 0x3e0375d0
	s_mov_b32 s74, 0x3f9837f0
	s_mov_b64 s[76:77], 0x2000
	s_movk_i32 s55, 0x3000
	v_mov_b32_e32 v208, 0x3727c5ac
	s_mov_b32 s57, 0x800000
	v_mov_b32_e32 v209, 0x7f800000
	s_branch .LBB0_922

.LBB0_931:
	s_lshl_b32 s0, s59, 9
	s_lshl_b32 s1, s34, 9
	v_add_u32_e32 v10, s0, v191
	v_add_u32_e32 v12, s1, v191
	v_add_u32_e32 v32, s0, v190
	v_add_u32_e32 v33, s1, v190
	ds_read_b64 v[10:11], v10
	ds_read_b64 v[12:13], v12
	ds_read_b64 v[16:17], v32
	ds_read_b64 v[18:19], v33
	v_or_b32_e32 v2, s34, v1
	v_or_b32_e32 v4, s59, v0
	v_ashrrev_i32_e32 v5, 31, v4
	v_ashrrev_i32_e32 v3, 31, v2
	v_lshlrev_b64 v[2:3], 9, v[2:3]
	v_lshlrev_b64 v[14:15], 9, v[4:5]
	v_lshl_add_u64 v[4:5], v[4:5], 2, s[24:25]
	v_lshl_add_u64 v[14:15], v[146:147], 0, v[14:15]
	v_lshl_add_u64 v[2:3], v[146:147], 0, v[2:3]
	s_waitcnt lgkmcnt(0)
	v_cvt_f32_i32_e32 v21, v18
	v_cvt_f32_i32_e32 v20, v16
	v_ashrrev_i32_e32 v23, 31, v12
	v_mov_b32_e32 v22, v12
	v_ashrrev_i32_e32 v25, 31, v10
	v_mov_b32_e32 v24, v10
	v_cvt_f32_i32_e32 v18, v17
	v_ashrrev_i32_e32 v17, 31, v13
	v_mov_b32_e32 v16, v13
	v_ashrrev_i32_e32 v13, 31, v11
	v_mov_b32_e32 v12, v11
	global_load_dwordx2 v[4:5], v[4:5], off
	s_nop 0
	global_load_dwordx2 v[14:15], v[14:15], off
	s_nop 0
	global_load_dwordx2 v[2:3], v[2:3], off
	v_lshlrev_b64 v[10:11], 2, v[24:25]
	v_lshlrev_b64 v[22:23], 2, v[22:23]
	v_lshlrev_b64 v[12:13], 2, v[12:13]
	v_lshlrev_b64 v[16:17], 2, v[16:17]
	v_lshl_add_u64 v[24:25], s[20:21], 0, v[10:11]
	v_lshl_add_u64 v[26:27], s[20:21], 0, v[22:23]
	v_lshl_add_u64 v[28:29], s[20:21], 0, v[12:13]
	v_lshl_add_u64 v[10:11], s[22:23], 0, v[10:11]
	v_lshl_add_u64 v[12:13], s[22:23], 0, v[12:13]
	v_lshl_add_u64 v[30:31], s[20:21], 0, v[16:17]
	v_lshl_add_u64 v[22:23], s[22:23], 0, v[22:23]
	v_lshl_add_u64 v[16:17], s[22:23], 0, v[16:17]
	global_load_dword v24, v[24:25], off
	s_nop 0
	global_load_dword v25, v[26:27], off
	s_nop 0
	global_load_dword v26, v[28:29], off
	global_load_dword v27, v[30:31], off
	s_nop 0
	global_load_dword v10, v[10:11], off
	s_nop 0
	global_load_dword v11, v[22:23], off
	s_nop 0
	global_load_dword v12, v[12:13], off
	s_nop 0
	global_load_dword v13, v[16:17], off
	v_cvt_f32_i32_e32 v19, v19
	v_mov_b64_e32 v[6:7], s[44:45]
	v_mov_b64_e32 v[8:9], s[62:63]
	s_add_i32 s59, s59, 2
	s_add_i32 s61, s61, -2
	s_add_i32 s34, s34, 2
	s_cmp_lg_u32 s61, 0
	s_waitcnt vmcnt(9)
	v_mov_b32_e32 v16, v14
	s_waitcnt vmcnt(8)
	v_mov_b32_e32 v17, v2
	v_mov_b32_e32 v2, v15
	s_waitcnt vmcnt(6)
	v_pk_mul_f32 v[14:15], v[4:5], v[24:25]
	s_waitcnt vmcnt(4)
	v_pk_mul_f32 v[4:5], v[4:5], v[26:27]
	s_nop 0
	v_pk_mul_f32 v[4:5], v[4:5], v[18:19]
	s_waitcnt vmcnt(2)
	v_pk_mul_f32 v[10:11], v[16:17], v[10:11]
	s_waitcnt vmcnt(0)
	v_pk_mul_f32 v[2:3], v[2:3], v[12:13]
	v_pk_mul_f32 v[12:13], v[14:15], v[20:21]
	v_pk_mul_f32 v[10:11], v[10:11], 0.5 op_sel_hi:[1,0]
	v_pk_mul_f32 v[2:3], v[2:3], 0.5 op_sel_hi:[1,0]
	v_pk_mul_f32 v[10:11], v[12:13], v[10:11]
	v_pk_mul_f32 v[12:13], v[12:13], s[40:41] op_sel_hi:[1,0]
	v_pk_mul_f32 v[2:3], v[4:5], v[2:3]
	v_pk_mul_f32 v[4:5], v[4:5], s[40:41] op_sel_hi:[1,0]
	v_and_b32_e32 v15, 0x7fffffff, v13
	v_and_b32_e32 v14, 0x7fffffff, v12
	v_pk_mul_f32 v[16:17], v[12:13], v[12:13]
	v_and_b32_e32 v19, 0x7fffffff, v5
	v_and_b32_e32 v18, 0x7fffffff, v4
	v_pk_mul_f32 v[20:21], v[4:5], v[4:5]
	v_pk_fma_f32 v[22:23], v[14:15], s[50:51], v[6:7] op_sel_hi:[1,0,0]
	v_pk_fma_f32 v[24:25], v[16:17], s[64:65], v[8:9] op_sel_hi:[1,0,0]
	v_pk_fma_f32 v[6:7], v[18:19], s[50:51], v[6:7] op_sel_hi:[1,0,0]
	v_pk_fma_f32 v[8:9], v[20:21], s[64:65], v[8:9] op_sel_hi:[1,0,0]
	v_pk_fma_f32 v[22:23], v[14:15], v[22:23], s[52:53] op_sel_hi:[1,1,0]
	v_pk_fma_f32 v[24:25], v[16:17], v[24:25], s[66:67] op_sel_hi:[1,1,0]
	v_pk_fma_f32 v[6:7], v[18:19], v[6:7], s[52:53] op_sel_hi:[1,1,0]
	v_pk_fma_f32 v[8:9], v[20:21], v[8:9], s[66:67] op_sel_hi:[1,1,0]
	v_pk_fma_f32 v[22:23], v[14:15], v[22:23], s[54:55] op_sel_hi:[1,1,0]
	v_pk_fma_f32 v[24:25], v[16:17], v[24:25], s[68:69] op_sel_hi:[1,1,0]
	v_pk_fma_f32 v[6:7], v[18:19], v[6:7], s[54:55] op_sel_hi:[1,1,0]
	v_pk_fma_f32 v[8:9], v[20:21], v[8:9], s[68:69] op_sel_hi:[1,1,0]
	v_pk_fma_f32 v[22:23], v[14:15], v[22:23], s[56:57] op_sel_hi:[1,1,0]
	v_pk_fma_f32 v[24:25], v[16:17], v[24:25], s[70:71] op_sel_hi:[1,1,0]
	v_pk_fma_f32 v[6:7], v[18:19], v[6:7], s[56:57] op_sel_hi:[1,1,0]
	v_pk_fma_f32 v[8:9], v[20:21], v[8:9], s[70:71] op_sel_hi:[1,1,0]
	v_pk_fma_f32 v[22:23], v[14:15], v[22:23], s[58:59] op_sel_hi:[1,1,0]
	v_pk_fma_f32 v[16:17], v[16:17], v[24:25], s[72:73] op_sel_hi:[1,1,0]
	v_pk_fma_f32 v[6:7], v[18:19], v[6:7], s[58:59] op_sel_hi:[1,1,0]
	v_pk_fma_f32 v[8:9], v[20:21], v[8:9], s[72:73] op_sel_hi:[1,1,0]
	v_pk_fma_f32 v[20:21], v[14:15], v[22:23], s[60:61] op_sel_hi:[1,1,0]
	v_pk_fma_f32 v[16:17], v[14:15], v[16:17], v[14:15]
	v_pk_fma_f32 v[6:7], v[18:19], v[6:7], s[60:61] op_sel_hi:[1,1,0]
	v_pk_fma_f32 v[14:15], v[14:15], v[20:21], v[14:15]
	v_pk_fma_f32 v[8:9], v[18:19], v[8:9], v[18:19]
	v_pk_fma_f32 v[6:7], v[18:19], v[6:7], v[18:19]
	v_mul_f32_e32 v18, 0xbfb8aa3b, v15
	v_mul_f32_e32 v19, 0xbfb8aa3b, v14
	v_mul_f32_e32 v20, 0xbfb8aa3b, v7
	v_mul_f32_e32 v21, 0xbfb8aa3b, v6
	v_fma_f32 v22, v15, s45, -v18
	v_rndne_f32_e32 v23, v18
	v_fma_f32 v24, v14, s45, -v19
	v_rndne_f32_e32 v25, v19
	v_fma_f32 v26, v7, s45, -v20
	v_rndne_f32_e32 v27, v20
	v_fma_f32 v28, v6, s45, -v21
	v_rndne_f32_e32 v29, v21
	v_fmac_f32_e32 v22, 0xb2a5705f, v15
	v_sub_f32_e32 v18, v18, v23
	v_fmac_f32_e32 v24, 0xb2a5705f, v14
	v_sub_f32_e32 v19, v19, v25
	v_fmac_f32_e32 v26, 0xb2a5705f, v7
	v_sub_f32_e32 v20, v20, v27
	v_fmac_f32_e32 v28, 0xb2a5705f, v6
	v_sub_f32_e32 v21, v21, v29
	v_add_f32_e32 v18, v18, v22
	v_add_f32_e32 v19, v19, v24
	v_cvt_i32_f32_e32 v23, v23
	v_cvt_i32_f32_e32 v25, v25
	v_add_f32_e32 v20, v20, v26
	v_add_f32_e32 v21, v21, v28
	v_exp_f32_e32 v18, v18
	v_exp_f32_e32 v19, v19
	v_cvt_i32_f32_e32 v27, v27
	v_cvt_i32_f32_e32 v29, v29
	v_exp_f32_e32 v20, v20
	v_exp_f32_e32 v21, v21
	v_ldexp_f32 v18, v18, v23
	v_ldexp_f32 v19, v19, v25
	v_cmp_nlt_f32_e32 vcc, s51, v14
	v_cmp_nlt_f32_e64 s[16:17], s51, v15
	v_ldexp_f32 v20, v20, v27
	v_cmp_nlt_f32_e64 s[0:1], s51, v7
	v_ldexp_f32 v21, v21, v29
	v_cmp_nlt_f32_e64 s[14:15], s51, v6
	v_cndmask_b32_e64 v18, 0, v18, s[16:17]
	v_cndmask_b32_e32 v19, 0, v19, vcc
	v_cmp_ngt_f32_e32 vcc, s53, v14
	v_cmp_ngt_f32_e64 s[16:17], s53, v15
	v_cndmask_b32_e64 v14, 0, v20, s[0:1]
	v_cmp_ngt_f32_e64 s[0:1], s53, v7
	v_cndmask_b32_e64 v20, 0, v21, s[14:15]
	v_cmp_ngt_f32_e64 s[14:15], s53, v6
	v_cndmask_b32_e64 v7, v209, v18, s[16:17]
	v_cndmask_b32_e32 v6, v209, v19, vcc
	v_cndmask_b32_e64 v15, v209, v14, s[0:1]
	v_cndmask_b32_e64 v14, v209, v20, s[14:15]
	v_pk_add_f32 v[6:7], v[6:7], 1.0 op_sel_hi:[1,0] neg_lo:[1,0] neg_hi:[1,0]
	v_cmp_lt_f32_e64 vcc, |v13|, 1.0
	v_cmp_lt_f32_e64 s[16:17], |v12|, 1.0
	v_pk_add_f32 v[14:15], v[14:15], 1.0 op_sel_hi:[1,0] neg_lo:[1,0] neg_hi:[1,0]
	v_cmp_lt_f32_e64 s[0:1], |v5|, 1.0
	v_cmp_lt_f32_e64 s[14:15], |v4|, 1.0
	v_cndmask_b32_e64 v6, v6, v16, s[16:17]
	v_cndmask_b32_e32 v7, v7, v17, vcc
	v_cndmask_b32_e64 v8, v14, v8, s[14:15]
	v_cndmask_b32_e64 v9, v15, v9, s[0:1]
	v_bfi_b32 v7, s43, v7, v13
	v_bfi_b32 v6, s43, v6, v12
	v_bfi_b32 v5, s43, v9, v5
	v_bfi_b32 v4, s43, v8, v4
	v_pk_add_f32 v[6:7], v[6:7], 1.0 op_sel_hi:[1,0]
	v_pk_add_f32 v[4:5], v[4:5], 1.0 op_sel_hi:[1,0]
	v_pk_mul_f32 v[6:7], v[10:11], v[6:7]
	v_pk_mul_f32 v[2:3], v[2:3], v[4:5]
	ds_write_b32 v32, v6
	ds_write_b32 v33, v7
	ds_write_b32 v32, v2 offset:4
	ds_write_b32 v33, v3 offset:4
	s_cbranch_scc1 .LBB0_931
	ds_read_b128 v[6:9], v189
	ds_read_b128 v[22:25], v189 offset:16
	ds_read_b128 v[38:41], v189 offset:32
	ds_read_b128 v[54:57], v189 offset:48
	v_lshlrev_b64 v[64:65], 12, v[176:177]
	s_waitcnt lgkmcnt(3)
	v_lshlrev_b32_e32 v0, 7, v7
	v_lshlrev_b32_e32 v1, 7, v6
	v_lshlrev_b32_e32 v9, 7, v9
	v_lshlrev_b32_e32 v8, 7, v8
	s_waitcnt lgkmcnt(2)
	v_lshlrev_b32_e32 v16, 7, v23
	v_lshlrev_b32_e32 v17, 7, v22
	v_lshlrev_b32_e32 v25, 7, v25
	v_lshlrev_b32_e32 v24, 7, v24
	s_waitcnt lgkmcnt(1)
	v_lshlrev_b32_e32 v32, 7, v39
	v_lshlrev_b32_e32 v33, 7, v38
	v_lshlrev_b32_e32 v41, 7, v41
	v_lshlrev_b32_e32 v40, 7, v40
	s_waitcnt lgkmcnt(0)
	v_lshlrev_b32_e32 v48, 7, v55
	v_lshlrev_b32_e32 v49, 7, v54
	v_lshlrev_b32_e32 v57, 7, v57
	v_lshlrev_b32_e32 v56, 7, v56
	v_or_b32_e32 v4, v0, v137
	v_or_b32_e32 v0, v1, v174
	v_or_b32_e32 v12, v9, v137
	v_or_b32_e32 v8, v8, v174
	v_or_b32_e32 v20, v16, v137
	v_or_b32_e32 v16, v17, v174
	v_or_b32_e32 v28, v25, v137
	v_or_b32_e32 v24, v24, v174
	v_or_b32_e32 v36, v32, v137
	v_or_b32_e32 v32, v33, v174
	v_or_b32_e32 v44, v41, v137
	v_or_b32_e32 v40, v40, v174
	v_or_b32_e32 v52, v48, v137
	v_or_b32_e32 v48, v49, v174
	v_or_b32_e32 v60, v57, v137
	v_or_b32_e32 v56, v56, v174
	v_lshl_add_u64 v[66:67], v[148:149], 0, v[64:65]
	global_load_dwordx4 v[0:3], v0, s[38:39]
	s_nop 0
	global_load_dwordx4 v[4:7], v4, s[38:39]
	s_nop 0
	global_load_dwordx4 v[8:11], v8, s[38:39]
	s_nop 0
	global_load_dwordx4 v[12:15], v12, s[38:39]
	s_nop 0
	global_load_dwordx4 v[16:19], v16, s[38:39]
	s_nop 0
	global_load_dwordx4 v[20:23], v20, s[38:39]
	s_nop 0
	global_load_dwordx4 v[24:27], v24, s[38:39]
	s_nop 0
	global_load_dwordx4 v[28:31], v28, s[38:39]
	s_nop 0
	global_load_dwordx4 v[32:35], v32, s[38:39]
	s_nop 0
	global_load_dwordx4 v[36:39], v36, s[38:39]
	s_nop 0
	global_load_dwordx4 v[40:43], v40, s[38:39]
	s_nop 0
	global_load_dwordx4 v[44:47], v44, s[38:39]
	s_nop 0
	global_load_dwordx4 v[48:51], v48, s[38:39]
	s_nop 0
	global_load_dwordx4 v[52:55], v52, s[38:39]
	s_nop 0
	global_load_dwordx4 v[56:59], v56, s[38:39]
	s_nop 0
	global_load_dwordx4 v[60:63], v60, s[38:39]
	v_lshl_add_u64 v[64:65], v[150:151], 0, v[64:65]
	v_mbcnt_lo_u32_b32 v68, -1, 0
	v_mbcnt_hi_u32_b32 v68, -1, v68
	v_and_b32_e32 v68, 15, v68
	v_add_u32_e32 v68, v68, v176
	v_mov_b32_e32 v69, v139
	v_lshl_add_u64 v[68:69], v[68:69], 3, s[26:27]
	global_load_dword v210, v[66:67], off nt
	global_load_dword v211, v[64:65], off nt
	global_load_dwordx2 v[248:249], v[68:69], off
	s_waitcnt vmcnt(0)
	v_mov_b32_e32 v138, v139
	s_mov_b32 s0, 0
	s_mov_b32 s16, 16
	s_movk_i32 s17, 0x100
	s_mov_b32 s34, 0x40000
	v_mov_b64_e32 v[178:179], v[138:139]
	v_mov_b64_e32 v[180:181], v[138:139]
	s_branch .LBB0_934
.LBB0_933:
	v_cvt_pk_f32_fp8_e32 v[222:223], v124
	v_cvt_pk_f32_fp8_sdwa v[224:225], v124 src0_sel:WORD_1
	v_cvt_pk_f32_fp8_e32 v[226:227], v125
	v_cvt_pk_f32_fp8_sdwa v[124:125], v125 src0_sel:WORD_1
	v_lshl_add_u32 v128, s59, 9, v193
	v_cvt_pk_f32_fp8_e32 v[234:235], v120
	v_cvt_pk_f32_fp8_sdwa v[236:237], v120 src0_sel:WORD_1
	v_cvt_pk_f32_fp8_e32 v[238:239], v121
	v_cvt_pk_f32_fp8_sdwa v[120:121], v121 src0_sel:WORD_1
	ds_read_b128 v[132:135], v128
	ds_read_b128 v[214:217], v128 offset:16
	ds_read_b128 v[218:221], v128 offset:32
	ds_read_b128 v[128:131], v128 offset:48
	v_cvt_pk_f32_fp8_e32 v[228:229], v126
	s_waitcnt lgkmcnt(3)
	v_pk_fma_f32 v[222:223], v[132:133], v[222:223], 0 op_sel_hi:[0,1,0]
	v_pk_fma_f32 v[224:225], v[132:133], v[224:225], 0 op_sel_hi:[0,1,0]
	v_pk_fma_f32 v[124:125], v[132:133], v[124:125], 0 op_sel_hi:[0,1,0]
	v_cvt_pk_f32_fp8_sdwa v[230:231], v126 src0_sel:WORD_1
	v_cvt_pk_f32_fp8_e32 v[232:233], v127
	v_cvt_pk_f32_fp8_sdwa v[126:127], v127 src0_sel:WORD_1
	v_pk_fma_f32 v[222:223], v[132:133], v[234:235], v[222:223] op_sel:[1,0,0]
	v_pk_fma_f32 v[224:225], v[132:133], v[236:237], v[224:225] op_sel:[1,0,0]
	v_pk_fma_f32 v[120:121], v[132:133], v[120:121], v[124:125] op_sel:[1,0,0]
	v_cvt_pk_f32_fp8_e32 v[124:125], v122
	v_cvt_pk_f32_fp8_sdwa v[234:235], v122 src0_sel:WORD_1
	v_cvt_pk_f32_fp8_e32 v[236:237], v123
	v_cvt_pk_f32_fp8_sdwa v[122:123], v123 src0_sel:WORD_1
	v_pk_fma_f32 v[226:227], v[132:133], v[226:227], 0 op_sel_hi:[0,1,0]
	v_pk_fma_f32 v[228:229], v[132:133], v[228:229], 0 op_sel_hi:[0,1,0]
	v_pk_fma_f32 v[230:231], v[132:133], v[230:231], 0 op_sel_hi:[0,1,0]
	v_pk_fma_f32 v[232:233], v[132:133], v[232:233], 0 op_sel_hi:[0,1,0]
	v_pk_fma_f32 v[126:127], v[132:133], v[126:127], 0 op_sel_hi:[0,1,0]
	v_pk_fma_f32 v[226:227], v[132:133], v[238:239], v[226:227] op_sel:[1,0,0]
	v_pk_fma_f32 v[124:125], v[132:133], v[124:125], v[228:229] op_sel:[1,0,0]
	v_pk_fma_f32 v[228:229], v[132:133], v[234:235], v[230:231] op_sel:[1,0,0]
	v_pk_fma_f32 v[230:231], v[132:133], v[236:237], v[232:233] op_sel:[1,0,0]
	v_pk_fma_f32 v[122:123], v[132:133], v[122:123], v[126:127] op_sel:[1,0,0]
	v_cvt_pk_f32_fp8_e32 v[126:127], v116
	v_cvt_pk_f32_fp8_sdwa v[132:133], v116 src0_sel:WORD_1
	v_cvt_pk_f32_fp8_e32 v[232:233], v117
	v_cvt_pk_f32_fp8_sdwa v[116:117], v117 src0_sel:WORD_1
	v_pk_fma_f32 v[126:127], v[134:135], v[126:127], v[222:223] op_sel_hi:[0,1,1]
	v_pk_fma_f32 v[132:133], v[134:135], v[132:133], v[224:225] op_sel_hi:[0,1,1]
	v_pk_fma_f32 v[222:223], v[134:135], v[232:233], v[226:227] op_sel_hi:[0,1,1]
	v_pk_fma_f32 v[116:117], v[134:135], v[116:117], v[120:121] op_sel_hi:[0,1,1]
	v_cvt_pk_f32_fp8_e32 v[120:121], v118
	v_cvt_pk_f32_fp8_sdwa v[224:225], v118 src0_sel:WORD_1
	v_cvt_pk_f32_fp8_e32 v[226:227], v119
	v_cvt_pk_f32_fp8_sdwa v[118:119], v119 src0_sel:WORD_1
	v_pk_fma_f32 v[120:121], v[134:135], v[120:121], v[124:125] op_sel_hi:[0,1,1]
	v_pk_fma_f32 v[124:125], v[134:135], v[224:225], v[228:229] op_sel_hi:[0,1,1]
	v_pk_fma_f32 v[224:225], v[134:135], v[226:227], v[230:231] op_sel_hi:[0,1,1]
	v_pk_fma_f32 v[118:119], v[134:135], v[118:119], v[122:123] op_sel_hi:[0,1,1]
	v_mov_b32_e32 v122, v135
	v_cvt_pk_f32_fp8_e32 v[134:135], v112
	v_cvt_pk_f32_fp8_sdwa v[226:227], v112 src0_sel:WORD_1
	v_cvt_pk_f32_fp8_e32 v[228:229], v113
	v_cvt_pk_f32_fp8_sdwa v[112:113], v113 src0_sel:WORD_1
	v_pk_fma_f32 v[126:127], v[122:123], v[134:135], v[126:127] op_sel_hi:[0,1,1]
	v_pk_fma_f32 v[132:133], v[122:123], v[226:227], v[132:133] op_sel_hi:[0,1,1]
	v_pk_fma_f32 v[134:135], v[122:123], v[228:229], v[222:223] op_sel_hi:[0,1,1]
	v_pk_fma_f32 v[112:113], v[122:123], v[112:113], v[116:117] op_sel_hi:[0,1,1]
	v_cvt_pk_f32_fp8_e32 v[116:117], v114
	v_cvt_pk_f32_fp8_sdwa v[222:223], v114 src0_sel:WORD_1
	v_cvt_pk_f32_fp8_e32 v[226:227], v115
	v_cvt_pk_f32_fp8_sdwa v[114:115], v115 src0_sel:WORD_1
	v_pk_fma_f32 v[116:117], v[122:123], v[116:117], v[120:121] op_sel_hi:[0,1,1]
	v_pk_fma_f32 v[120:121], v[122:123], v[222:223], v[124:125] op_sel_hi:[0,1,1]
	v_pk_fma_f32 v[124:125], v[122:123], v[226:227], v[224:225] op_sel_hi:[0,1,1]
	v_pk_fma_f32 v[114:115], v[122:123], v[114:115], v[118:119] op_sel_hi:[0,1,1]
	v_cvt_pk_f32_fp8_e32 v[118:119], v108
	v_cvt_pk_f32_fp8_sdwa v[122:123], v108 src0_sel:WORD_1
	v_cvt_pk_f32_fp8_e32 v[222:223], v109
	v_cvt_pk_f32_fp8_sdwa v[108:109], v109 src0_sel:WORD_1
	s_waitcnt lgkmcnt(2)
	v_pk_fma_f32 v[118:119], v[214:215], v[118:119], v[126:127] op_sel_hi:[0,1,1]
	v_pk_fma_f32 v[122:123], v[214:215], v[122:123], v[132:133] op_sel_hi:[0,1,1]
	v_pk_fma_f32 v[126:127], v[214:215], v[222:223], v[134:135] op_sel_hi:[0,1,1]
	v_pk_fma_f32 v[108:109], v[214:215], v[108:109], v[112:113] op_sel_hi:[0,1,1]
	v_cvt_pk_f32_fp8_e32 v[112:113], v110
	v_cvt_pk_f32_fp8_sdwa v[132:133], v110 src0_sel:WORD_1
	v_cvt_pk_f32_fp8_e32 v[134:135], v111
	v_cvt_pk_f32_fp8_sdwa v[110:111], v111 src0_sel:WORD_1
	v_pk_fma_f32 v[112:113], v[214:215], v[112:113], v[116:117] op_sel_hi:[0,1,1]
	v_pk_fma_f32 v[116:117], v[214:215], v[132:133], v[120:121] op_sel_hi:[0,1,1]
	v_pk_fma_f32 v[120:121], v[214:215], v[134:135], v[124:125] op_sel_hi:[0,1,1]
	v_pk_fma_f32 v[110:111], v[214:215], v[110:111], v[114:115] op_sel_hi:[0,1,1]
	v_cvt_pk_f32_fp8_e32 v[114:115], v104
	v_cvt_pk_f32_fp8_sdwa v[124:125], v104 src0_sel:WORD_1
	v_cvt_pk_f32_fp8_e32 v[132:133], v105
	v_cvt_pk_f32_fp8_sdwa v[104:105], v105 src0_sel:WORD_1
	v_pk_fma_f32 v[114:115], v[214:215], v[114:115], v[118:119] op_sel:[1,0,0]
	v_pk_fma_f32 v[118:119], v[214:215], v[124:125], v[122:123] op_sel:[1,0,0]
	v_pk_fma_f32 v[122:123], v[214:215], v[132:133], v[126:127] op_sel:[1,0,0]
	v_pk_fma_f32 v[104:105], v[214:215], v[104:105], v[108:109] op_sel:[1,0,0]
	v_cvt_pk_f32_fp8_e32 v[108:109], v106
	v_cvt_pk_f32_fp8_sdwa v[124:125], v106 src0_sel:WORD_1
	v_cvt_pk_f32_fp8_e32 v[126:127], v107
	v_cvt_pk_f32_fp8_sdwa v[106:107], v107 src0_sel:WORD_1
	v_pk_fma_f32 v[108:109], v[214:215], v[108:109], v[112:113] op_sel:[1,0,0]
	v_pk_fma_f32 v[112:113], v[214:215], v[124:125], v[116:117] op_sel:[1,0,0]
	v_pk_fma_f32 v[116:117], v[214:215], v[126:127], v[120:121] op_sel:[1,0,0]
	v_pk_fma_f32 v[106:107], v[214:215], v[106:107], v[110:111] op_sel:[1,0,0]
	v_cvt_pk_f32_fp8_e32 v[110:111], v100
	v_cvt_pk_f32_fp8_sdwa v[120:121], v100 src0_sel:WORD_1
	v_cvt_pk_f32_fp8_e32 v[124:125], v101
	v_cvt_pk_f32_fp8_sdwa v[100:101], v101 src0_sel:WORD_1
	v_pk_fma_f32 v[110:111], v[216:217], v[110:111], v[114:115] op_sel_hi:[0,1,1]
	v_pk_fma_f32 v[114:115], v[216:217], v[120:121], v[118:119] op_sel_hi:[0,1,1]
	v_pk_fma_f32 v[118:119], v[216:217], v[124:125], v[122:123] op_sel_hi:[0,1,1]
	v_pk_fma_f32 v[100:101], v[216:217], v[100:101], v[104:105] op_sel_hi:[0,1,1]
	v_cvt_pk_f32_fp8_e32 v[104:105], v102
	v_cvt_pk_f32_fp8_sdwa v[120:121], v102 src0_sel:WORD_1
	v_cvt_pk_f32_fp8_e32 v[122:123], v103
	v_cvt_pk_f32_fp8_sdwa v[102:103], v103 src0_sel:WORD_1
	v_pk_fma_f32 v[104:105], v[216:217], v[104:105], v[108:109] op_sel_hi:[0,1,1]
	v_pk_fma_f32 v[108:109], v[216:217], v[120:121], v[112:113] op_sel_hi:[0,1,1]
	v_pk_fma_f32 v[112:113], v[216:217], v[122:123], v[116:117] op_sel_hi:[0,1,1]
	v_cvt_pk_f32_fp8_e32 v[116:117], v96
	v_cvt_pk_f32_fp8_sdwa v[120:121], v96 src0_sel:WORD_1
	v_cvt_pk_f32_fp8_e32 v[122:123], v97
	v_cvt_pk_f32_fp8_sdwa v[96:97], v97 src0_sel:WORD_1
	v_pk_fma_f32 v[102:103], v[216:217], v[102:103], v[106:107] op_sel_hi:[0,1,1]
	v_mov_b32_e32 v106, v217
	v_pk_fma_f32 v[110:111], v[106:107], v[116:117], v[110:111] op_sel_hi:[0,1,1]
	v_pk_fma_f32 v[114:115], v[106:107], v[120:121], v[114:115] op_sel_hi:[0,1,1]
	v_pk_fma_f32 v[116:117], v[106:107], v[122:123], v[118:119] op_sel_hi:[0,1,1]
	v_pk_fma_f32 v[96:97], v[106:107], v[96:97], v[100:101] op_sel_hi:[0,1,1]
	v_cvt_pk_f32_fp8_e32 v[100:101], v98
	v_cvt_pk_f32_fp8_sdwa v[118:119], v98 src0_sel:WORD_1
	v_cvt_pk_f32_fp8_e32 v[120:121], v99
	v_cvt_pk_f32_fp8_sdwa v[98:99], v99 src0_sel:WORD_1
	v_pk_fma_f32 v[100:101], v[106:107], v[100:101], v[104:105] op_sel_hi:[0,1,1]
	v_pk_fma_f32 v[104:105], v[106:107], v[118:119], v[108:109] op_sel_hi:[0,1,1]
	v_pk_fma_f32 v[108:109], v[106:107], v[120:121], v[112:113] op_sel_hi:[0,1,1]
	v_pk_fma_f32 v[98:99], v[106:107], v[98:99], v[102:103] op_sel_hi:[0,1,1]
	v_cvt_pk_f32_fp8_e32 v[102:103], v92
	v_cvt_pk_f32_fp8_sdwa v[106:107], v92 src0_sel:WORD_1
	v_cvt_pk_f32_fp8_e32 v[112:113], v93
	v_cvt_pk_f32_fp8_sdwa v[92:93], v93 src0_sel:WORD_1
	s_waitcnt lgkmcnt(1)
	v_pk_fma_f32 v[102:103], v[218:219], v[102:103], v[110:111] op_sel_hi:[0,1,1]
	v_pk_fma_f32 v[106:107], v[218:219], v[106:107], v[114:115] op_sel_hi:[0,1,1]
	v_pk_fma_f32 v[110:111], v[218:219], v[112:113], v[116:117] op_sel_hi:[0,1,1]
	v_pk_fma_f32 v[92:93], v[218:219], v[92:93], v[96:97] op_sel_hi:[0,1,1]
	v_cvt_pk_f32_fp8_e32 v[96:97], v94
	v_cvt_pk_f32_fp8_sdwa v[112:113], v94 src0_sel:WORD_1
	v_cvt_pk_f32_fp8_e32 v[114:115], v95
	v_cvt_pk_f32_fp8_sdwa v[94:95], v95 src0_sel:WORD_1
	v_pk_fma_f32 v[96:97], v[218:219], v[96:97], v[100:101] op_sel_hi:[0,1,1]
	v_pk_fma_f32 v[100:101], v[218:219], v[112:113], v[104:105] op_sel_hi:[0,1,1]
	v_pk_fma_f32 v[104:105], v[218:219], v[114:115], v[108:109] op_sel_hi:[0,1,1]
	v_pk_fma_f32 v[94:95], v[218:219], v[94:95], v[98:99] op_sel_hi:[0,1,1]
	v_cvt_pk_f32_fp8_e32 v[98:99], v88
	v_cvt_pk_f32_fp8_sdwa v[108:109], v88 src0_sel:WORD_1
	v_cvt_pk_f32_fp8_e32 v[112:113], v89
	v_cvt_pk_f32_fp8_sdwa v[88:89], v89 src0_sel:WORD_1
	v_pk_fma_f32 v[98:99], v[218:219], v[98:99], v[102:103] op_sel:[1,0,0]
	v_pk_fma_f32 v[102:103], v[218:219], v[108:109], v[106:107] op_sel:[1,0,0]
	v_pk_fma_f32 v[106:107], v[218:219], v[112:113], v[110:111] op_sel:[1,0,0]
	v_pk_fma_f32 v[88:89], v[218:219], v[88:89], v[92:93] op_sel:[1,0,0]
	v_cvt_pk_f32_fp8_e32 v[92:93], v90
	v_cvt_pk_f32_fp8_sdwa v[108:109], v90 src0_sel:WORD_1
	v_cvt_pk_f32_fp8_e32 v[110:111], v91
	v_cvt_pk_f32_fp8_sdwa v[90:91], v91 src0_sel:WORD_1
	v_pk_fma_f32 v[92:93], v[218:219], v[92:93], v[96:97] op_sel:[1,0,0]
	v_pk_fma_f32 v[96:97], v[218:219], v[108:109], v[100:101] op_sel:[1,0,0]
	v_pk_fma_f32 v[100:101], v[218:219], v[110:111], v[104:105] op_sel:[1,0,0]
	v_pk_fma_f32 v[90:91], v[218:219], v[90:91], v[94:95] op_sel:[1,0,0]
	v_cvt_pk_f32_fp8_e32 v[94:95], v84
	v_cvt_pk_f32_fp8_sdwa v[104:105], v84 src0_sel:WORD_1
	v_cvt_pk_f32_fp8_e32 v[108:109], v85
	v_cvt_pk_f32_fp8_sdwa v[84:85], v85 src0_sel:WORD_1
	v_pk_fma_f32 v[94:95], v[220:221], v[94:95], v[98:99] op_sel_hi:[0,1,1]
	v_pk_fma_f32 v[98:99], v[220:221], v[104:105], v[102:103] op_sel_hi:[0,1,1]
	v_pk_fma_f32 v[102:103], v[220:221], v[108:109], v[106:107] op_sel_hi:[0,1,1]
	v_pk_fma_f32 v[84:85], v[220:221], v[84:85], v[88:89] op_sel_hi:[0,1,1]
	v_cvt_pk_f32_fp8_e32 v[88:89], v86
	v_cvt_pk_f32_fp8_sdwa v[104:105], v86 src0_sel:WORD_1
	v_cvt_pk_f32_fp8_e32 v[106:107], v87
	v_cvt_pk_f32_fp8_sdwa v[86:87], v87 src0_sel:WORD_1
	v_pk_fma_f32 v[88:89], v[220:221], v[88:89], v[92:93] op_sel_hi:[0,1,1]
	v_pk_fma_f32 v[92:93], v[220:221], v[104:105], v[96:97] op_sel_hi:[0,1,1]
	v_pk_fma_f32 v[96:97], v[220:221], v[106:107], v[100:101] op_sel_hi:[0,1,1]
	v_cvt_pk_f32_fp8_e32 v[100:101], v80
	v_cvt_pk_f32_fp8_sdwa v[104:105], v80 src0_sel:WORD_1
	v_cvt_pk_f32_fp8_e32 v[106:107], v81
	v_cvt_pk_f32_fp8_sdwa v[80:81], v81 src0_sel:WORD_1
	v_pk_fma_f32 v[86:87], v[220:221], v[86:87], v[90:91] op_sel_hi:[0,1,1]
	v_mov_b32_e32 v90, v221
	v_pk_fma_f32 v[94:95], v[90:91], v[100:101], v[94:95] op_sel_hi:[0,1,1]
	v_pk_fma_f32 v[98:99], v[90:91], v[104:105], v[98:99] op_sel_hi:[0,1,1]
	v_pk_fma_f32 v[100:101], v[90:91], v[106:107], v[102:103] op_sel_hi:[0,1,1]
	v_pk_fma_f32 v[80:81], v[90:91], v[80:81], v[84:85] op_sel_hi:[0,1,1]
	v_cvt_pk_f32_fp8_e32 v[84:85], v82
	v_cvt_pk_f32_fp8_sdwa v[102:103], v82 src0_sel:WORD_1
	v_cvt_pk_f32_fp8_e32 v[104:105], v83
	v_cvt_pk_f32_fp8_sdwa v[82:83], v83 src0_sel:WORD_1
	v_pk_fma_f32 v[84:85], v[90:91], v[84:85], v[88:89] op_sel_hi:[0,1,1]
	v_pk_fma_f32 v[88:89], v[90:91], v[102:103], v[92:93] op_sel_hi:[0,1,1]
	v_pk_fma_f32 v[92:93], v[90:91], v[104:105], v[96:97] op_sel_hi:[0,1,1]
	v_pk_fma_f32 v[82:83], v[90:91], v[82:83], v[86:87] op_sel_hi:[0,1,1]
	v_cvt_pk_f32_fp8_e32 v[86:87], v76
	v_cvt_pk_f32_fp8_sdwa v[90:91], v76 src0_sel:WORD_1
	v_cvt_pk_f32_fp8_e32 v[96:97], v77
	v_cvt_pk_f32_fp8_sdwa v[76:77], v77 src0_sel:WORD_1
	s_waitcnt lgkmcnt(0)
	v_pk_fma_f32 v[86:87], v[128:129], v[86:87], v[94:95] op_sel_hi:[0,1,1]
	v_pk_fma_f32 v[90:91], v[128:129], v[90:91], v[98:99] op_sel_hi:[0,1,1]
	v_pk_fma_f32 v[94:95], v[128:129], v[96:97], v[100:101] op_sel_hi:[0,1,1]
	v_pk_fma_f32 v[76:77], v[128:129], v[76:77], v[80:81] op_sel_hi:[0,1,1]
	v_cvt_pk_f32_fp8_e32 v[80:81], v78
	v_cvt_pk_f32_fp8_sdwa v[96:97], v78 src0_sel:WORD_1
	v_cvt_pk_f32_fp8_e32 v[98:99], v79
	v_cvt_pk_f32_fp8_sdwa v[78:79], v79 src0_sel:WORD_1
	v_pk_fma_f32 v[80:81], v[128:129], v[80:81], v[84:85] op_sel_hi:[0,1,1]
	v_pk_fma_f32 v[84:85], v[128:129], v[96:97], v[88:89] op_sel_hi:[0,1,1]
	v_pk_fma_f32 v[88:89], v[128:129], v[98:99], v[92:93] op_sel_hi:[0,1,1]
	v_pk_fma_f32 v[78:79], v[128:129], v[78:79], v[82:83] op_sel_hi:[0,1,1]
	v_cvt_pk_f32_fp8_e32 v[82:83], v72
	v_cvt_pk_f32_fp8_sdwa v[92:93], v72 src0_sel:WORD_1
	v_cvt_pk_f32_fp8_e32 v[96:97], v73
	v_cvt_pk_f32_fp8_sdwa v[72:73], v73 src0_sel:WORD_1
	v_pk_fma_f32 v[82:83], v[128:129], v[82:83], v[86:87] op_sel:[1,0,0]
	v_pk_fma_f32 v[86:87], v[128:129], v[92:93], v[90:91] op_sel:[1,0,0]
	v_pk_fma_f32 v[90:91], v[128:129], v[96:97], v[94:95] op_sel:[1,0,0]
	v_pk_fma_f32 v[72:73], v[128:129], v[72:73], v[76:77] op_sel:[1,0,0]
	v_cvt_pk_f32_fp8_e32 v[76:77], v74
	v_cvt_pk_f32_fp8_sdwa v[92:93], v74 src0_sel:WORD_1
	v_cvt_pk_f32_fp8_e32 v[94:95], v75
	v_cvt_pk_f32_fp8_sdwa v[74:75], v75 src0_sel:WORD_1
	v_pk_fma_f32 v[76:77], v[128:129], v[76:77], v[80:81] op_sel:[1,0,0]
	v_pk_fma_f32 v[80:81], v[128:129], v[92:93], v[84:85] op_sel:[1,0,0]
	v_pk_fma_f32 v[84:85], v[128:129], v[94:95], v[88:89] op_sel:[1,0,0]
	v_pk_fma_f32 v[74:75], v[128:129], v[74:75], v[78:79] op_sel:[1,0,0]
	v_cvt_pk_f32_fp8_e32 v[78:79], v68
	v_cvt_pk_f32_fp8_sdwa v[88:89], v68 src0_sel:WORD_1
	v_cvt_pk_f32_fp8_e32 v[92:93], v69
	v_cvt_pk_f32_fp8_sdwa v[68:69], v69 src0_sel:WORD_1
	v_pk_fma_f32 v[78:79], v[130:131], v[78:79], v[82:83] op_sel_hi:[0,1,1]
	v_pk_fma_f32 v[82:83], v[130:131], v[88:89], v[86:87] op_sel_hi:[0,1,1]
	v_pk_fma_f32 v[86:87], v[130:131], v[92:93], v[90:91] op_sel_hi:[0,1,1]
	v_pk_fma_f32 v[68:69], v[130:131], v[68:69], v[72:73] op_sel_hi:[0,1,1]
	v_cvt_pk_f32_fp8_e32 v[72:73], v70
	v_cvt_pk_f32_fp8_sdwa v[88:89], v70 src0_sel:WORD_1
	v_cvt_pk_f32_fp8_e32 v[90:91], v71
	v_cvt_pk_f32_fp8_sdwa v[70:71], v71 src0_sel:WORD_1
	v_pk_fma_f32 v[72:73], v[130:131], v[72:73], v[76:77] op_sel_hi:[0,1,1]
	v_pk_fma_f32 v[76:77], v[130:131], v[88:89], v[80:81] op_sel_hi:[0,1,1]
	v_pk_fma_f32 v[80:81], v[130:131], v[90:91], v[84:85] op_sel_hi:[0,1,1]
	v_cvt_pk_f32_fp8_e32 v[84:85], v64
	v_cvt_pk_f32_fp8_sdwa v[88:89], v64 src0_sel:WORD_1
	v_cvt_pk_f32_fp8_e32 v[90:91], v65
	v_cvt_pk_f32_fp8_sdwa v[64:65], v65 src0_sel:WORD_1
	v_pk_fma_f32 v[70:71], v[130:131], v[70:71], v[74:75] op_sel_hi:[0,1,1]
	v_mov_b32_e32 v74, v131
	v_pk_fma_f32 v[78:79], v[74:75], v[84:85], v[78:79] op_sel_hi:[0,1,1]
	v_pk_fma_f32 v[64:65], v[74:75], v[64:65], v[68:69] op_sel_hi:[0,1,1]
	v_cvt_pk_f32_fp8_e32 v[68:69], v66
	v_pk_fma_f32 v[82:83], v[74:75], v[88:89], v[82:83] op_sel_hi:[0,1,1]
	v_pk_fma_f32 v[84:85], v[74:75], v[90:91], v[86:87] op_sel_hi:[0,1,1]
	v_cvt_pk_f32_fp8_sdwa v[86:87], v66 src0_sel:WORD_1
	v_cvt_pk_f32_fp8_e32 v[88:89], v67
	v_cvt_pk_f32_fp8_sdwa v[66:67], v67 src0_sel:WORD_1
	v_pk_fma_f32 v[68:69], v[74:75], v[68:69], v[72:73] op_sel_hi:[0,1,1]
	v_pk_fma_f32 v[72:73], v[74:75], v[86:87], v[76:77] op_sel_hi:[0,1,1]
	v_pk_fma_f32 v[76:77], v[74:75], v[88:89], v[80:81] op_sel_hi:[0,1,1]
	v_pk_fma_f32 v[66:67], v[74:75], v[66:67], v[70:71] op_sel_hi:[0,1,1]
	v_cndmask_b32_e64 v70, v78, v68, s[8:9]
	v_cndmask_b32_e64 v71, v79, v69, s[8:9]
	ds_bpermute_b32 v70, v204, v70
	ds_bpermute_b32 v71, v204, v71
	v_cndmask_b32_e64 v74, v82, v72, s[8:9]
	v_cndmask_b32_e64 v75, v83, v73, s[8:9]
	v_cndmask_b32_e64 v80, v84, v76, s[8:9]
	v_cndmask_b32_e64 v81, v85, v77, s[8:9]
	v_cndmask_b32_e64 v86, v64, v66, s[8:9]
	v_cndmask_b32_e64 v87, v65, v67, s[8:9]
	ds_bpermute_b32 v74, v204, v74
	ds_bpermute_b32 v75, v204, v75
	ds_bpermute_b32 v80, v204, v80
	ds_bpermute_b32 v81, v204, v81
	ds_bpermute_b32 v86, v204, v86
	ds_bpermute_b32 v87, v204, v87
	v_cndmask_b32_e64 v69, v69, v79, s[8:9]
	v_cndmask_b32_e64 v68, v68, v78, s[8:9]
	s_waitcnt lgkmcnt(6)
	v_pk_add_f32 v[68:69], v[68:69], v[70:71]
	v_cndmask_b32_e64 v71, v73, v83, s[8:9]
	v_cndmask_b32_e64 v70, v72, v82, s[8:9]
	v_cndmask_b32_e64 v73, v77, v85, s[8:9]
	v_cndmask_b32_e64 v72, v76, v84, s[8:9]
	v_cndmask_b32_e64 v65, v67, v65, s[8:9]
	v_cndmask_b32_e64 v64, v66, v64, s[8:9]
	s_waitcnt lgkmcnt(4)
	v_pk_add_f32 v[70:71], v[70:71], v[74:75]
	s_waitcnt lgkmcnt(2)
	v_pk_add_f32 v[72:73], v[72:73], v[80:81]
	s_waitcnt lgkmcnt(0)
	v_pk_add_f32 v[64:65], v[64:65], v[86:87]
	v_cndmask_b32_e64 v75, v73, v69, s[10:11]
	v_cndmask_b32_e64 v67, v69, v73, s[10:11]
	v_cndmask_b32_e64 v69, v70, v64, s[10:11]
	v_cndmask_b32_e64 v66, v68, v72, s[10:11]
	ds_bpermute_b32 v76, v205, v69
	v_cndmask_b32_e64 v69, v71, v65, s[10:11]
	ds_bpermute_b32 v66, v205, v66
	ds_bpermute_b32 v67, v205, v67
	ds_bpermute_b32 v77, v205, v69
	v_cndmask_b32_e64 v74, v72, v68, s[10:11]
	v_cndmask_b32_e64 v65, v65, v71, s[10:11]
	v_cndmask_b32_e64 v64, v64, v70, s[10:11]
	s_waitcnt lgkmcnt(1)
	v_pk_add_f32 v[66:67], v[74:75], v[66:67]
	s_waitcnt lgkmcnt(0)
	v_pk_add_f32 v[64:65], v[64:65], v[76:77]
	v_and_b32_e32 v89, 0xffff0000, v212
	v_cndmask_b32_e64 v68, v66, v64, s[12:13]
	v_cndmask_b32_e64 v69, v67, v65, s[12:13]
	ds_bpermute_b32 v68, v206, v68
	ds_bpermute_b32 v69, v206, v69
	v_and_b32_e32 v91, 0xffff0000, v213
	v_lshlrev_b32_e32 v88, 16, v212
	v_lshlrev_b32_e32 v90, 16, v213
	v_readlane_b32 s98, v248, s59
	v_readlane_b32 s99, v249, s59
	v_cndmask_b32_e64 v65, v65, v67, s[12:13]
	v_cndmask_b32_e64 v64, v64, v66, s[12:13]
	v_pk_fma_f32 v[66:67], v[88:89], s[74:75], v[90:91] op_sel_hi:[1,0,1]
	v_lshlrev_b64 v[92:93], 13, v[186:187]
	v_pk_add_f32 v[66:67], v[66:67], s[98:99] op_sel_hi:[1,0] neg_lo:[0,1] neg_hi:[0,1]
	v_lshl_add_u64 v[70:71], s[78:79], 0, v[92:93]
	v_pk_mul_f32 v[66:67], s[98:99], v[66:67] op_sel:[1,0]
	s_waitcnt lgkmcnt(0)
	v_pk_add_f32 v[64:65], v[64:65], v[68:69]
	ds_bpermute_b32 v64, v250, v64
	ds_bpermute_b32 v65, v250, v65
	v_pk_fma_f32 v[66:67], v[66:67], v[178:179], v[180:181]
	v_lshl_add_u64 v[70:71], v[70:71], 0, v[138:139]
	s_waitcnt lgkmcnt(0)
	v_pk_fma_f32 v[64:65], v[66:67], s[74:75], v[64:65] op_sel_hi:[1,0,1]
	s_add_i32 s16, s16, 16
	s_addk_i32 s17, 0x100
	s_add_i32 s34, s34, 0x40000
	s_and_b64 vcc, exec, s[0:1]
	s_mov_b32 s0, s61
	global_store_dwordx2 v[70:71], v[64:65], off nt
	s_cbranch_vccnz .LBB0_938
.LBB0_934:
	s_add_i32 s15, s17, 0xffffff80
	s_and_b32 s15, s15, 0x780
	v_lshl_add_u32 v76, s15, 2, v189
	ds_read_b128 v[64:67], v76
	s_add_i32 s14, s34, 0xfffc0000
	s_add_i32 s1, s0, 1
	s_and_b32 s14, s14, 0x1e00000
	s_add_u32 s14, s38, s14
	s_waitcnt lgkmcnt(0)
	v_lshlrev_b32_e32 v65, 7, v65
	v_lshlrev_b32_e32 v64, 7, v64
	s_addc_u32 s15, s39, 0
	ds_read_b128 v[68:71], v76 offset:16
	ds_read_b128 v[72:75], v76 offset:32
	ds_read_b128 v[128:131], v76 offset:48
	v_or_b32_e32 v65, v65, v137
	v_or_b32_e32 v64, v64, v174
	global_load_dwordx4 v[124:127], v64, s[14:15]
	global_load_dwordx4 v[120:123], v65, s[14:15]
	v_lshlrev_b32_e32 v64, 7, v67
	v_lshlrev_b32_e32 v65, 7, v66
	v_or_b32_e32 v64, v64, v137
	v_or_b32_e32 v65, v65, v174
	global_load_dwordx4 v[116:119], v65, s[14:15]
	global_load_dwordx4 v[112:115], v64, s[14:15]
	s_waitcnt lgkmcnt(2)
	v_lshlrev_b32_e32 v64, 7, v69
	v_lshlrev_b32_e32 v65, 7, v68
	v_or_b32_e32 v64, v64, v137
	v_or_b32_e32 v65, v65, v174
	global_load_dwordx4 v[108:111], v65, s[14:15]
	global_load_dwordx4 v[104:107], v64, s[14:15]
	v_lshlrev_b32_e32 v64, 7, v71
	v_lshlrev_b32_e32 v65, 7, v70
	v_or_b32_e32 v64, v64, v137
	v_or_b32_e32 v65, v65, v174
	global_load_dwordx4 v[100:103], v65, s[14:15]
	global_load_dwordx4 v[96:99], v64, s[14:15]
	s_waitcnt lgkmcnt(1)
	v_lshlrev_b32_e32 v64, 7, v73
	v_lshlrev_b32_e32 v65, 7, v72
	v_or_b32_e32 v64, v64, v137
	v_or_b32_e32 v65, v65, v174
	global_load_dwordx4 v[92:95], v65, s[14:15]
	global_load_dwordx4 v[88:91], v64, s[14:15]
	v_lshlrev_b32_e32 v64, 7, v75
	v_lshlrev_b32_e32 v65, 7, v74
	s_and_b32 s59, s1, 15
	v_or_b32_e32 v64, v64, v137
	v_or_b32_e32 v65, v65, v174
	s_add_i32 s1, s16, -16
	v_or_b32_e32 v186, s59, v176
	global_load_dwordx4 v[84:87], v65, s[14:15]
	global_load_dwordx4 v[80:83], v64, s[14:15]
	s_waitcnt lgkmcnt(0)
	v_lshlrev_b32_e32 v64, 7, v129
	v_lshlrev_b32_e32 v65, 7, v128
	s_and_b32 s1, s1, 0x780
	v_ashrrev_i32_e32 v187, 31, v186
	v_or_b32_e32 v64, v64, v137
	v_or_b32_e32 v65, v65, v174
	v_or_b32_e32 v214, s1, v192
	v_lshlrev_b64 v[128:129], 12, v[186:187]
	global_load_dwordx4 v[76:79], v65, s[14:15]
	global_load_dwordx4 v[72:75], v64, s[14:15]
	v_lshlrev_b32_e32 v64, 7, v131
	v_lshlrev_b32_e32 v65, 7, v130
	v_lshl_add_u64 v[130:131], s[80:81], 0, v[128:129]
	v_lshlrev_b32_e32 v138, 1, v214
	v_lshl_add_u64 v[128:129], s[28:29], 0, v[128:129]
	v_or_b32_e32 v64, v64, v137
	v_or_b32_e32 v65, v65, v174
	v_lshl_add_u64 v[130:131], v[130:131], 0, v[138:139]
	v_lshl_add_u64 v[128:129], v[128:129], 0, v[138:139]
	s_and_b32 s1, s0, 14
	s_waitcnt vmcnt(32)
	v_cvt_pk_f32_fp8_e32 v[224:225], v0
	v_cvt_pk_f32_fp8_sdwa v[226:227], v0 src0_sel:WORD_1
	v_cvt_pk_f32_fp8_e32 v[228:229], v1
	v_cvt_pk_f32_fp8_sdwa v[230:231], v1 src0_sel:WORD_1
	global_load_dwordx4 v[68:71], v65, s[14:15]
	s_nop 0
	global_load_dwordx4 v[64:67], v64, s[14:15]
	global_load_dword v212, v[130:131], off nt
	global_load_dword v213, v[128:129], off nt
	v_lshl_add_u32 v128, s1, 9, v193
	s_waitcnt vmcnt(35)
	v_cvt_pk_f32_fp8_e32 v[240:241], v4
	v_cvt_pk_f32_fp8_sdwa v[242:243], v4 src0_sel:WORD_1
	v_cvt_pk_f32_fp8_e32 v[244:245], v5
	v_cvt_pk_f32_fp8_sdwa v[246:247], v5 src0_sel:WORD_1
	ds_read_b128 v[216:219], v128
	ds_read_b128 v[220:223], v128 offset:16
	ds_read_b128 v[132:135], v128 offset:32
	ds_read_b128 v[128:131], v128 offset:48
	v_cvt_pk_f32_fp8_e32 v[232:233], v2
	s_waitcnt lgkmcnt(3)
	v_pk_fma_f32 v[224:225], v[216:217], v[224:225], 0 op_sel_hi:[0,1,0]
	v_pk_fma_f32 v[226:227], v[216:217], v[226:227], 0 op_sel_hi:[0,1,0]
	v_pk_fma_f32 v[228:229], v[216:217], v[228:229], 0 op_sel_hi:[0,1,0]
	v_pk_fma_f32 v[230:231], v[216:217], v[230:231], 0 op_sel_hi:[0,1,0]
	v_cvt_pk_f32_fp8_sdwa v[234:235], v2 src0_sel:WORD_1
	v_cvt_pk_f32_fp8_e32 v[236:237], v3
	v_cvt_pk_f32_fp8_sdwa v[238:239], v3 src0_sel:WORD_1
	v_pk_fma_f32 v[224:225], v[216:217], v[240:241], v[224:225] op_sel:[1,0,0]
	v_pk_fma_f32 v[226:227], v[216:217], v[242:243], v[226:227] op_sel:[1,0,0]
	v_pk_fma_f32 v[228:229], v[216:217], v[244:245], v[228:229] op_sel:[1,0,0]
	v_pk_fma_f32 v[230:231], v[216:217], v[246:247], v[230:231] op_sel:[1,0,0]
	v_cvt_pk_f32_fp8_e32 v[240:241], v6
	v_cvt_pk_f32_fp8_sdwa v[242:243], v6 src0_sel:WORD_1
	v_cvt_pk_f32_fp8_e32 v[244:245], v7
	v_cvt_pk_f32_fp8_sdwa v[246:247], v7 src0_sel:WORD_1
	v_pk_fma_f32 v[232:233], v[216:217], v[232:233], 0 op_sel_hi:[0,1,0]
	v_pk_fma_f32 v[234:235], v[216:217], v[234:235], 0 op_sel_hi:[0,1,0]
	v_pk_fma_f32 v[236:237], v[216:217], v[236:237], 0 op_sel_hi:[0,1,0]
	v_pk_fma_f32 v[238:239], v[216:217], v[238:239], 0 op_sel_hi:[0,1,0]
	v_pk_fma_f32 v[232:233], v[216:217], v[240:241], v[232:233] op_sel:[1,0,0]
	v_pk_fma_f32 v[234:235], v[216:217], v[242:243], v[234:235] op_sel:[1,0,0]
	v_pk_fma_f32 v[236:237], v[216:217], v[244:245], v[236:237] op_sel:[1,0,0]
	v_pk_fma_f32 v[216:217], v[216:217], v[246:247], v[238:239] op_sel:[1,0,0]
	s_waitcnt vmcnt(34)
	v_cvt_pk_f32_fp8_e32 v[238:239], v8
	v_cvt_pk_f32_fp8_sdwa v[240:241], v8 src0_sel:WORD_1
	v_cvt_pk_f32_fp8_e32 v[242:243], v9
	v_cvt_pk_f32_fp8_sdwa v[244:245], v9 src0_sel:WORD_1
	v_pk_fma_f32 v[224:225], v[218:219], v[238:239], v[224:225] op_sel_hi:[0,1,1]
	v_pk_fma_f32 v[226:227], v[218:219], v[240:241], v[226:227] op_sel_hi:[0,1,1]
	v_pk_fma_f32 v[228:229], v[218:219], v[242:243], v[228:229] op_sel_hi:[0,1,1]
	v_pk_fma_f32 v[230:231], v[218:219], v[244:245], v[230:231] op_sel_hi:[0,1,1]
	v_cvt_pk_f32_fp8_e32 v[238:239], v10
	v_cvt_pk_f32_fp8_sdwa v[240:241], v10 src0_sel:WORD_1
	v_cvt_pk_f32_fp8_e32 v[242:243], v11
	v_cvt_pk_f32_fp8_sdwa v[244:245], v11 src0_sel:WORD_1
	v_pk_fma_f32 v[232:233], v[218:219], v[238:239], v[232:233] op_sel_hi:[0,1,1]
	v_pk_fma_f32 v[234:235], v[218:219], v[240:241], v[234:235] op_sel_hi:[0,1,1]
	v_pk_fma_f32 v[236:237], v[218:219], v[242:243], v[236:237] op_sel_hi:[0,1,1]
	v_pk_fma_f32 v[216:217], v[218:219], v[244:245], v[216:217] op_sel_hi:[0,1,1]
	v_mov_b32_e32 v138, v219
	s_waitcnt vmcnt(33)
	v_cvt_pk_f32_fp8_e32 v[218:219], v12
	v_cvt_pk_f32_fp8_sdwa v[238:239], v12 src0_sel:WORD_1
	v_cvt_pk_f32_fp8_e32 v[240:241], v13
	v_cvt_pk_f32_fp8_sdwa v[242:243], v13 src0_sel:WORD_1
	v_pk_fma_f32 v[218:219], v[138:139], v[218:219], v[224:225] op_sel_hi:[0,1,1]
	v_pk_fma_f32 v[224:225], v[138:139], v[238:239], v[226:227] op_sel_hi:[0,1,1]
	v_pk_fma_f32 v[226:227], v[138:139], v[240:241], v[228:229] op_sel_hi:[0,1,1]
	v_pk_fma_f32 v[228:229], v[138:139], v[242:243], v[230:231] op_sel_hi:[0,1,1]
	v_cvt_pk_f32_fp8_e32 v[230:231], v14
	v_cvt_pk_f32_fp8_sdwa v[238:239], v14 src0_sel:WORD_1
	v_cvt_pk_f32_fp8_e32 v[240:241], v15
	v_cvt_pk_f32_fp8_sdwa v[242:243], v15 src0_sel:WORD_1
	v_pk_fma_f32 v[230:231], v[138:139], v[230:231], v[232:233] op_sel_hi:[0,1,1]
	v_pk_fma_f32 v[232:233], v[138:139], v[238:239], v[234:235] op_sel_hi:[0,1,1]
	v_pk_fma_f32 v[234:235], v[138:139], v[240:241], v[236:237] op_sel_hi:[0,1,1]
	v_pk_fma_f32 v[216:217], v[138:139], v[242:243], v[216:217] op_sel_hi:[0,1,1]
	s_waitcnt vmcnt(32)
	v_cvt_pk_f32_fp8_e32 v[236:237], v16
	v_cvt_pk_f32_fp8_sdwa v[238:239], v16 src0_sel:WORD_1
	v_cvt_pk_f32_fp8_e32 v[240:241], v17
	v_cvt_pk_f32_fp8_sdwa v[242:243], v17 src0_sel:WORD_1
	s_waitcnt lgkmcnt(2)
	v_pk_fma_f32 v[218:219], v[220:221], v[236:237], v[218:219] op_sel_hi:[0,1,1]
	v_pk_fma_f32 v[224:225], v[220:221], v[238:239], v[224:225] op_sel_hi:[0,1,1]
	v_pk_fma_f32 v[226:227], v[220:221], v[240:241], v[226:227] op_sel_hi:[0,1,1]
	v_pk_fma_f32 v[228:229], v[220:221], v[242:243], v[228:229] op_sel_hi:[0,1,1]
	v_cvt_pk_f32_fp8_e32 v[236:237], v18
	v_cvt_pk_f32_fp8_sdwa v[238:239], v18 src0_sel:WORD_1
	v_cvt_pk_f32_fp8_e32 v[240:241], v19
	v_cvt_pk_f32_fp8_sdwa v[242:243], v19 src0_sel:WORD_1
	v_pk_fma_f32 v[230:231], v[220:221], v[236:237], v[230:231] op_sel_hi:[0,1,1]
	v_pk_fma_f32 v[232:233], v[220:221], v[238:239], v[232:233] op_sel_hi:[0,1,1]
	v_pk_fma_f32 v[234:235], v[220:221], v[240:241], v[234:235] op_sel_hi:[0,1,1]
	v_pk_fma_f32 v[216:217], v[220:221], v[242:243], v[216:217] op_sel_hi:[0,1,1]
	s_waitcnt vmcnt(31)
	v_cvt_pk_f32_fp8_e32 v[236:237], v20
	v_cvt_pk_f32_fp8_sdwa v[238:239], v20 src0_sel:WORD_1
	v_cvt_pk_f32_fp8_e32 v[240:241], v21
	v_cvt_pk_f32_fp8_sdwa v[242:243], v21 src0_sel:WORD_1
	v_pk_fma_f32 v[218:219], v[220:221], v[236:237], v[218:219] op_sel:[1,0,0]
	v_pk_fma_f32 v[224:225], v[220:221], v[238:239], v[224:225] op_sel:[1,0,0]
	v_pk_fma_f32 v[226:227], v[220:221], v[240:241], v[226:227] op_sel:[1,0,0]
	v_pk_fma_f32 v[228:229], v[220:221], v[242:243], v[228:229] op_sel:[1,0,0]
	v_cvt_pk_f32_fp8_e32 v[236:237], v22
	v_cvt_pk_f32_fp8_sdwa v[238:239], v22 src0_sel:WORD_1
	v_cvt_pk_f32_fp8_e32 v[240:241], v23
	v_cvt_pk_f32_fp8_sdwa v[242:243], v23 src0_sel:WORD_1
	v_pk_fma_f32 v[230:231], v[220:221], v[236:237], v[230:231] op_sel:[1,0,0]
	v_pk_fma_f32 v[232:233], v[220:221], v[238:239], v[232:233] op_sel:[1,0,0]
	v_pk_fma_f32 v[234:235], v[220:221], v[240:241], v[234:235] op_sel:[1,0,0]
	v_pk_fma_f32 v[216:217], v[220:221], v[242:243], v[216:217] op_sel:[1,0,0]
	s_waitcnt vmcnt(30)
	v_cvt_pk_f32_fp8_e32 v[220:221], v24
	v_cvt_pk_f32_fp8_sdwa v[236:237], v24 src0_sel:WORD_1
	v_cvt_pk_f32_fp8_e32 v[238:239], v25
	v_cvt_pk_f32_fp8_sdwa v[240:241], v25 src0_sel:WORD_1
	v_pk_fma_f32 v[218:219], v[222:223], v[220:221], v[218:219] op_sel_hi:[0,1,1]
	v_pk_fma_f32 v[220:221], v[222:223], v[236:237], v[224:225] op_sel_hi:[0,1,1]
	v_pk_fma_f32 v[224:225], v[222:223], v[238:239], v[226:227] op_sel_hi:[0,1,1]
	v_pk_fma_f32 v[226:227], v[222:223], v[240:241], v[228:229] op_sel_hi:[0,1,1]
	v_cvt_pk_f32_fp8_e32 v[228:229], v26
	v_cvt_pk_f32_fp8_sdwa v[236:237], v26 src0_sel:WORD_1
	v_cvt_pk_f32_fp8_e32 v[238:239], v27
	v_cvt_pk_f32_fp8_sdwa v[240:241], v27 src0_sel:WORD_1
	v_pk_fma_f32 v[228:229], v[222:223], v[228:229], v[230:231] op_sel_hi:[0,1,1]
	v_pk_fma_f32 v[230:231], v[222:223], v[236:237], v[232:233] op_sel_hi:[0,1,1]
	v_pk_fma_f32 v[232:233], v[222:223], v[238:239], v[234:235] op_sel_hi:[0,1,1]
	v_pk_fma_f32 v[216:217], v[222:223], v[240:241], v[216:217] op_sel_hi:[0,1,1]
	v_mov_b32_e32 v138, v223
	s_waitcnt vmcnt(29)
	v_cvt_pk_f32_fp8_e32 v[222:223], v28
	v_cvt_pk_f32_fp8_sdwa v[234:235], v28 src0_sel:WORD_1
	v_cvt_pk_f32_fp8_e32 v[236:237], v29
	v_cvt_pk_f32_fp8_sdwa v[238:239], v29 src0_sel:WORD_1
	v_pk_fma_f32 v[218:219], v[138:139], v[222:223], v[218:219] op_sel_hi:[0,1,1]
	v_pk_fma_f32 v[220:221], v[138:139], v[234:235], v[220:221] op_sel_hi:[0,1,1]
	v_pk_fma_f32 v[222:223], v[138:139], v[236:237], v[224:225] op_sel_hi:[0,1,1]
	v_pk_fma_f32 v[224:225], v[138:139], v[238:239], v[226:227] op_sel_hi:[0,1,1]
	v_cvt_pk_f32_fp8_e32 v[226:227], v30
	v_cvt_pk_f32_fp8_sdwa v[234:235], v30 src0_sel:WORD_1
	v_cvt_pk_f32_fp8_e32 v[236:237], v31
	v_cvt_pk_f32_fp8_sdwa v[238:239], v31 src0_sel:WORD_1
	v_pk_fma_f32 v[226:227], v[138:139], v[226:227], v[228:229] op_sel_hi:[0,1,1]
	v_pk_fma_f32 v[228:229], v[138:139], v[234:235], v[230:231] op_sel_hi:[0,1,1]
	v_pk_fma_f32 v[230:231], v[138:139], v[236:237], v[232:233] op_sel_hi:[0,1,1]
	v_pk_fma_f32 v[216:217], v[138:139], v[238:239], v[216:217] op_sel_hi:[0,1,1]
	s_waitcnt vmcnt(28)
	v_cvt_pk_f32_fp8_e32 v[232:233], v32
	v_cvt_pk_f32_fp8_sdwa v[234:235], v32 src0_sel:WORD_1
	v_cvt_pk_f32_fp8_e32 v[236:237], v33
	v_cvt_pk_f32_fp8_sdwa v[238:239], v33 src0_sel:WORD_1
	s_waitcnt lgkmcnt(1)
	v_pk_fma_f32 v[218:219], v[132:133], v[232:233], v[218:219] op_sel_hi:[0,1,1]
	v_pk_fma_f32 v[220:221], v[132:133], v[234:235], v[220:221] op_sel_hi:[0,1,1]
	v_pk_fma_f32 v[222:223], v[132:133], v[236:237], v[222:223] op_sel_hi:[0,1,1]
	v_pk_fma_f32 v[224:225], v[132:133], v[238:239], v[224:225] op_sel_hi:[0,1,1]
	v_cvt_pk_f32_fp8_e32 v[232:233], v34
	v_cvt_pk_f32_fp8_sdwa v[234:235], v34 src0_sel:WORD_1
	v_cvt_pk_f32_fp8_e32 v[236:237], v35
	v_cvt_pk_f32_fp8_sdwa v[238:239], v35 src0_sel:WORD_1
	v_pk_fma_f32 v[226:227], v[132:133], v[232:233], v[226:227] op_sel_hi:[0,1,1]
	v_pk_fma_f32 v[228:229], v[132:133], v[234:235], v[228:229] op_sel_hi:[0,1,1]
	v_pk_fma_f32 v[230:231], v[132:133], v[236:237], v[230:231] op_sel_hi:[0,1,1]
	v_pk_fma_f32 v[216:217], v[132:133], v[238:239], v[216:217] op_sel_hi:[0,1,1]
	s_waitcnt vmcnt(27)
	v_cvt_pk_f32_fp8_e32 v[232:233], v36
	v_cvt_pk_f32_fp8_sdwa v[234:235], v36 src0_sel:WORD_1
	v_cvt_pk_f32_fp8_e32 v[236:237], v37
	v_cvt_pk_f32_fp8_sdwa v[238:239], v37 src0_sel:WORD_1
	v_pk_fma_f32 v[218:219], v[132:133], v[232:233], v[218:219] op_sel:[1,0,0]
	v_pk_fma_f32 v[220:221], v[132:133], v[234:235], v[220:221] op_sel:[1,0,0]
	v_pk_fma_f32 v[222:223], v[132:133], v[236:237], v[222:223] op_sel:[1,0,0]
	v_pk_fma_f32 v[224:225], v[132:133], v[238:239], v[224:225] op_sel:[1,0,0]
	v_cvt_pk_f32_fp8_e32 v[232:233], v38
	v_cvt_pk_f32_fp8_sdwa v[234:235], v38 src0_sel:WORD_1
	v_cvt_pk_f32_fp8_e32 v[236:237], v39
	v_cvt_pk_f32_fp8_sdwa v[238:239], v39 src0_sel:WORD_1
	v_pk_fma_f32 v[226:227], v[132:133], v[232:233], v[226:227] op_sel:[1,0,0]
	v_pk_fma_f32 v[228:229], v[132:133], v[234:235], v[228:229] op_sel:[1,0,0]
	v_pk_fma_f32 v[230:231], v[132:133], v[236:237], v[230:231] op_sel:[1,0,0]
	v_pk_fma_f32 v[132:133], v[132:133], v[238:239], v[216:217] op_sel:[1,0,0]
	s_waitcnt vmcnt(26)
	v_cvt_pk_f32_fp8_e32 v[216:217], v40
	v_cvt_pk_f32_fp8_sdwa v[232:233], v40 src0_sel:WORD_1
	v_cvt_pk_f32_fp8_e32 v[234:235], v41
	v_cvt_pk_f32_fp8_sdwa v[236:237], v41 src0_sel:WORD_1
	v_pk_fma_f32 v[216:217], v[134:135], v[216:217], v[218:219] op_sel_hi:[0,1,1]
	v_pk_fma_f32 v[218:219], v[134:135], v[232:233], v[220:221] op_sel_hi:[0,1,1]
	v_pk_fma_f32 v[220:221], v[134:135], v[234:235], v[222:223] op_sel_hi:[0,1,1]
	v_pk_fma_f32 v[222:223], v[134:135], v[236:237], v[224:225] op_sel_hi:[0,1,1]
	v_cvt_pk_f32_fp8_e32 v[224:225], v42
	v_cvt_pk_f32_fp8_sdwa v[232:233], v42 src0_sel:WORD_1
	v_cvt_pk_f32_fp8_e32 v[234:235], v43
	v_cvt_pk_f32_fp8_sdwa v[236:237], v43 src0_sel:WORD_1
	v_pk_fma_f32 v[224:225], v[134:135], v[224:225], v[226:227] op_sel_hi:[0,1,1]
	v_pk_fma_f32 v[226:227], v[134:135], v[232:233], v[228:229] op_sel_hi:[0,1,1]
	v_pk_fma_f32 v[228:229], v[134:135], v[234:235], v[230:231] op_sel_hi:[0,1,1]
	v_pk_fma_f32 v[132:133], v[134:135], v[236:237], v[132:133] op_sel_hi:[0,1,1]
	s_waitcnt vmcnt(25)
	v_cvt_pk_f32_fp8_e32 v[230:231], v44
	v_cvt_pk_f32_fp8_sdwa v[232:233], v44 src0_sel:WORD_1
	v_cvt_pk_f32_fp8_e32 v[234:235], v45
	v_cvt_pk_f32_fp8_sdwa v[236:237], v45 src0_sel:WORD_1
	v_mov_b32_e32 v134, v135
	v_pk_fma_f32 v[216:217], v[134:135], v[230:231], v[216:217] op_sel_hi:[0,1,1]
	v_pk_fma_f32 v[218:219], v[134:135], v[232:233], v[218:219] op_sel_hi:[0,1,1]
	v_pk_fma_f32 v[220:221], v[134:135], v[234:235], v[220:221] op_sel_hi:[0,1,1]
	v_pk_fma_f32 v[222:223], v[134:135], v[236:237], v[222:223] op_sel_hi:[0,1,1]
	v_cvt_pk_f32_fp8_e32 v[230:231], v46
	v_cvt_pk_f32_fp8_sdwa v[232:233], v46 src0_sel:WORD_1
	v_cvt_pk_f32_fp8_e32 v[234:235], v47
	v_cvt_pk_f32_fp8_sdwa v[236:237], v47 src0_sel:WORD_1
	v_pk_fma_f32 v[224:225], v[134:135], v[230:231], v[224:225] op_sel_hi:[0,1,1]
	v_pk_fma_f32 v[226:227], v[134:135], v[232:233], v[226:227] op_sel_hi:[0,1,1]
	v_pk_fma_f32 v[228:229], v[134:135], v[234:235], v[228:229] op_sel_hi:[0,1,1]
	v_pk_fma_f32 v[132:133], v[134:135], v[236:237], v[132:133] op_sel_hi:[0,1,1]
	s_waitcnt vmcnt(24)
	v_cvt_pk_f32_fp8_e32 v[134:135], v48
	v_cvt_pk_f32_fp8_sdwa v[230:231], v48 src0_sel:WORD_1
	v_cvt_pk_f32_fp8_e32 v[232:233], v49
	v_cvt_pk_f32_fp8_sdwa v[234:235], v49 src0_sel:WORD_1
	s_waitcnt lgkmcnt(0)
	v_pk_fma_f32 v[134:135], v[128:129], v[134:135], v[216:217] op_sel_hi:[0,1,1]
	v_pk_fma_f32 v[216:217], v[128:129], v[230:231], v[218:219] op_sel_hi:[0,1,1]
	v_pk_fma_f32 v[218:219], v[128:129], v[232:233], v[220:221] op_sel_hi:[0,1,1]
	v_pk_fma_f32 v[220:221], v[128:129], v[234:235], v[222:223] op_sel_hi:[0,1,1]
	v_cvt_pk_f32_fp8_e32 v[222:223], v50
	v_cvt_pk_f32_fp8_sdwa v[230:231], v50 src0_sel:WORD_1
	v_cvt_pk_f32_fp8_e32 v[232:233], v51
	v_cvt_pk_f32_fp8_sdwa v[234:235], v51 src0_sel:WORD_1
	v_pk_fma_f32 v[222:223], v[128:129], v[222:223], v[224:225] op_sel_hi:[0,1,1]
	v_pk_fma_f32 v[224:225], v[128:129], v[230:231], v[226:227] op_sel_hi:[0,1,1]
	v_pk_fma_f32 v[226:227], v[128:129], v[232:233], v[228:229] op_sel_hi:[0,1,1]
	v_pk_fma_f32 v[132:133], v[128:129], v[234:235], v[132:133] op_sel_hi:[0,1,1]
	s_waitcnt vmcnt(23)
	v_cvt_pk_f32_fp8_e32 v[228:229], v52
	v_cvt_pk_f32_fp8_sdwa v[230:231], v52 src0_sel:WORD_1
	v_cvt_pk_f32_fp8_e32 v[232:233], v53
	v_cvt_pk_f32_fp8_sdwa v[234:235], v53 src0_sel:WORD_1
	v_pk_fma_f32 v[134:135], v[128:129], v[228:229], v[134:135] op_sel:[1,0,0]
	v_pk_fma_f32 v[216:217], v[128:129], v[230:231], v[216:217] op_sel:[1,0,0]
	v_pk_fma_f32 v[218:219], v[128:129], v[232:233], v[218:219] op_sel:[1,0,0]
	v_pk_fma_f32 v[220:221], v[128:129], v[234:235], v[220:221] op_sel:[1,0,0]
	v_cvt_pk_f32_fp8_e32 v[228:229], v54
	v_cvt_pk_f32_fp8_sdwa v[230:231], v54 src0_sel:WORD_1
	v_cvt_pk_f32_fp8_e32 v[232:233], v55
	v_cvt_pk_f32_fp8_sdwa v[234:235], v55 src0_sel:WORD_1
	v_pk_fma_f32 v[222:223], v[128:129], v[228:229], v[222:223] op_sel:[1,0,0]
	v_pk_fma_f32 v[224:225], v[128:129], v[230:231], v[224:225] op_sel:[1,0,0]
	v_pk_fma_f32 v[226:227], v[128:129], v[232:233], v[226:227] op_sel:[1,0,0]
	v_pk_fma_f32 v[128:129], v[128:129], v[234:235], v[132:133] op_sel:[1,0,0]
	s_waitcnt vmcnt(22)
	v_cvt_pk_f32_fp8_e32 v[132:133], v56
	v_cvt_pk_f32_fp8_sdwa v[228:229], v56 src0_sel:WORD_1
	v_cvt_pk_f32_fp8_e32 v[230:231], v57
	v_cvt_pk_f32_fp8_sdwa v[232:233], v57 src0_sel:WORD_1
	v_pk_fma_f32 v[132:133], v[130:131], v[132:133], v[134:135] op_sel_hi:[0,1,1]
	v_pk_fma_f32 v[134:135], v[130:131], v[228:229], v[216:217] op_sel_hi:[0,1,1]
	v_pk_fma_f32 v[216:217], v[130:131], v[230:231], v[218:219] op_sel_hi:[0,1,1]
	v_pk_fma_f32 v[218:219], v[130:131], v[232:233], v[220:221] op_sel_hi:[0,1,1]
	v_cvt_pk_f32_fp8_e32 v[220:221], v58
	v_cvt_pk_f32_fp8_sdwa v[228:229], v58 src0_sel:WORD_1
	v_cvt_pk_f32_fp8_e32 v[230:231], v59
	v_cvt_pk_f32_fp8_sdwa v[232:233], v59 src0_sel:WORD_1
	v_pk_fma_f32 v[220:221], v[130:131], v[220:221], v[222:223] op_sel_hi:[0,1,1]
	v_pk_fma_f32 v[222:223], v[130:131], v[228:229], v[224:225] op_sel_hi:[0,1,1]
	s_waitcnt vmcnt(21)
	v_cvt_pk_f32_fp8_sdwa v[228:229], v60 src0_sel:WORD_1
	v_pk_fma_f32 v[224:225], v[130:131], v[230:231], v[226:227] op_sel_hi:[0,1,1]
	v_cvt_pk_f32_fp8_e32 v[226:227], v60
	v_cvt_pk_f32_fp8_e32 v[230:231], v61
	v_pk_fma_f32 v[128:129], v[130:131], v[232:233], v[128:129] op_sel_hi:[0,1,1]
	v_mov_b32_e32 v130, v131
	v_cvt_pk_f32_fp8_sdwa v[232:233], v61 src0_sel:WORD_1
	v_pk_fma_f32 v[134:135], v[130:131], v[228:229], v[134:135] op_sel_hi:[0,1,1]
	v_cvt_pk_f32_fp8_sdwa v[228:229], v62 src0_sel:WORD_1
	v_pk_fma_f32 v[132:133], v[130:131], v[226:227], v[132:133] op_sel_hi:[0,1,1]
	v_pk_fma_f32 v[216:217], v[130:131], v[230:231], v[216:217] op_sel_hi:[0,1,1]
	v_cvt_pk_f32_fp8_e32 v[226:227], v62
	v_cvt_pk_f32_fp8_e32 v[230:231], v63
	v_pk_fma_f32 v[218:219], v[130:131], v[232:233], v[218:219] op_sel_hi:[0,1,1]
	v_cvt_pk_f32_fp8_sdwa v[232:233], v63 src0_sel:WORD_1
	v_pk_fma_f32 v[222:223], v[130:131], v[228:229], v[222:223] op_sel_hi:[0,1,1]
	v_cndmask_b32_e64 v138, v134, v222, s[8:9]
	v_pk_fma_f32 v[220:221], v[130:131], v[226:227], v[220:221] op_sel_hi:[0,1,1]
	v_pk_fma_f32 v[224:225], v[130:131], v[230:231], v[224:225] op_sel_hi:[0,1,1]
	ds_bpermute_b32 v226, v204, v138
	v_cndmask_b32_e64 v138, v135, v223, s[8:9]
	ds_bpermute_b32 v227, v204, v138
	v_cndmask_b32_e64 v138, v216, v224, s[8:9]
	v_pk_fma_f32 v[128:129], v[130:131], v[232:233], v[128:129] op_sel_hi:[0,1,1]
	v_cndmask_b32_e64 v130, v132, v220, s[8:9]
	v_cndmask_b32_e64 v131, v133, v221, s[8:9]
	ds_bpermute_b32 v228, v204, v138
	v_cndmask_b32_e64 v138, v217, v225, s[8:9]
	ds_bpermute_b32 v130, v204, v130
	ds_bpermute_b32 v131, v204, v131
	ds_bpermute_b32 v229, v204, v138
	v_cndmask_b32_e64 v138, v218, v128, s[8:9]
	ds_bpermute_b32 v230, v204, v138
	v_cndmask_b32_e64 v138, v219, v129, s[8:9]
	ds_bpermute_b32 v231, v204, v138
	v_cndmask_b32_e64 v133, v221, v133, s[8:9]
	v_cndmask_b32_e64 v132, v220, v132, s[8:9]
	s_waitcnt lgkmcnt(3)
	v_pk_add_f32 v[130:131], v[132:133], v[130:131]
	v_cndmask_b32_e64 v133, v223, v135, s[8:9]
	v_cndmask_b32_e64 v132, v222, v134, s[8:9]
	v_cndmask_b32_e64 v135, v225, v217, s[8:9]
	v_cndmask_b32_e64 v134, v224, v216, s[8:9]
	s_waitcnt lgkmcnt(2)
	v_pk_add_f32 v[134:135], v[134:135], v[228:229]
	v_cndmask_b32_e64 v129, v129, v219, s[8:9]
	v_cndmask_b32_e64 v128, v128, v218, s[8:9]
	v_pk_add_f32 v[132:133], v[132:133], v[226:227]
	s_waitcnt lgkmcnt(0)
	v_pk_add_f32 v[128:129], v[128:129], v[230:231]
	v_cndmask_b32_e64 v219, v135, v131, s[10:11]
	v_cndmask_b32_e64 v131, v131, v135, s[10:11]
	ds_bpermute_b32 v217, v205, v131
	v_cndmask_b32_e64 v131, v132, v128, s[10:11]
	v_cndmask_b32_e64 v138, v130, v134, s[10:11]
	ds_bpermute_b32 v220, v205, v131
	v_cndmask_b32_e64 v131, v133, v129, s[10:11]
	ds_bpermute_b32 v216, v205, v138
	ds_bpermute_b32 v221, v205, v131
	v_cndmask_b32_e64 v218, v134, v130, s[10:11]
	v_cndmask_b32_e64 v129, v129, v133, s[10:11]
	v_cndmask_b32_e64 v128, v128, v132, s[10:11]
	s_waitcnt lgkmcnt(1)
	v_pk_add_f32 v[130:131], v[218:219], v[216:217]
	s_waitcnt lgkmcnt(0)
	v_pk_add_f32 v[132:133], v[128:129], v[220:221]
	s_cmp_lg_u32 s1, 0
	v_cndmask_b32_e64 v128, v130, v132, s[12:13]
	v_cndmask_b32_e64 v129, v131, v133, s[12:13]
	ds_bpermute_b32 v128, v206, v128
	ds_bpermute_b32 v129, v206, v129
	v_lshlrev_b32_e32 v138, 2, v214
	s_cbranch_scc1 .LBB0_936
	global_load_dwordx2 v[178:179], v138, s[46:47]
	global_load_dwordx2 v[180:181], v138, s[48:49]
.LBB0_936:
	v_cndmask_b32_e64 v131, v133, v131, s[12:13]
	v_cndmask_b32_e64 v130, v132, v130, s[12:13]
	s_waitcnt vmcnt(20)
	v_lshlrev_b32_e32 v132, 16, v210
	v_and_b32_e32 v133, 0xffff0000, v210
	s_waitcnt vmcnt(19)
	v_lshlrev_b32_e32 v134, 16, v211
	v_and_b32_e32 v135, 0xffff0000, v211
	v_readlane_b32 s98, v248, s1
	v_readlane_b32 s99, v249, s1
	v_or_b32_e32 v214, s1, v176
	s_waitcnt lgkmcnt(0)
	v_pk_add_f32 v[128:129], v[130:131], v[128:129]
	ds_bpermute_b32 v128, v250, v128
	ds_bpermute_b32 v129, v250, v129
	v_pk_fma_f32 v[130:131], v[132:133], s[74:75], v[134:135] op_sel_hi:[1,0,1]
	v_ashrrev_i32_e32 v215, 31, v214
	v_pk_add_f32 v[130:131], v[130:131], s[98:99] op_sel_hi:[1,0] neg_lo:[0,1] neg_hi:[0,1]
	s_add_i32 s61, s0, 2
	v_lshlrev_b64 v[214:215], 13, v[214:215]
	v_pk_mul_f32 v[130:131], s[98:99], v[130:131] op_sel:[1,0]
	s_cmpk_gt_u32 s0, 0xfd
	v_lshl_add_u64 v[214:215], s[78:79], 0, v[214:215]
	s_waitcnt vmcnt(0)
	v_pk_fma_f32 v[130:131], v[130:131], v[178:179], v[180:181]
	s_cselect_b64 s[0:1], -1, 0
	v_lshl_add_u64 v[214:215], v[214:215], 0, v[138:139]
	s_waitcnt lgkmcnt(0)
	v_pk_fma_f32 v[128:129], v[130:131], s[74:75], v[128:129] op_sel_hi:[1,0,1]
	s_and_b64 vcc, exec, s[0:1]
	global_store_dwordx2 v[214:215], v[128:129], off nt
	s_cbranch_vccnz .LBB0_933
	s_and_b32 s15, s17, 0x700
	v_lshl_add_u32 v0, s15, 2, v189
	ds_read_b128 v[6:9], v0
	ds_read_b128 v[22:25], v0 offset:16
	ds_read_b128 v[38:41], v0 offset:32
	ds_read_b128 v[54:57], v0 offset:48
	s_and_b32 s14, s34, 0x3e00000
	s_add_u32 s14, s38, s14
	s_waitcnt lgkmcnt(2)
	v_lshlrev_b32_e32 v16, 7, v23
	v_lshlrev_b32_e32 v0, 7, v7
	v_lshlrev_b32_e32 v1, 7, v6
	v_lshlrev_b32_e32 v9, 7, v9
	v_lshlrev_b32_e32 v8, 7, v8
	v_lshlrev_b32_e32 v17, 7, v22
	v_lshlrev_b32_e32 v25, 7, v25
	v_lshlrev_b32_e32 v24, 7, v24
	s_waitcnt lgkmcnt(1)
	v_lshlrev_b32_e32 v32, 7, v39
	v_lshlrev_b32_e32 v33, 7, v38
	v_lshlrev_b32_e32 v41, 7, v41
	v_lshlrev_b32_e32 v40, 7, v40
	s_waitcnt lgkmcnt(0)
	v_lshlrev_b32_e32 v48, 7, v55
	v_lshlrev_b32_e32 v49, 7, v54
	v_lshlrev_b32_e32 v57, 7, v57
	v_lshlrev_b32_e32 v56, 7, v56
	s_addc_u32 s15, s39, 0
	v_or_b32_e32 v4, v0, v137
	v_or_b32_e32 v0, v1, v174
	v_or_b32_e32 v12, v9, v137
	v_or_b32_e32 v8, v8, v174
	v_or_b32_e32 v20, v16, v137
	v_or_b32_e32 v16, v17, v174
	v_or_b32_e32 v28, v25, v137
	v_or_b32_e32 v24, v24, v174
	v_or_b32_e32 v36, v32, v137
	v_or_b32_e32 v32, v33, v174
	v_or_b32_e32 v44, v41, v137
	v_or_b32_e32 v40, v40, v174
	v_or_b32_e32 v52, v48, v137
	v_or_b32_e32 v48, v49, v174
	v_or_b32_e32 v60, v57, v137
	v_or_b32_e32 v56, v56, v174
	v_and_or_b32 v128, s61, 14, v176
	global_load_dwordx4 v[0:3], v0, s[14:15]
	s_nop 0
	global_load_dwordx4 v[4:7], v4, s[14:15]
	s_nop 0
	global_load_dwordx4 v[8:11], v8, s[14:15]
	s_nop 0
	global_load_dwordx4 v[12:15], v12, s[14:15]
	s_nop 0
	global_load_dwordx4 v[16:19], v16, s[14:15]
	s_nop 0
	global_load_dwordx4 v[20:23], v20, s[14:15]
	s_nop 0
	global_load_dwordx4 v[24:27], v24, s[14:15]
	s_nop 0
	global_load_dwordx4 v[28:31], v28, s[14:15]
	s_nop 0
	global_load_dwordx4 v[32:35], v32, s[14:15]
	s_nop 0
	global_load_dwordx4 v[36:39], v36, s[14:15]
	s_nop 0
	global_load_dwordx4 v[40:43], v40, s[14:15]
	s_nop 0
	global_load_dwordx4 v[44:47], v44, s[14:15]
	s_nop 0
	global_load_dwordx4 v[48:51], v48, s[14:15]
	s_nop 0
	global_load_dwordx4 v[52:55], v52, s[14:15]
	s_nop 0
	global_load_dwordx4 v[56:59], v56, s[14:15]
	s_nop 0
	global_load_dwordx4 v[60:63], v60, s[14:15]
	s_and_b32 s14, s16, 0xf80
	v_ashrrev_i32_e32 v129, 31, v128
	v_or_b32_e32 v134, s14, v192
	v_lshlrev_b64 v[130:131], 12, v[128:129]
	v_lshl_add_u64 v[132:133], s[80:81], 0, v[130:131]
	v_lshlrev_b32_e32 v134, 1, v134
	v_mov_b32_e32 v135, v139
	v_lshl_add_u64 v[132:133], v[132:133], 0, v[134:135]
	v_lshl_add_u64 v[130:131], s[28:29], 0, v[130:131]
	v_lshl_add_u64 v[130:131], v[130:131], 0, v[134:135]
	global_load_dword v210, v[132:133], off nt
	global_load_dword v211, v[130:131], off nt
	s_branch .LBB0_933

	.amdhsa_kernel _Z4mega6Paramsii
		.amdhsa_group_segment_fixed_size 16
		.amdhsa_private_segment_fixed_size 0
		.amdhsa_kernarg_size 416
		.amdhsa_user_sgpr_count 2
		.amdhsa_user_sgpr_dispatch_ptr 0
		.amdhsa_user_sgpr_queue_ptr 0
		.amdhsa_user_sgpr_kernarg_segment_ptr 1
		.amdhsa_user_sgpr_dispatch_id 0
		.amdhsa_user_sgpr_kernarg_preload_length 0
		.amdhsa_user_sgpr_kernarg_preload_offset 0
		.amdhsa_user_sgpr_private_segment_size 0
		.amdhsa_uses_dynamic_stack 0
		.amdhsa_enable_private_segment 0
		.amdhsa_system_sgpr_workgroup_id_x 1
		.amdhsa_system_sgpr_workgroup_id_y 0
		.amdhsa_system_sgpr_workgroup_id_z 0
		.amdhsa_system_sgpr_workgroup_info 0
		.amdhsa_system_vgpr_workitem_id 2
		.amdhsa_next_free_vgpr 256
		.amdhsa_next_free_sgpr 100
		.amdhsa_accum_offset 256
		.amdhsa_reserve_vcc 1
		.amdhsa_float_round_mode_32 0
		.amdhsa_float_round_mode_16_64 0
		.amdhsa_float_denorm_mode_32 3
		.amdhsa_float_denorm_mode_16_64 3
		.amdhsa_dx10_clamp 1
		.amdhsa_ieee_mode 1
		.amdhsa_fp16_overflow 0
		.amdhsa_tg_split 0
		.amdhsa_exception_fp_ieee_invalid_op 0
		.amdhsa_exception_fp_denorm_src 0
		.amdhsa_exception_fp_ieee_div_zero 0
		.amdhsa_exception_fp_ieee_overflow 0
		.amdhsa_exception_fp_ieee_underflow 0
		.amdhsa_exception_fp_ieee_inexact 0
		.amdhsa_exception_int_div_zero 0
	.end_amdhsa_kernel

amdhsa.kernels:
  - .agpr_count:     0
    .args:
      - .offset:         0
        .size:           152
        .value_kind:     by_value
      - .offset:         152
        .size:           4
        .value_kind:     by_value
      - .offset:         156
        .size:           4
        .value_kind:     by_value
      - .offset:         160
        .size:           4
        .value_kind:     hidden_block_count_x
      - .offset:         164
        .size:           4
        .value_kind:     hidden_block_count_y
      - .offset:         168
        .size:           4
        .value_kind:     hidden_block_count_z
      - .offset:         172
        .size:           2
        .value_kind:     hidden_group_size_x
      - .offset:         174
        .size:           2
        .value_kind:     hidden_group_size_y
      - .offset:         176
        .size:           2
        .value_kind:     hidden_group_size_z
      - .offset:         178
        .size:           2
        .value_kind:     hidden_remainder_x
      - .offset:         180
        .size:           2
        .value_kind:     hidden_remainder_y
      - .offset:         182
        .size:           2
        .value_kind:     hidden_remainder_z
      - .offset:         200
        .size:           8
        .value_kind:     hidden_global_offset_x
      - .offset:         208
        .size:           8
        .value_kind:     hidden_global_offset_y
      - .offset:         216
        .size:           8
        .value_kind:     hidden_global_offset_z
      - .offset:         224
        .size:           2
        .value_kind:     hidden_grid_dims
      - .offset:         248
        .size:           8
        .value_kind:     hidden_multigrid_sync_arg
      - .offset:         280
        .size:           4
        .value_kind:     hidden_dynamic_lds_size
    .group_segment_fixed_size: 16
    .kernarg_segment_align: 8
    .kernarg_segment_size: 416
    .language:       OpenCL C
    .language_version:
      - 2
      - 0
    .max_flat_workgroup_size: 512
    .name:           _Z4mega6Paramsii
    .private_segment_fixed_size: 0
    .sgpr_count:     106
    .sgpr_spill_count: 13
    .symbol:         _Z4mega6Paramsii.kd
    .uniform_work_group_size: 1
    .uses_dynamic_stack: false
    .vgpr_count:     256
    .vgpr_spill_count: 0
    .wavefront_size: 64
